# k6_pv3
# speedup vs baseline: 1.0593x; 1.0054x over previous
; DI void phase_peer_b(const Params& p, int layer, const float* gnext, bool last) {
;     ...
; #pragma unroll 1
;   for (size_t row = (size_t)blockIdx.x * 4 + wave; row < (size_t)T; row += (size_t)gridDim.x * 4) {
;     const int i0 = ibuf[row * 128 + lane], i1 = ibuf[row * 128 + 64 + lane];
;     const float w0 = wbuf[row * 128 + lane], w1 = wbuf[row * 128 + 64 + lane];
;     float acc[16];
; #pragma unroll
;     for (int i = 0; i < 16; ++i) acc[i] = 0.f;
; #pragma unroll 1
;     for (int bt = 0; bt < 8; ++bt) {
;       u32x4 vr[16];
; #pragma unroll
;       for (int j = 0; j < 16; ++j) {
;         const int e = bt * 16 + j;
;         const int eidx = __builtin_amdgcn_readlane(e < 64 ? i0 : i1, e & 63);
;         vr[j] = *(const u32x4*)(EV + (size_t)eidx * DM + lane * 16);
.LBB0_501:
	s_or_b64 exec, exec, s[10:11]
	s_add_u32 s58, s68, 0x294a0800
	s_addc_u32 s59, s69, 0
	s_mov_b32 s3, 0
	v_mov_b32_e32 v181, 0
	s_add_u32 s60, s68, 0x2b4b0800
	v_lshl_add_u64 v[192:193], s[2:3], 2, v[180:181]
	s_mov_b64 s[10:11], 0x10080
	s_addc_u32 s61, s69, 0
	v_cmp_gt_u64_e64 s[10:11], s[10:11], v[192:193]
	v_lshlrev_b32_e32 v196, 6, v176
	s_barrier
	s_mov_b64 exec, -1
	v_mbcnt_lo_u32_b32 v165, -1, 0
	v_mbcnt_hi_u32_b32 v165, -1, v165
	v_and_b32_e32 v160, 7, v165
	v_lshlrev_b32_e32 v167, 6, v160
	v_lshlrev_b32_e32 v160, 4, v160
	v_lshrrev_b32_e32 v166, 3, v165
	s_and_b32 s24, s95, 7
	s_lshr_b32 s22, s95, 3
	s_lshr_b32 s23, s70, 3
	s_cmp_ge_u32 s22, s23
	s_cbranch_scc1 .Lpv0_end
	s_lshl_b32 s22, s22, 2
	s_add_u32 s22, s22, s94
	s_lshl_b32 s23, s23, 2
	s_lshl_b32 s25, s24, 21
	s_add_u32 s25, s25, 0x190c0000
	s_add_u32 s14, s68, s25
	s_addc_u32 s15, s69, 0
	s_add_u32 s16, s68, 0x2b4b0800
	s_addc_u32 s17, s69, 0
	s_add_u32 s18, s68, 0x294a0800
	s_addc_u32 s19, s69, 0
	s_lshl_b32 s25, s24, 9
	s_add_u32 s20, s68, s25
	s_addc_u32 s21, s69, 0
	s_mul_i32 s25, s94, 8320
	v_lshlrev_b32_e32 v162, 4, v165
	v_add_u32_e32 v162, s25, v162
	v_mul_u32_u24_e32 v163, 1040, v166
	v_add_u32_e32 v163, s25, v163
	v_and_b32_e32 v161, 31, v165
	v_lshlrev_b32_e32 v161, 4, v161
	v_mov_b32_e32 v168, s16
	v_mov_b32_e32 v169, s17
	v_mov_b32_e32 v170, s18
	v_mov_b32_e32 v171, s19
	v_cmp_gt_u32_e32 vcc, 32, v165
	s_nop 1
	v_cndmask_b32_e32 v168, v170, v168, vcc
	v_cndmask_b32_e32 v169, v171, v169, vcc
	v_add_co_u32_e32 v168, vcc, v168, v161
	s_nop 1
	v_addc_co_u32_e32 v169, vcc, 0, v169, vcc
	s_cmpk_ge_u32 s22, 0x2010
	s_cbranch_scc1 .Lpv0_end
	s_lshl_b32 s24, s22, 12
	s_mov_b32 s25, 0
	v_lshl_add_u64 v[170:171], v[168:169], 0, s[24:25]
	global_load_dwordx4 v[16:19], v[170:171], off offset:0
	global_load_dwordx4 v[20:23], v[170:171], off offset:512
	global_load_dwordx4 v[24:27], v[170:171], off offset:1024
	global_load_dwordx4 v[28:31], v[170:171], off offset:1536
	global_load_dwordx4 v[32:35], v[170:171], off offset:2048
	global_load_dwordx4 v[36:39], v[170:171], off offset:2560
	global_load_dwordx4 v[40:43], v[170:171], off offset:3072
	global_load_dwordx4 v[44:47], v[170:171], off offset:3584
	s_waitcnt vmcnt(0)
.Lpv0_item:
	v_mov_b32_e32 v164, s22
	v_lshl_add_u32 v164, v164, 3, v166
	v_lshl_add_u32 v164, v164, 12, v167
	v_mov_b32_e32 v0, 0
	v_mov_b32_e32 v1, 0
	v_mov_b32_e32 v2, 0
	v_mov_b32_e32 v3, 0
	v_mov_b32_e32 v4, 0
	v_mov_b32_e32 v5, 0
	v_mov_b32_e32 v6, 0
	v_mov_b32_e32 v7, 0
	v_mov_b32_e32 v8, 0
	v_mov_b32_e32 v9, 0
	v_mov_b32_e32 v10, 0
	v_mov_b32_e32 v11, 0
	v_mov_b32_e32 v12, 0
	v_mov_b32_e32 v13, 0
	v_mov_b32_e32 v14, 0
	v_mov_b32_e32 v15, 0
	s_waitcnt vmcnt(4)
	ds_write_b128 v162, v[16:19]
	ds_write_b128 v162, v[20:23] offset:1040
	ds_write_b128 v162, v[24:27] offset:2080
	ds_write_b128 v162, v[28:31] offset:3120
	ds_write_b128 v162, v[32:35] offset:4160
	ds_write_b128 v162, v[36:39] offset:5200
	ds_write_b128 v162, v[40:43] offset:6240
	ds_write_b128 v162, v[44:47] offset:7280
	s_waitcnt lgkmcnt(0)
	ds_read_b128 v[16:19], v163 offset:0
	ds_read_b128 v[20:23], v163 offset:16
	ds_read_b128 v[24:27], v163 offset:32
	ds_read_b128 v[28:31], v163 offset:48
	ds_read_b128 v[48:51], v163 offset:512
	ds_read_b128 v[52:55], v163 offset:528
	ds_read_b128 v[56:59], v163 offset:544
	ds_read_b128 v[60:63], v163 offset:560
	ds_read_b128 v[32:35], v163 offset:64
	ds_read_b128 v[36:39], v163 offset:80
	ds_read_b128 v[40:43], v163 offset:96
	ds_read_b128 v[44:47], v163 offset:112
	s_waitcnt lgkmcnt(0)
	v_lshl_add_u32 v161, v16, 7, v160
	global_load_dwordx4 v[80:83], v161, s[14:15]
	v_lshl_add_u32 v161, v17, 7, v160
	global_load_dwordx4 v[84:87], v161, s[14:15]
	v_lshl_add_u32 v161, v18, 7, v160
	global_load_dwordx4 v[88:91], v161, s[14:15]
	v_lshl_add_u32 v161, v19, 7, v160
	global_load_dwordx4 v[92:95], v161, s[14:15]
	v_lshl_add_u32 v161, v20, 7, v160
	global_load_dwordx4 v[96:99], v161, s[14:15]
	v_lshl_add_u32 v161, v21, 7, v160
	global_load_dwordx4 v[100:103], v161, s[14:15]
	v_lshl_add_u32 v161, v22, 7, v160
	global_load_dwordx4 v[104:107], v161, s[14:15]
	v_lshl_add_u32 v161, v23, 7, v160
	global_load_dwordx4 v[108:111], v161, s[14:15]
	v_lshl_add_u32 v161, v24, 7, v160
	global_load_dwordx4 v[112:115], v161, s[14:15]
	v_lshl_add_u32 v161, v25, 7, v160
	global_load_dwordx4 v[116:119], v161, s[14:15]
	v_lshl_add_u32 v161, v26, 7, v160
	global_load_dwordx4 v[120:123], v161, s[14:15]
	v_lshl_add_u32 v161, v27, 7, v160
	global_load_dwordx4 v[124:127], v161, s[14:15]
	v_lshl_add_u32 v161, v28, 7, v160
	global_load_dwordx4 v[128:131], v161, s[14:15]
	v_lshl_add_u32 v161, v29, 7, v160
	global_load_dwordx4 v[132:135], v161, s[14:15]
	v_lshl_add_u32 v161, v30, 7, v160
	global_load_dwordx4 v[136:139], v161, s[14:15]
	v_lshl_add_u32 v161, v31, 7, v160
	global_load_dwordx4 v[140:143], v161, s[14:15]
	ds_read_b128 v[16:19], v163 offset:128
	ds_read_b128 v[20:23], v163 offset:144
	ds_read_b128 v[24:27], v163 offset:160
	ds_read_b128 v[28:31], v163 offset:176
	ds_read_b128 v[64:67], v163 offset:576
	ds_read_b128 v[68:71], v163 offset:592
	ds_read_b128 v[72:75], v163 offset:608
	ds_read_b128 v[76:79], v163 offset:624
	s_waitcnt vmcnt(15)
; DI void phase_peer_b(const Params& p, int layer, const float* gnext, bool last) {
;     ...
; #pragma unroll
;       for (int j = 0; j < 16; ++j) {
;         const int e = bt * 16 + j;
;         const int eidx = __builtin_amdgcn_readlane(e < 64 ? i0 : i1, e & 63);
;         vr[j] = *(const u32x4*)(EV + (size_t)eidx * DM + lane * 16);
;       }
; #pragma unroll
;       for (int j = 0; j < 16; ++j) {
;         const int e = bt * 16 + j;
;         const float wj = __int_as_float(__builtin_amdgcn_readlane(__float_as_int(e < 64 ? w0 : w1), e & 63));
; #pragma unroll
;         for (int w = 0; w < 4; ++w) {
;           const f32x2 lo = __builtin_amdgcn_cvt_pk_f32_fp8((int)vr[j][w], false);
;           const f32x2 hi = __builtin_amdgcn_cvt_pk_f32_fp8((int)vr[j][w], true);
;           acc[4 * w] += wj * lo[0]; acc[4 * w + 1] += wj * lo[1]; acc[4 * w + 2] += wj * hi[0]; acc[4 * w + 3] += wj * hi[1];
;         }
	v_cvt_pk_f32_fp8_e32 v[144:145], v80
	v_cvt_pk_f32_fp8_sdwa v[146:147], v80 src0_sel:WORD_1
	v_cvt_pk_f32_fp8_e32 v[148:149], v81
	v_cvt_pk_f32_fp8_sdwa v[150:151], v81 src0_sel:WORD_1
	v_cvt_pk_f32_fp8_e32 v[152:153], v82
	v_cvt_pk_f32_fp8_sdwa v[154:155], v82 src0_sel:WORD_1
	v_cvt_pk_f32_fp8_e32 v[156:157], v83
	v_cvt_pk_f32_fp8_sdwa v[158:159], v83 src0_sel:WORD_1
	v_fmac_f32_e32 v0, v48, v144
	v_fmac_f32_e32 v1, v48, v145
	v_fmac_f32_e32 v2, v48, v146
	v_fmac_f32_e32 v3, v48, v147
	v_fmac_f32_e32 v4, v48, v148
	v_fmac_f32_e32 v5, v48, v149
	v_fmac_f32_e32 v6, v48, v150
	v_fmac_f32_e32 v7, v48, v151
	v_fmac_f32_e32 v8, v48, v152
	v_fmac_f32_e32 v9, v48, v153
	v_fmac_f32_e32 v10, v48, v154
	v_fmac_f32_e32 v11, v48, v155
	v_fmac_f32_e32 v12, v48, v156
	v_fmac_f32_e32 v13, v48, v157
	v_fmac_f32_e32 v14, v48, v158
	v_fmac_f32_e32 v15, v48, v159
	v_lshl_add_u32 v161, v32, 7, v160
	global_load_dwordx4 v[80:83], v161, s[14:15]
	s_waitcnt vmcnt(15)
	v_cvt_pk_f32_fp8_e32 v[144:145], v84
	v_cvt_pk_f32_fp8_sdwa v[146:147], v84 src0_sel:WORD_1
	v_cvt_pk_f32_fp8_e32 v[148:149], v85
	v_cvt_pk_f32_fp8_sdwa v[150:151], v85 src0_sel:WORD_1
	v_cvt_pk_f32_fp8_e32 v[152:153], v86
	v_cvt_pk_f32_fp8_sdwa v[154:155], v86 src0_sel:WORD_1
	v_cvt_pk_f32_fp8_e32 v[156:157], v87
	v_cvt_pk_f32_fp8_sdwa v[158:159], v87 src0_sel:WORD_1
	v_fmac_f32_e32 v0, v49, v144
	v_fmac_f32_e32 v1, v49, v145
	v_fmac_f32_e32 v2, v49, v146
	v_fmac_f32_e32 v3, v49, v147
	v_fmac_f32_e32 v4, v49, v148
	v_fmac_f32_e32 v5, v49, v149
	v_fmac_f32_e32 v6, v49, v150
	v_fmac_f32_e32 v7, v49, v151
	v_fmac_f32_e32 v8, v49, v152
	v_fmac_f32_e32 v9, v49, v153
	v_fmac_f32_e32 v10, v49, v154
	v_fmac_f32_e32 v11, v49, v155
	v_fmac_f32_e32 v12, v49, v156
	v_fmac_f32_e32 v13, v49, v157
	v_fmac_f32_e32 v14, v49, v158
	v_fmac_f32_e32 v15, v49, v159
	v_lshl_add_u32 v161, v33, 7, v160
	global_load_dwordx4 v[84:87], v161, s[14:15]
	s_waitcnt vmcnt(15)
	v_cvt_pk_f32_fp8_e32 v[144:145], v88
	v_cvt_pk_f32_fp8_sdwa v[146:147], v88 src0_sel:WORD_1
	v_cvt_pk_f32_fp8_e32 v[148:149], v89
	v_cvt_pk_f32_fp8_sdwa v[150:151], v89 src0_sel:WORD_1
	v_cvt_pk_f32_fp8_e32 v[152:153], v90
	v_cvt_pk_f32_fp8_sdwa v[154:155], v90 src0_sel:WORD_1
	v_cvt_pk_f32_fp8_e32 v[156:157], v91
	v_cvt_pk_f32_fp8_sdwa v[158:159], v91 src0_sel:WORD_1
	v_fmac_f32_e32 v0, v50, v144
	v_fmac_f32_e32 v1, v50, v145
	v_fmac_f32_e32 v2, v50, v146
	v_fmac_f32_e32 v3, v50, v147
	v_fmac_f32_e32 v4, v50, v148
	v_fmac_f32_e32 v5, v50, v149
	v_fmac_f32_e32 v6, v50, v150
	v_fmac_f32_e32 v7, v50, v151
	v_fmac_f32_e32 v8, v50, v152
	v_fmac_f32_e32 v9, v50, v153
	v_fmac_f32_e32 v10, v50, v154
	v_fmac_f32_e32 v11, v50, v155
	v_fmac_f32_e32 v12, v50, v156
	v_fmac_f32_e32 v13, v50, v157
	v_fmac_f32_e32 v14, v50, v158
	v_fmac_f32_e32 v15, v50, v159
	v_lshl_add_u32 v161, v34, 7, v160
	global_load_dwordx4 v[88:91], v161, s[14:15]
	s_waitcnt vmcnt(15)
	v_cvt_pk_f32_fp8_e32 v[144:145], v92
	v_cvt_pk_f32_fp8_sdwa v[146:147], v92 src0_sel:WORD_1
	v_cvt_pk_f32_fp8_e32 v[148:149], v93
	v_cvt_pk_f32_fp8_sdwa v[150:151], v93 src0_sel:WORD_1
	v_cvt_pk_f32_fp8_e32 v[152:153], v94
	v_cvt_pk_f32_fp8_sdwa v[154:155], v94 src0_sel:WORD_1
	v_cvt_pk_f32_fp8_e32 v[156:157], v95
	v_cvt_pk_f32_fp8_sdwa v[158:159], v95 src0_sel:WORD_1
	v_fmac_f32_e32 v0, v51, v144
	v_fmac_f32_e32 v1, v51, v145
	v_fmac_f32_e32 v2, v51, v146
	v_fmac_f32_e32 v3, v51, v147
	v_fmac_f32_e32 v4, v51, v148
	v_fmac_f32_e32 v5, v51, v149
	v_fmac_f32_e32 v6, v51, v150
	v_fmac_f32_e32 v7, v51, v151
	v_fmac_f32_e32 v8, v51, v152
	v_fmac_f32_e32 v9, v51, v153
	v_fmac_f32_e32 v10, v51, v154
	v_fmac_f32_e32 v11, v51, v155
	v_fmac_f32_e32 v12, v51, v156
	v_fmac_f32_e32 v13, v51, v157
	v_fmac_f32_e32 v14, v51, v158
	v_fmac_f32_e32 v15, v51, v159
	v_lshl_add_u32 v161, v35, 7, v160
	global_load_dwordx4 v[92:95], v161, s[14:15]
	s_waitcnt vmcnt(15)
	v_cvt_pk_f32_fp8_e32 v[144:145], v96
	v_cvt_pk_f32_fp8_sdwa v[146:147], v96 src0_sel:WORD_1
	v_cvt_pk_f32_fp8_e32 v[148:149], v97
	v_cvt_pk_f32_fp8_sdwa v[150:151], v97 src0_sel:WORD_1
	v_cvt_pk_f32_fp8_e32 v[152:153], v98
	v_cvt_pk_f32_fp8_sdwa v[154:155], v98 src0_sel:WORD_1
	v_cvt_pk_f32_fp8_e32 v[156:157], v99
	v_cvt_pk_f32_fp8_sdwa v[158:159], v99 src0_sel:WORD_1
	v_fmac_f32_e32 v0, v52, v144
	v_fmac_f32_e32 v1, v52, v145
	v_fmac_f32_e32 v2, v52, v146
	v_fmac_f32_e32 v3, v52, v147
	v_fmac_f32_e32 v4, v52, v148
	v_fmac_f32_e32 v5, v52, v149
	v_fmac_f32_e32 v6, v52, v150
	v_fmac_f32_e32 v7, v52, v151
	v_fmac_f32_e32 v8, v52, v152
	v_fmac_f32_e32 v9, v52, v153
	v_fmac_f32_e32 v10, v52, v154
	v_fmac_f32_e32 v11, v52, v155
	v_fmac_f32_e32 v12, v52, v156
	v_fmac_f32_e32 v13, v52, v157
	v_fmac_f32_e32 v14, v52, v158
	v_fmac_f32_e32 v15, v52, v159
	v_lshl_add_u32 v161, v36, 7, v160
	global_load_dwordx4 v[96:99], v161, s[14:15]
	s_waitcnt vmcnt(15)
	v_cvt_pk_f32_fp8_e32 v[144:145], v100
	v_cvt_pk_f32_fp8_sdwa v[146:147], v100 src0_sel:WORD_1
	v_cvt_pk_f32_fp8_e32 v[148:149], v101
	v_cvt_pk_f32_fp8_sdwa v[150:151], v101 src0_sel:WORD_1
	v_cvt_pk_f32_fp8_e32 v[152:153], v102
	v_cvt_pk_f32_fp8_sdwa v[154:155], v102 src0_sel:WORD_1
	v_cvt_pk_f32_fp8_e32 v[156:157], v103
	v_cvt_pk_f32_fp8_sdwa v[158:159], v103 src0_sel:WORD_1
	v_fmac_f32_e32 v0, v53, v144
	v_fmac_f32_e32 v1, v53, v145
	v_fmac_f32_e32 v2, v53, v146
	v_fmac_f32_e32 v3, v53, v147
	v_fmac_f32_e32 v4, v53, v148
	v_fmac_f32_e32 v5, v53, v149
	v_fmac_f32_e32 v6, v53, v150
	v_fmac_f32_e32 v7, v53, v151
	v_fmac_f32_e32 v8, v53, v152
	v_fmac_f32_e32 v9, v53, v153
	v_fmac_f32_e32 v10, v53, v154
	v_fmac_f32_e32 v11, v53, v155
	v_fmac_f32_e32 v12, v53, v156
	v_fmac_f32_e32 v13, v53, v157
	v_fmac_f32_e32 v14, v53, v158
	v_fmac_f32_e32 v15, v53, v159
	v_lshl_add_u32 v161, v37, 7, v160
	global_load_dwordx4 v[100:103], v161, s[14:15]
	s_waitcnt vmcnt(15)
; DI void phase_peer_b(const Params& p, int layer, const float* gnext, bool last) {
;     ...
; #pragma unroll
;       for (int j = 0; j < 16; ++j) {
;         const int e = bt * 16 + j;
;         const int eidx = __builtin_amdgcn_readlane(e < 64 ? i0 : i1, e & 63);
;         vr[j] = *(const u32x4*)(EV + (size_t)eidx * DM + lane * 16);
;       }
; #pragma unroll
;       for (int j = 0; j < 16; ++j) {
;         const int e = bt * 16 + j;
;         const float wj = __int_as_float(__builtin_amdgcn_readlane(__float_as_int(e < 64 ? w0 : w1), e & 63));
; #pragma unroll
;         for (int w = 0; w < 4; ++w) {
;           const f32x2 lo = __builtin_amdgcn_cvt_pk_f32_fp8((int)vr[j][w], false);
;           const f32x2 hi = __builtin_amdgcn_cvt_pk_f32_fp8((int)vr[j][w], true);
;           acc[4 * w] += wj * lo[0]; acc[4 * w + 1] += wj * lo[1]; acc[4 * w + 2] += wj * hi[0]; acc[4 * w + 3] += wj * hi[1];
;         }
	v_cvt_pk_f32_fp8_e32 v[144:145], v104
	v_cvt_pk_f32_fp8_sdwa v[146:147], v104 src0_sel:WORD_1
	v_cvt_pk_f32_fp8_e32 v[148:149], v105
	v_cvt_pk_f32_fp8_sdwa v[150:151], v105 src0_sel:WORD_1
	v_cvt_pk_f32_fp8_e32 v[152:153], v106
	v_cvt_pk_f32_fp8_sdwa v[154:155], v106 src0_sel:WORD_1
	v_cvt_pk_f32_fp8_e32 v[156:157], v107
	v_cvt_pk_f32_fp8_sdwa v[158:159], v107 src0_sel:WORD_1
	v_fmac_f32_e32 v0, v54, v144
	v_fmac_f32_e32 v1, v54, v145
	v_fmac_f32_e32 v2, v54, v146
	v_fmac_f32_e32 v3, v54, v147
	v_fmac_f32_e32 v4, v54, v148
	v_fmac_f32_e32 v5, v54, v149
	v_fmac_f32_e32 v6, v54, v150
	v_fmac_f32_e32 v7, v54, v151
	v_fmac_f32_e32 v8, v54, v152
	v_fmac_f32_e32 v9, v54, v153
	v_fmac_f32_e32 v10, v54, v154
	v_fmac_f32_e32 v11, v54, v155
	v_fmac_f32_e32 v12, v54, v156
	v_fmac_f32_e32 v13, v54, v157
	v_fmac_f32_e32 v14, v54, v158
	v_fmac_f32_e32 v15, v54, v159
	v_lshl_add_u32 v161, v38, 7, v160
	global_load_dwordx4 v[104:107], v161, s[14:15]
	s_waitcnt vmcnt(15)
	v_cvt_pk_f32_fp8_e32 v[144:145], v108
	v_cvt_pk_f32_fp8_sdwa v[146:147], v108 src0_sel:WORD_1
	v_cvt_pk_f32_fp8_e32 v[148:149], v109
	v_cvt_pk_f32_fp8_sdwa v[150:151], v109 src0_sel:WORD_1
	v_cvt_pk_f32_fp8_e32 v[152:153], v110
	v_cvt_pk_f32_fp8_sdwa v[154:155], v110 src0_sel:WORD_1
	v_cvt_pk_f32_fp8_e32 v[156:157], v111
	v_cvt_pk_f32_fp8_sdwa v[158:159], v111 src0_sel:WORD_1
	v_fmac_f32_e32 v0, v55, v144
	v_fmac_f32_e32 v1, v55, v145
	v_fmac_f32_e32 v2, v55, v146
	v_fmac_f32_e32 v3, v55, v147
	v_fmac_f32_e32 v4, v55, v148
	v_fmac_f32_e32 v5, v55, v149
	v_fmac_f32_e32 v6, v55, v150
	v_fmac_f32_e32 v7, v55, v151
	v_fmac_f32_e32 v8, v55, v152
	v_fmac_f32_e32 v9, v55, v153
	v_fmac_f32_e32 v10, v55, v154
	v_fmac_f32_e32 v11, v55, v155
	v_fmac_f32_e32 v12, v55, v156
	v_fmac_f32_e32 v13, v55, v157
	v_fmac_f32_e32 v14, v55, v158
	v_fmac_f32_e32 v15, v55, v159
	v_lshl_add_u32 v161, v39, 7, v160
	global_load_dwordx4 v[108:111], v161, s[14:15]
	s_waitcnt vmcnt(15)
	v_cvt_pk_f32_fp8_e32 v[144:145], v112
	v_cvt_pk_f32_fp8_sdwa v[146:147], v112 src0_sel:WORD_1
	v_cvt_pk_f32_fp8_e32 v[148:149], v113
	v_cvt_pk_f32_fp8_sdwa v[150:151], v113 src0_sel:WORD_1
	v_cvt_pk_f32_fp8_e32 v[152:153], v114
	v_cvt_pk_f32_fp8_sdwa v[154:155], v114 src0_sel:WORD_1
	v_cvt_pk_f32_fp8_e32 v[156:157], v115
	v_cvt_pk_f32_fp8_sdwa v[158:159], v115 src0_sel:WORD_1
	v_fmac_f32_e32 v0, v56, v144
	v_fmac_f32_e32 v1, v56, v145
	v_fmac_f32_e32 v2, v56, v146
	v_fmac_f32_e32 v3, v56, v147
	v_fmac_f32_e32 v4, v56, v148
	v_fmac_f32_e32 v5, v56, v149
	v_fmac_f32_e32 v6, v56, v150
	v_fmac_f32_e32 v7, v56, v151
	v_fmac_f32_e32 v8, v56, v152
	v_fmac_f32_e32 v9, v56, v153
	v_fmac_f32_e32 v10, v56, v154
	v_fmac_f32_e32 v11, v56, v155
	v_fmac_f32_e32 v12, v56, v156
	v_fmac_f32_e32 v13, v56, v157
	v_fmac_f32_e32 v14, v56, v158
	v_fmac_f32_e32 v15, v56, v159
	v_lshl_add_u32 v161, v40, 7, v160
	global_load_dwordx4 v[112:115], v161, s[14:15]
	s_waitcnt vmcnt(15)
	v_cvt_pk_f32_fp8_e32 v[144:145], v116
	v_cvt_pk_f32_fp8_sdwa v[146:147], v116 src0_sel:WORD_1
	v_cvt_pk_f32_fp8_e32 v[148:149], v117
	v_cvt_pk_f32_fp8_sdwa v[150:151], v117 src0_sel:WORD_1
	v_cvt_pk_f32_fp8_e32 v[152:153], v118
	v_cvt_pk_f32_fp8_sdwa v[154:155], v118 src0_sel:WORD_1
	v_cvt_pk_f32_fp8_e32 v[156:157], v119
	v_cvt_pk_f32_fp8_sdwa v[158:159], v119 src0_sel:WORD_1
	v_fmac_f32_e32 v0, v57, v144
	v_fmac_f32_e32 v1, v57, v145
	v_fmac_f32_e32 v2, v57, v146
	v_fmac_f32_e32 v3, v57, v147
	v_fmac_f32_e32 v4, v57, v148
	v_fmac_f32_e32 v5, v57, v149
	v_fmac_f32_e32 v6, v57, v150
	v_fmac_f32_e32 v7, v57, v151
	v_fmac_f32_e32 v8, v57, v152
	v_fmac_f32_e32 v9, v57, v153
	v_fmac_f32_e32 v10, v57, v154
	v_fmac_f32_e32 v11, v57, v155
	v_fmac_f32_e32 v12, v57, v156
	v_fmac_f32_e32 v13, v57, v157
	v_fmac_f32_e32 v14, v57, v158
	v_fmac_f32_e32 v15, v57, v159
	v_lshl_add_u32 v161, v41, 7, v160
	global_load_dwordx4 v[116:119], v161, s[14:15]
	s_waitcnt vmcnt(15)
	v_cvt_pk_f32_fp8_e32 v[144:145], v120
	v_cvt_pk_f32_fp8_sdwa v[146:147], v120 src0_sel:WORD_1
	v_cvt_pk_f32_fp8_e32 v[148:149], v121
	v_cvt_pk_f32_fp8_sdwa v[150:151], v121 src0_sel:WORD_1
	v_cvt_pk_f32_fp8_e32 v[152:153], v122
	v_cvt_pk_f32_fp8_sdwa v[154:155], v122 src0_sel:WORD_1
	v_cvt_pk_f32_fp8_e32 v[156:157], v123
	v_cvt_pk_f32_fp8_sdwa v[158:159], v123 src0_sel:WORD_1
	v_fmac_f32_e32 v0, v58, v144
	v_fmac_f32_e32 v1, v58, v145
	v_fmac_f32_e32 v2, v58, v146
	v_fmac_f32_e32 v3, v58, v147
	v_fmac_f32_e32 v4, v58, v148
	v_fmac_f32_e32 v5, v58, v149
	v_fmac_f32_e32 v6, v58, v150
	v_fmac_f32_e32 v7, v58, v151
	v_fmac_f32_e32 v8, v58, v152
	v_fmac_f32_e32 v9, v58, v153
	v_fmac_f32_e32 v10, v58, v154
	v_fmac_f32_e32 v11, v58, v155
	v_fmac_f32_e32 v12, v58, v156
	v_fmac_f32_e32 v13, v58, v157
	v_fmac_f32_e32 v14, v58, v158
	v_fmac_f32_e32 v15, v58, v159
	v_lshl_add_u32 v161, v42, 7, v160
	global_load_dwordx4 v[120:123], v161, s[14:15]
	s_waitcnt vmcnt(15)
	v_cvt_pk_f32_fp8_e32 v[144:145], v124
	v_cvt_pk_f32_fp8_sdwa v[146:147], v124 src0_sel:WORD_1
	v_cvt_pk_f32_fp8_e32 v[148:149], v125
	v_cvt_pk_f32_fp8_sdwa v[150:151], v125 src0_sel:WORD_1
	v_cvt_pk_f32_fp8_e32 v[152:153], v126
	v_cvt_pk_f32_fp8_sdwa v[154:155], v126 src0_sel:WORD_1
	v_cvt_pk_f32_fp8_e32 v[156:157], v127
	v_cvt_pk_f32_fp8_sdwa v[158:159], v127 src0_sel:WORD_1
	v_fmac_f32_e32 v0, v59, v144
	v_fmac_f32_e32 v1, v59, v145
	v_fmac_f32_e32 v2, v59, v146
	v_fmac_f32_e32 v3, v59, v147
	v_fmac_f32_e32 v4, v59, v148
	v_fmac_f32_e32 v5, v59, v149
	v_fmac_f32_e32 v6, v59, v150
	v_fmac_f32_e32 v7, v59, v151
	v_fmac_f32_e32 v8, v59, v152
	v_fmac_f32_e32 v9, v59, v153
	v_fmac_f32_e32 v10, v59, v154
	v_fmac_f32_e32 v11, v59, v155
	v_fmac_f32_e32 v12, v59, v156
	v_fmac_f32_e32 v13, v59, v157
	v_fmac_f32_e32 v14, v59, v158
	v_fmac_f32_e32 v15, v59, v159
	v_lshl_add_u32 v161, v43, 7, v160
	global_load_dwordx4 v[124:127], v161, s[14:15]
	s_waitcnt vmcnt(15)
; DI void phase_peer_b(const Params& p, int layer, const float* gnext, bool last) {
;     ...
; #pragma unroll
;       for (int j = 0; j < 16; ++j) {
;         const int e = bt * 16 + j;
;         const int eidx = __builtin_amdgcn_readlane(e < 64 ? i0 : i1, e & 63);
;         vr[j] = *(const u32x4*)(EV + (size_t)eidx * DM + lane * 16);
;       }
; #pragma unroll
;       for (int j = 0; j < 16; ++j) {
;         const int e = bt * 16 + j;
;         const float wj = __int_as_float(__builtin_amdgcn_readlane(__float_as_int(e < 64 ? w0 : w1), e & 63));
; #pragma unroll
;         for (int w = 0; w < 4; ++w) {
;           const f32x2 lo = __builtin_amdgcn_cvt_pk_f32_fp8((int)vr[j][w], false);
;           const f32x2 hi = __builtin_amdgcn_cvt_pk_f32_fp8((int)vr[j][w], true);
;           acc[4 * w] += wj * lo[0]; acc[4 * w + 1] += wj * lo[1]; acc[4 * w + 2] += wj * hi[0]; acc[4 * w + 3] += wj * hi[1];
;         }
	v_cvt_pk_f32_fp8_e32 v[144:145], v128
	v_cvt_pk_f32_fp8_sdwa v[146:147], v128 src0_sel:WORD_1
	v_cvt_pk_f32_fp8_e32 v[148:149], v129
	v_cvt_pk_f32_fp8_sdwa v[150:151], v129 src0_sel:WORD_1
	v_cvt_pk_f32_fp8_e32 v[152:153], v130
	v_cvt_pk_f32_fp8_sdwa v[154:155], v130 src0_sel:WORD_1
	v_cvt_pk_f32_fp8_e32 v[156:157], v131
	v_cvt_pk_f32_fp8_sdwa v[158:159], v131 src0_sel:WORD_1
	v_fmac_f32_e32 v0, v60, v144
	v_fmac_f32_e32 v1, v60, v145
	v_fmac_f32_e32 v2, v60, v146
	v_fmac_f32_e32 v3, v60, v147
	v_fmac_f32_e32 v4, v60, v148
	v_fmac_f32_e32 v5, v60, v149
	v_fmac_f32_e32 v6, v60, v150
	v_fmac_f32_e32 v7, v60, v151
	v_fmac_f32_e32 v8, v60, v152
	v_fmac_f32_e32 v9, v60, v153
	v_fmac_f32_e32 v10, v60, v154
	v_fmac_f32_e32 v11, v60, v155
	v_fmac_f32_e32 v12, v60, v156
	v_fmac_f32_e32 v13, v60, v157
	v_fmac_f32_e32 v14, v60, v158
	v_fmac_f32_e32 v15, v60, v159
	v_lshl_add_u32 v161, v44, 7, v160
	global_load_dwordx4 v[128:131], v161, s[14:15]
	s_waitcnt vmcnt(15)
	v_cvt_pk_f32_fp8_e32 v[144:145], v132
	v_cvt_pk_f32_fp8_sdwa v[146:147], v132 src0_sel:WORD_1
	v_cvt_pk_f32_fp8_e32 v[148:149], v133
	v_cvt_pk_f32_fp8_sdwa v[150:151], v133 src0_sel:WORD_1
	v_cvt_pk_f32_fp8_e32 v[152:153], v134
	v_cvt_pk_f32_fp8_sdwa v[154:155], v134 src0_sel:WORD_1
	v_cvt_pk_f32_fp8_e32 v[156:157], v135
	v_cvt_pk_f32_fp8_sdwa v[158:159], v135 src0_sel:WORD_1
	v_fmac_f32_e32 v0, v61, v144
	v_fmac_f32_e32 v1, v61, v145
	v_fmac_f32_e32 v2, v61, v146
	v_fmac_f32_e32 v3, v61, v147
	v_fmac_f32_e32 v4, v61, v148
	v_fmac_f32_e32 v5, v61, v149
	v_fmac_f32_e32 v6, v61, v150
	v_fmac_f32_e32 v7, v61, v151
	v_fmac_f32_e32 v8, v61, v152
	v_fmac_f32_e32 v9, v61, v153
	v_fmac_f32_e32 v10, v61, v154
	v_fmac_f32_e32 v11, v61, v155
	v_fmac_f32_e32 v12, v61, v156
	v_fmac_f32_e32 v13, v61, v157
	v_fmac_f32_e32 v14, v61, v158
	v_fmac_f32_e32 v15, v61, v159
	v_lshl_add_u32 v161, v45, 7, v160
	global_load_dwordx4 v[132:135], v161, s[14:15]
	s_waitcnt vmcnt(15)
	v_cvt_pk_f32_fp8_e32 v[144:145], v136
	v_cvt_pk_f32_fp8_sdwa v[146:147], v136 src0_sel:WORD_1
	v_cvt_pk_f32_fp8_e32 v[148:149], v137
	v_cvt_pk_f32_fp8_sdwa v[150:151], v137 src0_sel:WORD_1
	v_cvt_pk_f32_fp8_e32 v[152:153], v138
	v_cvt_pk_f32_fp8_sdwa v[154:155], v138 src0_sel:WORD_1
	v_cvt_pk_f32_fp8_e32 v[156:157], v139
	v_cvt_pk_f32_fp8_sdwa v[158:159], v139 src0_sel:WORD_1
	v_fmac_f32_e32 v0, v62, v144
	v_fmac_f32_e32 v1, v62, v145
	v_fmac_f32_e32 v2, v62, v146
	v_fmac_f32_e32 v3, v62, v147
	v_fmac_f32_e32 v4, v62, v148
	v_fmac_f32_e32 v5, v62, v149
	v_fmac_f32_e32 v6, v62, v150
	v_fmac_f32_e32 v7, v62, v151
	v_fmac_f32_e32 v8, v62, v152
	v_fmac_f32_e32 v9, v62, v153
	v_fmac_f32_e32 v10, v62, v154
	v_fmac_f32_e32 v11, v62, v155
	v_fmac_f32_e32 v12, v62, v156
	v_fmac_f32_e32 v13, v62, v157
	v_fmac_f32_e32 v14, v62, v158
	v_fmac_f32_e32 v15, v62, v159
	v_lshl_add_u32 v161, v46, 7, v160
	global_load_dwordx4 v[136:139], v161, s[14:15]
	s_waitcnt vmcnt(15)
	v_cvt_pk_f32_fp8_e32 v[144:145], v140
	v_cvt_pk_f32_fp8_sdwa v[146:147], v140 src0_sel:WORD_1
	v_cvt_pk_f32_fp8_e32 v[148:149], v141
	v_cvt_pk_f32_fp8_sdwa v[150:151], v141 src0_sel:WORD_1
	v_cvt_pk_f32_fp8_e32 v[152:153], v142
	v_cvt_pk_f32_fp8_sdwa v[154:155], v142 src0_sel:WORD_1
	v_cvt_pk_f32_fp8_e32 v[156:157], v143
	v_cvt_pk_f32_fp8_sdwa v[158:159], v143 src0_sel:WORD_1
	v_fmac_f32_e32 v0, v63, v144
	v_fmac_f32_e32 v1, v63, v145
	v_fmac_f32_e32 v2, v63, v146
	v_fmac_f32_e32 v3, v63, v147
	v_fmac_f32_e32 v4, v63, v148
	v_fmac_f32_e32 v5, v63, v149
	v_fmac_f32_e32 v6, v63, v150
	v_fmac_f32_e32 v7, v63, v151
	v_fmac_f32_e32 v8, v63, v152
	v_fmac_f32_e32 v9, v63, v153
	v_fmac_f32_e32 v10, v63, v154
	v_fmac_f32_e32 v11, v63, v155
	v_fmac_f32_e32 v12, v63, v156
	v_fmac_f32_e32 v13, v63, v157
	v_fmac_f32_e32 v14, v63, v158
	v_fmac_f32_e32 v15, v63, v159
	v_lshl_add_u32 v161, v47, 7, v160
	global_load_dwordx4 v[140:143], v161, s[14:15]
	s_waitcnt lgkmcnt(0)
	ds_read_b128 v[32:35], v163 offset:192
	ds_read_b128 v[36:39], v163 offset:208
	ds_read_b128 v[40:43], v163 offset:224
	ds_read_b128 v[44:47], v163 offset:240
	ds_read_b128 v[48:51], v163 offset:640
	ds_read_b128 v[52:55], v163 offset:656
	ds_read_b128 v[56:59], v163 offset:672
	ds_read_b128 v[60:63], v163 offset:688
	s_waitcnt vmcnt(15)
	v_cvt_pk_f32_fp8_e32 v[144:145], v80
	v_cvt_pk_f32_fp8_sdwa v[146:147], v80 src0_sel:WORD_1
	v_cvt_pk_f32_fp8_e32 v[148:149], v81
	v_cvt_pk_f32_fp8_sdwa v[150:151], v81 src0_sel:WORD_1
	v_cvt_pk_f32_fp8_e32 v[152:153], v82
	v_cvt_pk_f32_fp8_sdwa v[154:155], v82 src0_sel:WORD_1
	v_cvt_pk_f32_fp8_e32 v[156:157], v83
	v_cvt_pk_f32_fp8_sdwa v[158:159], v83 src0_sel:WORD_1
	v_fmac_f32_e32 v0, v64, v144
	v_fmac_f32_e32 v1, v64, v145
	v_fmac_f32_e32 v2, v64, v146
	v_fmac_f32_e32 v3, v64, v147
	v_fmac_f32_e32 v4, v64, v148
	v_fmac_f32_e32 v5, v64, v149
	v_fmac_f32_e32 v6, v64, v150
	v_fmac_f32_e32 v7, v64, v151
	v_fmac_f32_e32 v8, v64, v152
	v_fmac_f32_e32 v9, v64, v153
	v_fmac_f32_e32 v10, v64, v154
	v_fmac_f32_e32 v11, v64, v155
	v_fmac_f32_e32 v12, v64, v156
	v_fmac_f32_e32 v13, v64, v157
	v_fmac_f32_e32 v14, v64, v158
	v_fmac_f32_e32 v15, v64, v159
	v_lshl_add_u32 v161, v16, 7, v160
	global_load_dwordx4 v[80:83], v161, s[14:15]
	s_waitcnt vmcnt(15)
; DI void phase_peer_b(const Params& p, int layer, const float* gnext, bool last) {
;     ...
; #pragma unroll
;       for (int j = 0; j < 16; ++j) {
;         const int e = bt * 16 + j;
;         const int eidx = __builtin_amdgcn_readlane(e < 64 ? i0 : i1, e & 63);
;         vr[j] = *(const u32x4*)(EV + (size_t)eidx * DM + lane * 16);
;       }
; #pragma unroll
;       for (int j = 0; j < 16; ++j) {
;         const int e = bt * 16 + j;
;         const float wj = __int_as_float(__builtin_amdgcn_readlane(__float_as_int(e < 64 ? w0 : w1), e & 63));
; #pragma unroll
;         for (int w = 0; w < 4; ++w) {
;           const f32x2 lo = __builtin_amdgcn_cvt_pk_f32_fp8((int)vr[j][w], false);
;           const f32x2 hi = __builtin_amdgcn_cvt_pk_f32_fp8((int)vr[j][w], true);
;           acc[4 * w] += wj * lo[0]; acc[4 * w + 1] += wj * lo[1]; acc[4 * w + 2] += wj * hi[0]; acc[4 * w + 3] += wj * hi[1];
;         }
	v_cvt_pk_f32_fp8_e32 v[144:145], v84
	v_cvt_pk_f32_fp8_sdwa v[146:147], v84 src0_sel:WORD_1
	v_cvt_pk_f32_fp8_e32 v[148:149], v85
	v_cvt_pk_f32_fp8_sdwa v[150:151], v85 src0_sel:WORD_1
	v_cvt_pk_f32_fp8_e32 v[152:153], v86
	v_cvt_pk_f32_fp8_sdwa v[154:155], v86 src0_sel:WORD_1
	v_cvt_pk_f32_fp8_e32 v[156:157], v87
	v_cvt_pk_f32_fp8_sdwa v[158:159], v87 src0_sel:WORD_1
	v_fmac_f32_e32 v0, v65, v144
	v_fmac_f32_e32 v1, v65, v145
	v_fmac_f32_e32 v2, v65, v146
	v_fmac_f32_e32 v3, v65, v147
	v_fmac_f32_e32 v4, v65, v148
	v_fmac_f32_e32 v5, v65, v149
	v_fmac_f32_e32 v6, v65, v150
	v_fmac_f32_e32 v7, v65, v151
	v_fmac_f32_e32 v8, v65, v152
	v_fmac_f32_e32 v9, v65, v153
	v_fmac_f32_e32 v10, v65, v154
	v_fmac_f32_e32 v11, v65, v155
	v_fmac_f32_e32 v12, v65, v156
	v_fmac_f32_e32 v13, v65, v157
	v_fmac_f32_e32 v14, v65, v158
	v_fmac_f32_e32 v15, v65, v159
	v_lshl_add_u32 v161, v17, 7, v160
	global_load_dwordx4 v[84:87], v161, s[14:15]
	s_waitcnt vmcnt(15)
	v_cvt_pk_f32_fp8_e32 v[144:145], v88
	v_cvt_pk_f32_fp8_sdwa v[146:147], v88 src0_sel:WORD_1
	v_cvt_pk_f32_fp8_e32 v[148:149], v89
	v_cvt_pk_f32_fp8_sdwa v[150:151], v89 src0_sel:WORD_1
	v_cvt_pk_f32_fp8_e32 v[152:153], v90
	v_cvt_pk_f32_fp8_sdwa v[154:155], v90 src0_sel:WORD_1
	v_cvt_pk_f32_fp8_e32 v[156:157], v91
	v_cvt_pk_f32_fp8_sdwa v[158:159], v91 src0_sel:WORD_1
	v_fmac_f32_e32 v0, v66, v144
	v_fmac_f32_e32 v1, v66, v145
	v_fmac_f32_e32 v2, v66, v146
	v_fmac_f32_e32 v3, v66, v147
	v_fmac_f32_e32 v4, v66, v148
	v_fmac_f32_e32 v5, v66, v149
	v_fmac_f32_e32 v6, v66, v150
	v_fmac_f32_e32 v7, v66, v151
	v_fmac_f32_e32 v8, v66, v152
	v_fmac_f32_e32 v9, v66, v153
	v_fmac_f32_e32 v10, v66, v154
	v_fmac_f32_e32 v11, v66, v155
	v_fmac_f32_e32 v12, v66, v156
	v_fmac_f32_e32 v13, v66, v157
	v_fmac_f32_e32 v14, v66, v158
	v_fmac_f32_e32 v15, v66, v159
	v_lshl_add_u32 v161, v18, 7, v160
	global_load_dwordx4 v[88:91], v161, s[14:15]
	s_waitcnt vmcnt(15)
	v_cvt_pk_f32_fp8_e32 v[144:145], v92
	v_cvt_pk_f32_fp8_sdwa v[146:147], v92 src0_sel:WORD_1
	v_cvt_pk_f32_fp8_e32 v[148:149], v93
	v_cvt_pk_f32_fp8_sdwa v[150:151], v93 src0_sel:WORD_1
	v_cvt_pk_f32_fp8_e32 v[152:153], v94
	v_cvt_pk_f32_fp8_sdwa v[154:155], v94 src0_sel:WORD_1
	v_cvt_pk_f32_fp8_e32 v[156:157], v95
	v_cvt_pk_f32_fp8_sdwa v[158:159], v95 src0_sel:WORD_1
	v_fmac_f32_e32 v0, v67, v144
	v_fmac_f32_e32 v1, v67, v145
	v_fmac_f32_e32 v2, v67, v146
	v_fmac_f32_e32 v3, v67, v147
	v_fmac_f32_e32 v4, v67, v148
	v_fmac_f32_e32 v5, v67, v149
	v_fmac_f32_e32 v6, v67, v150
	v_fmac_f32_e32 v7, v67, v151
	v_fmac_f32_e32 v8, v67, v152
	v_fmac_f32_e32 v9, v67, v153
	v_fmac_f32_e32 v10, v67, v154
	v_fmac_f32_e32 v11, v67, v155
	v_fmac_f32_e32 v12, v67, v156
	v_fmac_f32_e32 v13, v67, v157
	v_fmac_f32_e32 v14, v67, v158
	v_fmac_f32_e32 v15, v67, v159
	v_lshl_add_u32 v161, v19, 7, v160
	global_load_dwordx4 v[92:95], v161, s[14:15]
	s_waitcnt vmcnt(15)
	v_cvt_pk_f32_fp8_e32 v[144:145], v96
	v_cvt_pk_f32_fp8_sdwa v[146:147], v96 src0_sel:WORD_1
	v_cvt_pk_f32_fp8_e32 v[148:149], v97
	v_cvt_pk_f32_fp8_sdwa v[150:151], v97 src0_sel:WORD_1
	v_cvt_pk_f32_fp8_e32 v[152:153], v98
	v_cvt_pk_f32_fp8_sdwa v[154:155], v98 src0_sel:WORD_1
	v_cvt_pk_f32_fp8_e32 v[156:157], v99
	v_cvt_pk_f32_fp8_sdwa v[158:159], v99 src0_sel:WORD_1
	v_fmac_f32_e32 v0, v68, v144
	v_fmac_f32_e32 v1, v68, v145
	v_fmac_f32_e32 v2, v68, v146
	v_fmac_f32_e32 v3, v68, v147
	v_fmac_f32_e32 v4, v68, v148
	v_fmac_f32_e32 v5, v68, v149
	v_fmac_f32_e32 v6, v68, v150
	v_fmac_f32_e32 v7, v68, v151
	v_fmac_f32_e32 v8, v68, v152
	v_fmac_f32_e32 v9, v68, v153
	v_fmac_f32_e32 v10, v68, v154
	v_fmac_f32_e32 v11, v68, v155
	v_fmac_f32_e32 v12, v68, v156
	v_fmac_f32_e32 v13, v68, v157
	v_fmac_f32_e32 v14, v68, v158
	v_fmac_f32_e32 v15, v68, v159
	v_lshl_add_u32 v161, v20, 7, v160
	global_load_dwordx4 v[96:99], v161, s[14:15]
	s_waitcnt vmcnt(15)
	v_cvt_pk_f32_fp8_e32 v[144:145], v100
	v_cvt_pk_f32_fp8_sdwa v[146:147], v100 src0_sel:WORD_1
	v_cvt_pk_f32_fp8_e32 v[148:149], v101
	v_cvt_pk_f32_fp8_sdwa v[150:151], v101 src0_sel:WORD_1
	v_cvt_pk_f32_fp8_e32 v[152:153], v102
	v_cvt_pk_f32_fp8_sdwa v[154:155], v102 src0_sel:WORD_1
	v_cvt_pk_f32_fp8_e32 v[156:157], v103
	v_cvt_pk_f32_fp8_sdwa v[158:159], v103 src0_sel:WORD_1
	v_fmac_f32_e32 v0, v69, v144
	v_fmac_f32_e32 v1, v69, v145
	v_fmac_f32_e32 v2, v69, v146
	v_fmac_f32_e32 v3, v69, v147
	v_fmac_f32_e32 v4, v69, v148
	v_fmac_f32_e32 v5, v69, v149
	v_fmac_f32_e32 v6, v69, v150
	v_fmac_f32_e32 v7, v69, v151
	v_fmac_f32_e32 v8, v69, v152
	v_fmac_f32_e32 v9, v69, v153
	v_fmac_f32_e32 v10, v69, v154
	v_fmac_f32_e32 v11, v69, v155
	v_fmac_f32_e32 v12, v69, v156
	v_fmac_f32_e32 v13, v69, v157
	v_fmac_f32_e32 v14, v69, v158
	v_fmac_f32_e32 v15, v69, v159
	v_lshl_add_u32 v161, v21, 7, v160
	global_load_dwordx4 v[100:103], v161, s[14:15]
	s_waitcnt vmcnt(15)
	v_cvt_pk_f32_fp8_e32 v[144:145], v104
	v_cvt_pk_f32_fp8_sdwa v[146:147], v104 src0_sel:WORD_1
	v_cvt_pk_f32_fp8_e32 v[148:149], v105
	v_cvt_pk_f32_fp8_sdwa v[150:151], v105 src0_sel:WORD_1
	v_cvt_pk_f32_fp8_e32 v[152:153], v106
	v_cvt_pk_f32_fp8_sdwa v[154:155], v106 src0_sel:WORD_1
	v_cvt_pk_f32_fp8_e32 v[156:157], v107
	v_cvt_pk_f32_fp8_sdwa v[158:159], v107 src0_sel:WORD_1
	v_fmac_f32_e32 v0, v70, v144
	v_fmac_f32_e32 v1, v70, v145
	v_fmac_f32_e32 v2, v70, v146
	v_fmac_f32_e32 v3, v70, v147
	v_fmac_f32_e32 v4, v70, v148
	v_fmac_f32_e32 v5, v70, v149
	v_fmac_f32_e32 v6, v70, v150
	v_fmac_f32_e32 v7, v70, v151
	v_fmac_f32_e32 v8, v70, v152
	v_fmac_f32_e32 v9, v70, v153
	v_fmac_f32_e32 v10, v70, v154
	v_fmac_f32_e32 v11, v70, v155
	v_fmac_f32_e32 v12, v70, v156
	v_fmac_f32_e32 v13, v70, v157
	v_fmac_f32_e32 v14, v70, v158
	v_fmac_f32_e32 v15, v70, v159
	v_lshl_add_u32 v161, v22, 7, v160
	global_load_dwordx4 v[104:107], v161, s[14:15]
	s_waitcnt vmcnt(15)
; DI void phase_peer_b(const Params& p, int layer, const float* gnext, bool last) {
;     ...
; #pragma unroll
;       for (int j = 0; j < 16; ++j) {
;         const int e = bt * 16 + j;
;         const int eidx = __builtin_amdgcn_readlane(e < 64 ? i0 : i1, e & 63);
;         vr[j] = *(const u32x4*)(EV + (size_t)eidx * DM + lane * 16);
;       }
; #pragma unroll
;       for (int j = 0; j < 16; ++j) {
;         const int e = bt * 16 + j;
;         const float wj = __int_as_float(__builtin_amdgcn_readlane(__float_as_int(e < 64 ? w0 : w1), e & 63));
; #pragma unroll
;         for (int w = 0; w < 4; ++w) {
;           const f32x2 lo = __builtin_amdgcn_cvt_pk_f32_fp8((int)vr[j][w], false);
;           const f32x2 hi = __builtin_amdgcn_cvt_pk_f32_fp8((int)vr[j][w], true);
;           acc[4 * w] += wj * lo[0]; acc[4 * w + 1] += wj * lo[1]; acc[4 * w + 2] += wj * hi[0]; acc[4 * w + 3] += wj * hi[1];
;         }
	v_cvt_pk_f32_fp8_e32 v[144:145], v108
	v_cvt_pk_f32_fp8_sdwa v[146:147], v108 src0_sel:WORD_1
	v_cvt_pk_f32_fp8_e32 v[148:149], v109
	v_cvt_pk_f32_fp8_sdwa v[150:151], v109 src0_sel:WORD_1
	v_cvt_pk_f32_fp8_e32 v[152:153], v110
	v_cvt_pk_f32_fp8_sdwa v[154:155], v110 src0_sel:WORD_1
	v_cvt_pk_f32_fp8_e32 v[156:157], v111
	v_cvt_pk_f32_fp8_sdwa v[158:159], v111 src0_sel:WORD_1
	v_fmac_f32_e32 v0, v71, v144
	v_fmac_f32_e32 v1, v71, v145
	v_fmac_f32_e32 v2, v71, v146
	v_fmac_f32_e32 v3, v71, v147
	v_fmac_f32_e32 v4, v71, v148
	v_fmac_f32_e32 v5, v71, v149
	v_fmac_f32_e32 v6, v71, v150
	v_fmac_f32_e32 v7, v71, v151
	v_fmac_f32_e32 v8, v71, v152
	v_fmac_f32_e32 v9, v71, v153
	v_fmac_f32_e32 v10, v71, v154
	v_fmac_f32_e32 v11, v71, v155
	v_fmac_f32_e32 v12, v71, v156
	v_fmac_f32_e32 v13, v71, v157
	v_fmac_f32_e32 v14, v71, v158
	v_fmac_f32_e32 v15, v71, v159
	v_lshl_add_u32 v161, v23, 7, v160
	global_load_dwordx4 v[108:111], v161, s[14:15]
	s_waitcnt vmcnt(15)
	v_cvt_pk_f32_fp8_e32 v[144:145], v112
	v_cvt_pk_f32_fp8_sdwa v[146:147], v112 src0_sel:WORD_1
	v_cvt_pk_f32_fp8_e32 v[148:149], v113
	v_cvt_pk_f32_fp8_sdwa v[150:151], v113 src0_sel:WORD_1
	v_cvt_pk_f32_fp8_e32 v[152:153], v114
	v_cvt_pk_f32_fp8_sdwa v[154:155], v114 src0_sel:WORD_1
	v_cvt_pk_f32_fp8_e32 v[156:157], v115
	v_cvt_pk_f32_fp8_sdwa v[158:159], v115 src0_sel:WORD_1
	v_fmac_f32_e32 v0, v72, v144
	v_fmac_f32_e32 v1, v72, v145
	v_fmac_f32_e32 v2, v72, v146
	v_fmac_f32_e32 v3, v72, v147
	v_fmac_f32_e32 v4, v72, v148
	v_fmac_f32_e32 v5, v72, v149
	v_fmac_f32_e32 v6, v72, v150
	v_fmac_f32_e32 v7, v72, v151
	v_fmac_f32_e32 v8, v72, v152
	v_fmac_f32_e32 v9, v72, v153
	v_fmac_f32_e32 v10, v72, v154
	v_fmac_f32_e32 v11, v72, v155
	v_fmac_f32_e32 v12, v72, v156
	v_fmac_f32_e32 v13, v72, v157
	v_fmac_f32_e32 v14, v72, v158
	v_fmac_f32_e32 v15, v72, v159
	v_lshl_add_u32 v161, v24, 7, v160
	global_load_dwordx4 v[112:115], v161, s[14:15]
	s_waitcnt vmcnt(15)
	v_cvt_pk_f32_fp8_e32 v[144:145], v116
	v_cvt_pk_f32_fp8_sdwa v[146:147], v116 src0_sel:WORD_1
	v_cvt_pk_f32_fp8_e32 v[148:149], v117
	v_cvt_pk_f32_fp8_sdwa v[150:151], v117 src0_sel:WORD_1
	v_cvt_pk_f32_fp8_e32 v[152:153], v118
	v_cvt_pk_f32_fp8_sdwa v[154:155], v118 src0_sel:WORD_1
	v_cvt_pk_f32_fp8_e32 v[156:157], v119
	v_cvt_pk_f32_fp8_sdwa v[158:159], v119 src0_sel:WORD_1
	v_fmac_f32_e32 v0, v73, v144
	v_fmac_f32_e32 v1, v73, v145
	v_fmac_f32_e32 v2, v73, v146
	v_fmac_f32_e32 v3, v73, v147
	v_fmac_f32_e32 v4, v73, v148
	v_fmac_f32_e32 v5, v73, v149
	v_fmac_f32_e32 v6, v73, v150
	v_fmac_f32_e32 v7, v73, v151
	v_fmac_f32_e32 v8, v73, v152
	v_fmac_f32_e32 v9, v73, v153
	v_fmac_f32_e32 v10, v73, v154
	v_fmac_f32_e32 v11, v73, v155
	v_fmac_f32_e32 v12, v73, v156
	v_fmac_f32_e32 v13, v73, v157
	v_fmac_f32_e32 v14, v73, v158
	v_fmac_f32_e32 v15, v73, v159
	v_lshl_add_u32 v161, v25, 7, v160
	global_load_dwordx4 v[116:119], v161, s[14:15]
	s_waitcnt vmcnt(15)
	v_cvt_pk_f32_fp8_e32 v[144:145], v120
	v_cvt_pk_f32_fp8_sdwa v[146:147], v120 src0_sel:WORD_1
	v_cvt_pk_f32_fp8_e32 v[148:149], v121
	v_cvt_pk_f32_fp8_sdwa v[150:151], v121 src0_sel:WORD_1
	v_cvt_pk_f32_fp8_e32 v[152:153], v122
	v_cvt_pk_f32_fp8_sdwa v[154:155], v122 src0_sel:WORD_1
	v_cvt_pk_f32_fp8_e32 v[156:157], v123
	v_cvt_pk_f32_fp8_sdwa v[158:159], v123 src0_sel:WORD_1
	v_fmac_f32_e32 v0, v74, v144
	v_fmac_f32_e32 v1, v74, v145
	v_fmac_f32_e32 v2, v74, v146
	v_fmac_f32_e32 v3, v74, v147
	v_fmac_f32_e32 v4, v74, v148
	v_fmac_f32_e32 v5, v74, v149
	v_fmac_f32_e32 v6, v74, v150
	v_fmac_f32_e32 v7, v74, v151
	v_fmac_f32_e32 v8, v74, v152
	v_fmac_f32_e32 v9, v74, v153
	v_fmac_f32_e32 v10, v74, v154
	v_fmac_f32_e32 v11, v74, v155
	v_fmac_f32_e32 v12, v74, v156
	v_fmac_f32_e32 v13, v74, v157
	v_fmac_f32_e32 v14, v74, v158
	v_fmac_f32_e32 v15, v74, v159
	v_lshl_add_u32 v161, v26, 7, v160
	global_load_dwordx4 v[120:123], v161, s[14:15]
	s_waitcnt vmcnt(15)
	v_cvt_pk_f32_fp8_e32 v[144:145], v124
	v_cvt_pk_f32_fp8_sdwa v[146:147], v124 src0_sel:WORD_1
	v_cvt_pk_f32_fp8_e32 v[148:149], v125
	v_cvt_pk_f32_fp8_sdwa v[150:151], v125 src0_sel:WORD_1
	v_cvt_pk_f32_fp8_e32 v[152:153], v126
	v_cvt_pk_f32_fp8_sdwa v[154:155], v126 src0_sel:WORD_1
	v_cvt_pk_f32_fp8_e32 v[156:157], v127
	v_cvt_pk_f32_fp8_sdwa v[158:159], v127 src0_sel:WORD_1
	v_fmac_f32_e32 v0, v75, v144
	v_fmac_f32_e32 v1, v75, v145
	v_fmac_f32_e32 v2, v75, v146
	v_fmac_f32_e32 v3, v75, v147
	v_fmac_f32_e32 v4, v75, v148
	v_fmac_f32_e32 v5, v75, v149
	v_fmac_f32_e32 v6, v75, v150
	v_fmac_f32_e32 v7, v75, v151
	v_fmac_f32_e32 v8, v75, v152
	v_fmac_f32_e32 v9, v75, v153
	v_fmac_f32_e32 v10, v75, v154
	v_fmac_f32_e32 v11, v75, v155
	v_fmac_f32_e32 v12, v75, v156
	v_fmac_f32_e32 v13, v75, v157
	v_fmac_f32_e32 v14, v75, v158
	v_fmac_f32_e32 v15, v75, v159
	v_lshl_add_u32 v161, v27, 7, v160
	global_load_dwordx4 v[124:127], v161, s[14:15]
	s_waitcnt vmcnt(15)
	v_cvt_pk_f32_fp8_e32 v[144:145], v128
	v_cvt_pk_f32_fp8_sdwa v[146:147], v128 src0_sel:WORD_1
	v_cvt_pk_f32_fp8_e32 v[148:149], v129
	v_cvt_pk_f32_fp8_sdwa v[150:151], v129 src0_sel:WORD_1
	v_cvt_pk_f32_fp8_e32 v[152:153], v130
	v_cvt_pk_f32_fp8_sdwa v[154:155], v130 src0_sel:WORD_1
	v_cvt_pk_f32_fp8_e32 v[156:157], v131
	v_cvt_pk_f32_fp8_sdwa v[158:159], v131 src0_sel:WORD_1
	v_fmac_f32_e32 v0, v76, v144
	v_fmac_f32_e32 v1, v76, v145
	v_fmac_f32_e32 v2, v76, v146
	v_fmac_f32_e32 v3, v76, v147
	v_fmac_f32_e32 v4, v76, v148
	v_fmac_f32_e32 v5, v76, v149
	v_fmac_f32_e32 v6, v76, v150
	v_fmac_f32_e32 v7, v76, v151
	v_fmac_f32_e32 v8, v76, v152
	v_fmac_f32_e32 v9, v76, v153
	v_fmac_f32_e32 v10, v76, v154
	v_fmac_f32_e32 v11, v76, v155
	v_fmac_f32_e32 v12, v76, v156
	v_fmac_f32_e32 v13, v76, v157
	v_fmac_f32_e32 v14, v76, v158
	v_fmac_f32_e32 v15, v76, v159
	v_lshl_add_u32 v161, v28, 7, v160
	global_load_dwordx4 v[128:131], v161, s[14:15]
	s_waitcnt vmcnt(15)
; DI void phase_peer_b(const Params& p, int layer, const float* gnext, bool last) {
;     ...
; #pragma unroll
;       for (int j = 0; j < 16; ++j) {
;         const int e = bt * 16 + j;
;         const int eidx = __builtin_amdgcn_readlane(e < 64 ? i0 : i1, e & 63);
;         vr[j] = *(const u32x4*)(EV + (size_t)eidx * DM + lane * 16);
;       }
; #pragma unroll
;       for (int j = 0; j < 16; ++j) {
;         const int e = bt * 16 + j;
;         const float wj = __int_as_float(__builtin_amdgcn_readlane(__float_as_int(e < 64 ? w0 : w1), e & 63));
; #pragma unroll
;         for (int w = 0; w < 4; ++w) {
;           const f32x2 lo = __builtin_amdgcn_cvt_pk_f32_fp8((int)vr[j][w], false);
;           const f32x2 hi = __builtin_amdgcn_cvt_pk_f32_fp8((int)vr[j][w], true);
;           acc[4 * w] += wj * lo[0]; acc[4 * w + 1] += wj * lo[1]; acc[4 * w + 2] += wj * hi[0]; acc[4 * w + 3] += wj * hi[1];
;         }
	v_cvt_pk_f32_fp8_e32 v[144:145], v132
	v_cvt_pk_f32_fp8_sdwa v[146:147], v132 src0_sel:WORD_1
	v_cvt_pk_f32_fp8_e32 v[148:149], v133
	v_cvt_pk_f32_fp8_sdwa v[150:151], v133 src0_sel:WORD_1
	v_cvt_pk_f32_fp8_e32 v[152:153], v134
	v_cvt_pk_f32_fp8_sdwa v[154:155], v134 src0_sel:WORD_1
	v_cvt_pk_f32_fp8_e32 v[156:157], v135
	v_cvt_pk_f32_fp8_sdwa v[158:159], v135 src0_sel:WORD_1
	v_fmac_f32_e32 v0, v77, v144
	v_fmac_f32_e32 v1, v77, v145
	v_fmac_f32_e32 v2, v77, v146
	v_fmac_f32_e32 v3, v77, v147
	v_fmac_f32_e32 v4, v77, v148
	v_fmac_f32_e32 v5, v77, v149
	v_fmac_f32_e32 v6, v77, v150
	v_fmac_f32_e32 v7, v77, v151
	v_fmac_f32_e32 v8, v77, v152
	v_fmac_f32_e32 v9, v77, v153
	v_fmac_f32_e32 v10, v77, v154
	v_fmac_f32_e32 v11, v77, v155
	v_fmac_f32_e32 v12, v77, v156
	v_fmac_f32_e32 v13, v77, v157
	v_fmac_f32_e32 v14, v77, v158
	v_fmac_f32_e32 v15, v77, v159
	v_lshl_add_u32 v161, v29, 7, v160
	global_load_dwordx4 v[132:135], v161, s[14:15]
	s_waitcnt vmcnt(15)
	v_cvt_pk_f32_fp8_e32 v[144:145], v136
	v_cvt_pk_f32_fp8_sdwa v[146:147], v136 src0_sel:WORD_1
	v_cvt_pk_f32_fp8_e32 v[148:149], v137
	v_cvt_pk_f32_fp8_sdwa v[150:151], v137 src0_sel:WORD_1
	v_cvt_pk_f32_fp8_e32 v[152:153], v138
	v_cvt_pk_f32_fp8_sdwa v[154:155], v138 src0_sel:WORD_1
	v_cvt_pk_f32_fp8_e32 v[156:157], v139
	v_cvt_pk_f32_fp8_sdwa v[158:159], v139 src0_sel:WORD_1
	v_fmac_f32_e32 v0, v78, v144
	v_fmac_f32_e32 v1, v78, v145
	v_fmac_f32_e32 v2, v78, v146
	v_fmac_f32_e32 v3, v78, v147
	v_fmac_f32_e32 v4, v78, v148
	v_fmac_f32_e32 v5, v78, v149
	v_fmac_f32_e32 v6, v78, v150
	v_fmac_f32_e32 v7, v78, v151
	v_fmac_f32_e32 v8, v78, v152
	v_fmac_f32_e32 v9, v78, v153
	v_fmac_f32_e32 v10, v78, v154
	v_fmac_f32_e32 v11, v78, v155
	v_fmac_f32_e32 v12, v78, v156
	v_fmac_f32_e32 v13, v78, v157
	v_fmac_f32_e32 v14, v78, v158
	v_fmac_f32_e32 v15, v78, v159
	v_lshl_add_u32 v161, v30, 7, v160
	global_load_dwordx4 v[136:139], v161, s[14:15]
	s_waitcnt vmcnt(15)
	v_cvt_pk_f32_fp8_e32 v[144:145], v140
	v_cvt_pk_f32_fp8_sdwa v[146:147], v140 src0_sel:WORD_1
	v_cvt_pk_f32_fp8_e32 v[148:149], v141
	v_cvt_pk_f32_fp8_sdwa v[150:151], v141 src0_sel:WORD_1
	v_cvt_pk_f32_fp8_e32 v[152:153], v142
	v_cvt_pk_f32_fp8_sdwa v[154:155], v142 src0_sel:WORD_1
	v_cvt_pk_f32_fp8_e32 v[156:157], v143
	v_cvt_pk_f32_fp8_sdwa v[158:159], v143 src0_sel:WORD_1
	v_fmac_f32_e32 v0, v79, v144
	v_fmac_f32_e32 v1, v79, v145
	v_fmac_f32_e32 v2, v79, v146
	v_fmac_f32_e32 v3, v79, v147
	v_fmac_f32_e32 v4, v79, v148
	v_fmac_f32_e32 v5, v79, v149
	v_fmac_f32_e32 v6, v79, v150
	v_fmac_f32_e32 v7, v79, v151
	v_fmac_f32_e32 v8, v79, v152
	v_fmac_f32_e32 v9, v79, v153
	v_fmac_f32_e32 v10, v79, v154
	v_fmac_f32_e32 v11, v79, v155
	v_fmac_f32_e32 v12, v79, v156
	v_fmac_f32_e32 v13, v79, v157
	v_fmac_f32_e32 v14, v79, v158
	v_fmac_f32_e32 v15, v79, v159
	v_lshl_add_u32 v161, v31, 7, v160
	global_load_dwordx4 v[140:143], v161, s[14:15]
	s_waitcnt lgkmcnt(0)
	ds_read_b128 v[16:19], v163 offset:256
	ds_read_b128 v[20:23], v163 offset:272
	ds_read_b128 v[24:27], v163 offset:288
	ds_read_b128 v[28:31], v163 offset:304
	ds_read_b128 v[64:67], v163 offset:704
	ds_read_b128 v[68:71], v163 offset:720
	ds_read_b128 v[72:75], v163 offset:736
	ds_read_b128 v[76:79], v163 offset:752
	s_waitcnt vmcnt(15)
	v_cvt_pk_f32_fp8_e32 v[144:145], v80
	v_cvt_pk_f32_fp8_sdwa v[146:147], v80 src0_sel:WORD_1
	v_cvt_pk_f32_fp8_e32 v[148:149], v81
	v_cvt_pk_f32_fp8_sdwa v[150:151], v81 src0_sel:WORD_1
	v_cvt_pk_f32_fp8_e32 v[152:153], v82
	v_cvt_pk_f32_fp8_sdwa v[154:155], v82 src0_sel:WORD_1
	v_cvt_pk_f32_fp8_e32 v[156:157], v83
	v_cvt_pk_f32_fp8_sdwa v[158:159], v83 src0_sel:WORD_1
	v_fmac_f32_e32 v0, v48, v144
	v_fmac_f32_e32 v1, v48, v145
	v_fmac_f32_e32 v2, v48, v146
	v_fmac_f32_e32 v3, v48, v147
	v_fmac_f32_e32 v4, v48, v148
	v_fmac_f32_e32 v5, v48, v149
	v_fmac_f32_e32 v6, v48, v150
	v_fmac_f32_e32 v7, v48, v151
	v_fmac_f32_e32 v8, v48, v152
	v_fmac_f32_e32 v9, v48, v153
	v_fmac_f32_e32 v10, v48, v154
	v_fmac_f32_e32 v11, v48, v155
	v_fmac_f32_e32 v12, v48, v156
	v_fmac_f32_e32 v13, v48, v157
	v_fmac_f32_e32 v14, v48, v158
	v_fmac_f32_e32 v15, v48, v159
	v_lshl_add_u32 v161, v32, 7, v160
	global_load_dwordx4 v[80:83], v161, s[14:15]
	s_waitcnt vmcnt(15)
	v_cvt_pk_f32_fp8_e32 v[144:145], v84
	v_cvt_pk_f32_fp8_sdwa v[146:147], v84 src0_sel:WORD_1
	v_cvt_pk_f32_fp8_e32 v[148:149], v85
	v_cvt_pk_f32_fp8_sdwa v[150:151], v85 src0_sel:WORD_1
	v_cvt_pk_f32_fp8_e32 v[152:153], v86
	v_cvt_pk_f32_fp8_sdwa v[154:155], v86 src0_sel:WORD_1
	v_cvt_pk_f32_fp8_e32 v[156:157], v87
	v_cvt_pk_f32_fp8_sdwa v[158:159], v87 src0_sel:WORD_1
	v_fmac_f32_e32 v0, v49, v144
	v_fmac_f32_e32 v1, v49, v145
	v_fmac_f32_e32 v2, v49, v146
	v_fmac_f32_e32 v3, v49, v147
	v_fmac_f32_e32 v4, v49, v148
	v_fmac_f32_e32 v5, v49, v149
	v_fmac_f32_e32 v6, v49, v150
	v_fmac_f32_e32 v7, v49, v151
	v_fmac_f32_e32 v8, v49, v152
	v_fmac_f32_e32 v9, v49, v153
	v_fmac_f32_e32 v10, v49, v154
	v_fmac_f32_e32 v11, v49, v155
	v_fmac_f32_e32 v12, v49, v156
	v_fmac_f32_e32 v13, v49, v157
	v_fmac_f32_e32 v14, v49, v158
	v_fmac_f32_e32 v15, v49, v159
	v_lshl_add_u32 v161, v33, 7, v160
	global_load_dwordx4 v[84:87], v161, s[14:15]
	s_waitcnt vmcnt(15)
; DI void phase_peer_b(const Params& p, int layer, const float* gnext, bool last) {
;     ...
; #pragma unroll
;       for (int j = 0; j < 16; ++j) {
;         const int e = bt * 16 + j;
;         const int eidx = __builtin_amdgcn_readlane(e < 64 ? i0 : i1, e & 63);
;         vr[j] = *(const u32x4*)(EV + (size_t)eidx * DM + lane * 16);
;       }
; #pragma unroll
;       for (int j = 0; j < 16; ++j) {
;         const int e = bt * 16 + j;
;         const float wj = __int_as_float(__builtin_amdgcn_readlane(__float_as_int(e < 64 ? w0 : w1), e & 63));
; #pragma unroll
;         for (int w = 0; w < 4; ++w) {
;           const f32x2 lo = __builtin_amdgcn_cvt_pk_f32_fp8((int)vr[j][w], false);
;           const f32x2 hi = __builtin_amdgcn_cvt_pk_f32_fp8((int)vr[j][w], true);
;           acc[4 * w] += wj * lo[0]; acc[4 * w + 1] += wj * lo[1]; acc[4 * w + 2] += wj * hi[0]; acc[4 * w + 3] += wj * hi[1];
;         }
	v_cvt_pk_f32_fp8_e32 v[144:145], v88
	v_cvt_pk_f32_fp8_sdwa v[146:147], v88 src0_sel:WORD_1
	v_cvt_pk_f32_fp8_e32 v[148:149], v89
	v_cvt_pk_f32_fp8_sdwa v[150:151], v89 src0_sel:WORD_1
	v_cvt_pk_f32_fp8_e32 v[152:153], v90
	v_cvt_pk_f32_fp8_sdwa v[154:155], v90 src0_sel:WORD_1
	v_cvt_pk_f32_fp8_e32 v[156:157], v91
	v_cvt_pk_f32_fp8_sdwa v[158:159], v91 src0_sel:WORD_1
	v_fmac_f32_e32 v0, v50, v144
	v_fmac_f32_e32 v1, v50, v145
	v_fmac_f32_e32 v2, v50, v146
	v_fmac_f32_e32 v3, v50, v147
	v_fmac_f32_e32 v4, v50, v148
	v_fmac_f32_e32 v5, v50, v149
	v_fmac_f32_e32 v6, v50, v150
	v_fmac_f32_e32 v7, v50, v151
	v_fmac_f32_e32 v8, v50, v152
	v_fmac_f32_e32 v9, v50, v153
	v_fmac_f32_e32 v10, v50, v154
	v_fmac_f32_e32 v11, v50, v155
	v_fmac_f32_e32 v12, v50, v156
	v_fmac_f32_e32 v13, v50, v157
	v_fmac_f32_e32 v14, v50, v158
	v_fmac_f32_e32 v15, v50, v159
	v_lshl_add_u32 v161, v34, 7, v160
	global_load_dwordx4 v[88:91], v161, s[14:15]
	s_waitcnt vmcnt(15)
	v_cvt_pk_f32_fp8_e32 v[144:145], v92
	v_cvt_pk_f32_fp8_sdwa v[146:147], v92 src0_sel:WORD_1
	v_cvt_pk_f32_fp8_e32 v[148:149], v93
	v_cvt_pk_f32_fp8_sdwa v[150:151], v93 src0_sel:WORD_1
	v_cvt_pk_f32_fp8_e32 v[152:153], v94
	v_cvt_pk_f32_fp8_sdwa v[154:155], v94 src0_sel:WORD_1
	v_cvt_pk_f32_fp8_e32 v[156:157], v95
	v_cvt_pk_f32_fp8_sdwa v[158:159], v95 src0_sel:WORD_1
	v_fmac_f32_e32 v0, v51, v144
	v_fmac_f32_e32 v1, v51, v145
	v_fmac_f32_e32 v2, v51, v146
	v_fmac_f32_e32 v3, v51, v147
	v_fmac_f32_e32 v4, v51, v148
	v_fmac_f32_e32 v5, v51, v149
	v_fmac_f32_e32 v6, v51, v150
	v_fmac_f32_e32 v7, v51, v151
	v_fmac_f32_e32 v8, v51, v152
	v_fmac_f32_e32 v9, v51, v153
	v_fmac_f32_e32 v10, v51, v154
	v_fmac_f32_e32 v11, v51, v155
	v_fmac_f32_e32 v12, v51, v156
	v_fmac_f32_e32 v13, v51, v157
	v_fmac_f32_e32 v14, v51, v158
	v_fmac_f32_e32 v15, v51, v159
	v_lshl_add_u32 v161, v35, 7, v160
	global_load_dwordx4 v[92:95], v161, s[14:15]
	s_waitcnt vmcnt(15)
	v_cvt_pk_f32_fp8_e32 v[144:145], v96
	v_cvt_pk_f32_fp8_sdwa v[146:147], v96 src0_sel:WORD_1
	v_cvt_pk_f32_fp8_e32 v[148:149], v97
	v_cvt_pk_f32_fp8_sdwa v[150:151], v97 src0_sel:WORD_1
	v_cvt_pk_f32_fp8_e32 v[152:153], v98
	v_cvt_pk_f32_fp8_sdwa v[154:155], v98 src0_sel:WORD_1
	v_cvt_pk_f32_fp8_e32 v[156:157], v99
	v_cvt_pk_f32_fp8_sdwa v[158:159], v99 src0_sel:WORD_1
	v_fmac_f32_e32 v0, v52, v144
	v_fmac_f32_e32 v1, v52, v145
	v_fmac_f32_e32 v2, v52, v146
	v_fmac_f32_e32 v3, v52, v147
	v_fmac_f32_e32 v4, v52, v148
	v_fmac_f32_e32 v5, v52, v149
	v_fmac_f32_e32 v6, v52, v150
	v_fmac_f32_e32 v7, v52, v151
	v_fmac_f32_e32 v8, v52, v152
	v_fmac_f32_e32 v9, v52, v153
	v_fmac_f32_e32 v10, v52, v154
	v_fmac_f32_e32 v11, v52, v155
	v_fmac_f32_e32 v12, v52, v156
	v_fmac_f32_e32 v13, v52, v157
	v_fmac_f32_e32 v14, v52, v158
	v_fmac_f32_e32 v15, v52, v159
	v_lshl_add_u32 v161, v36, 7, v160
	global_load_dwordx4 v[96:99], v161, s[14:15]
	s_waitcnt vmcnt(15)
	v_cvt_pk_f32_fp8_e32 v[144:145], v100
	v_cvt_pk_f32_fp8_sdwa v[146:147], v100 src0_sel:WORD_1
	v_cvt_pk_f32_fp8_e32 v[148:149], v101
	v_cvt_pk_f32_fp8_sdwa v[150:151], v101 src0_sel:WORD_1
	v_cvt_pk_f32_fp8_e32 v[152:153], v102
	v_cvt_pk_f32_fp8_sdwa v[154:155], v102 src0_sel:WORD_1
	v_cvt_pk_f32_fp8_e32 v[156:157], v103
	v_cvt_pk_f32_fp8_sdwa v[158:159], v103 src0_sel:WORD_1
	v_fmac_f32_e32 v0, v53, v144
	v_fmac_f32_e32 v1, v53, v145
	v_fmac_f32_e32 v2, v53, v146
	v_fmac_f32_e32 v3, v53, v147
	v_fmac_f32_e32 v4, v53, v148
	v_fmac_f32_e32 v5, v53, v149
	v_fmac_f32_e32 v6, v53, v150
	v_fmac_f32_e32 v7, v53, v151
	v_fmac_f32_e32 v8, v53, v152
	v_fmac_f32_e32 v9, v53, v153
	v_fmac_f32_e32 v10, v53, v154
	v_fmac_f32_e32 v11, v53, v155
	v_fmac_f32_e32 v12, v53, v156
	v_fmac_f32_e32 v13, v53, v157
	v_fmac_f32_e32 v14, v53, v158
	v_fmac_f32_e32 v15, v53, v159
	v_lshl_add_u32 v161, v37, 7, v160
	global_load_dwordx4 v[100:103], v161, s[14:15]
	s_waitcnt vmcnt(15)
	v_cvt_pk_f32_fp8_e32 v[144:145], v104
	v_cvt_pk_f32_fp8_sdwa v[146:147], v104 src0_sel:WORD_1
	v_cvt_pk_f32_fp8_e32 v[148:149], v105
	v_cvt_pk_f32_fp8_sdwa v[150:151], v105 src0_sel:WORD_1
	v_cvt_pk_f32_fp8_e32 v[152:153], v106
	v_cvt_pk_f32_fp8_sdwa v[154:155], v106 src0_sel:WORD_1
	v_cvt_pk_f32_fp8_e32 v[156:157], v107
	v_cvt_pk_f32_fp8_sdwa v[158:159], v107 src0_sel:WORD_1
	v_fmac_f32_e32 v0, v54, v144
	v_fmac_f32_e32 v1, v54, v145
	v_fmac_f32_e32 v2, v54, v146
	v_fmac_f32_e32 v3, v54, v147
	v_fmac_f32_e32 v4, v54, v148
	v_fmac_f32_e32 v5, v54, v149
	v_fmac_f32_e32 v6, v54, v150
	v_fmac_f32_e32 v7, v54, v151
	v_fmac_f32_e32 v8, v54, v152
	v_fmac_f32_e32 v9, v54, v153
	v_fmac_f32_e32 v10, v54, v154
	v_fmac_f32_e32 v11, v54, v155
	v_fmac_f32_e32 v12, v54, v156
	v_fmac_f32_e32 v13, v54, v157
	v_fmac_f32_e32 v14, v54, v158
	v_fmac_f32_e32 v15, v54, v159
	v_lshl_add_u32 v161, v38, 7, v160
	global_load_dwordx4 v[104:107], v161, s[14:15]
	s_waitcnt vmcnt(15)
	v_cvt_pk_f32_fp8_e32 v[144:145], v108
	v_cvt_pk_f32_fp8_sdwa v[146:147], v108 src0_sel:WORD_1
	v_cvt_pk_f32_fp8_e32 v[148:149], v109
	v_cvt_pk_f32_fp8_sdwa v[150:151], v109 src0_sel:WORD_1
	v_cvt_pk_f32_fp8_e32 v[152:153], v110
	v_cvt_pk_f32_fp8_sdwa v[154:155], v110 src0_sel:WORD_1
	v_cvt_pk_f32_fp8_e32 v[156:157], v111
	v_cvt_pk_f32_fp8_sdwa v[158:159], v111 src0_sel:WORD_1
	v_fmac_f32_e32 v0, v55, v144
	v_fmac_f32_e32 v1, v55, v145
	v_fmac_f32_e32 v2, v55, v146
	v_fmac_f32_e32 v3, v55, v147
	v_fmac_f32_e32 v4, v55, v148
	v_fmac_f32_e32 v5, v55, v149
	v_fmac_f32_e32 v6, v55, v150
	v_fmac_f32_e32 v7, v55, v151
	v_fmac_f32_e32 v8, v55, v152
	v_fmac_f32_e32 v9, v55, v153
	v_fmac_f32_e32 v10, v55, v154
	v_fmac_f32_e32 v11, v55, v155
	v_fmac_f32_e32 v12, v55, v156
	v_fmac_f32_e32 v13, v55, v157
	v_fmac_f32_e32 v14, v55, v158
	v_fmac_f32_e32 v15, v55, v159
	v_lshl_add_u32 v161, v39, 7, v160
	global_load_dwordx4 v[108:111], v161, s[14:15]
	s_waitcnt vmcnt(15)
; DI void phase_peer_b(const Params& p, int layer, const float* gnext, bool last) {
;     ...
; #pragma unroll
;       for (int j = 0; j < 16; ++j) {
;         const int e = bt * 16 + j;
;         const float wj = __int_as_float(__builtin_amdgcn_readlane(__float_as_int(e < 64 ? w0 : w1), e & 63));
; #pragma unroll
;         for (int w = 0; w < 4; ++w) {
;           const f32x2 lo = __builtin_amdgcn_cvt_pk_f32_fp8((int)vr[j][w], false);
;           const f32x2 hi = __builtin_amdgcn_cvt_pk_f32_fp8((int)vr[j][w], true);
;           acc[4 * w] += wj * lo[0]; acc[4 * w + 1] += wj * lo[1]; acc[4 * w + 2] += wj * hi[0]; acc[4 * w + 3] += wj * hi[1];
;         }
;       }
	v_cvt_pk_f32_fp8_e32 v[144:145], v112
	v_cvt_pk_f32_fp8_sdwa v[146:147], v112 src0_sel:WORD_1
	v_cvt_pk_f32_fp8_e32 v[148:149], v113
	v_cvt_pk_f32_fp8_sdwa v[150:151], v113 src0_sel:WORD_1
	v_cvt_pk_f32_fp8_e32 v[152:153], v114
	v_cvt_pk_f32_fp8_sdwa v[154:155], v114 src0_sel:WORD_1
	v_cvt_pk_f32_fp8_e32 v[156:157], v115
	v_cvt_pk_f32_fp8_sdwa v[158:159], v115 src0_sel:WORD_1
	v_fmac_f32_e32 v0, v56, v144
	v_fmac_f32_e32 v1, v56, v145
	v_fmac_f32_e32 v2, v56, v146
	v_fmac_f32_e32 v3, v56, v147
	v_fmac_f32_e32 v4, v56, v148
	v_fmac_f32_e32 v5, v56, v149
	v_fmac_f32_e32 v6, v56, v150
	v_fmac_f32_e32 v7, v56, v151
	v_fmac_f32_e32 v8, v56, v152
	v_fmac_f32_e32 v9, v56, v153
	v_fmac_f32_e32 v10, v56, v154
	v_fmac_f32_e32 v11, v56, v155
	v_fmac_f32_e32 v12, v56, v156
	v_fmac_f32_e32 v13, v56, v157
	v_fmac_f32_e32 v14, v56, v158
	v_fmac_f32_e32 v15, v56, v159
	v_lshl_add_u32 v161, v40, 7, v160
	global_load_dwordx4 v[112:115], v161, s[14:15]
	s_waitcnt vmcnt(15)
	v_cvt_pk_f32_fp8_e32 v[144:145], v116
	v_cvt_pk_f32_fp8_sdwa v[146:147], v116 src0_sel:WORD_1
	v_cvt_pk_f32_fp8_e32 v[148:149], v117
	v_cvt_pk_f32_fp8_sdwa v[150:151], v117 src0_sel:WORD_1
	v_cvt_pk_f32_fp8_e32 v[152:153], v118
	v_cvt_pk_f32_fp8_sdwa v[154:155], v118 src0_sel:WORD_1
	v_cvt_pk_f32_fp8_e32 v[156:157], v119
	v_cvt_pk_f32_fp8_sdwa v[158:159], v119 src0_sel:WORD_1
	v_fmac_f32_e32 v0, v57, v144
	v_fmac_f32_e32 v1, v57, v145
	v_fmac_f32_e32 v2, v57, v146
	v_fmac_f32_e32 v3, v57, v147
	v_fmac_f32_e32 v4, v57, v148
	v_fmac_f32_e32 v5, v57, v149
	v_fmac_f32_e32 v6, v57, v150
	v_fmac_f32_e32 v7, v57, v151
	v_fmac_f32_e32 v8, v57, v152
	v_fmac_f32_e32 v9, v57, v153
	v_fmac_f32_e32 v10, v57, v154
	v_fmac_f32_e32 v11, v57, v155
	v_fmac_f32_e32 v12, v57, v156
	v_fmac_f32_e32 v13, v57, v157
	v_fmac_f32_e32 v14, v57, v158
	v_fmac_f32_e32 v15, v57, v159
	v_lshl_add_u32 v161, v41, 7, v160
	global_load_dwordx4 v[116:119], v161, s[14:15]
	s_waitcnt vmcnt(15)
	v_cvt_pk_f32_fp8_e32 v[144:145], v120
	v_cvt_pk_f32_fp8_sdwa v[146:147], v120 src0_sel:WORD_1
	v_cvt_pk_f32_fp8_e32 v[148:149], v121
	v_cvt_pk_f32_fp8_sdwa v[150:151], v121 src0_sel:WORD_1
	v_cvt_pk_f32_fp8_e32 v[152:153], v122
	v_cvt_pk_f32_fp8_sdwa v[154:155], v122 src0_sel:WORD_1
	v_cvt_pk_f32_fp8_e32 v[156:157], v123
	v_cvt_pk_f32_fp8_sdwa v[158:159], v123 src0_sel:WORD_1
	v_fmac_f32_e32 v0, v58, v144
	v_fmac_f32_e32 v1, v58, v145
	v_fmac_f32_e32 v2, v58, v146
	v_fmac_f32_e32 v3, v58, v147
	v_fmac_f32_e32 v4, v58, v148
	v_fmac_f32_e32 v5, v58, v149
	v_fmac_f32_e32 v6, v58, v150
	v_fmac_f32_e32 v7, v58, v151
	v_fmac_f32_e32 v8, v58, v152
	v_fmac_f32_e32 v9, v58, v153
	v_fmac_f32_e32 v10, v58, v154
	v_fmac_f32_e32 v11, v58, v155
	v_fmac_f32_e32 v12, v58, v156
	v_fmac_f32_e32 v13, v58, v157
	v_fmac_f32_e32 v14, v58, v158
	v_fmac_f32_e32 v15, v58, v159
	v_lshl_add_u32 v161, v42, 7, v160
	global_load_dwordx4 v[120:123], v161, s[14:15]
	s_waitcnt vmcnt(15)
	v_cvt_pk_f32_fp8_e32 v[144:145], v124
	v_cvt_pk_f32_fp8_sdwa v[146:147], v124 src0_sel:WORD_1
	v_cvt_pk_f32_fp8_e32 v[148:149], v125
	v_cvt_pk_f32_fp8_sdwa v[150:151], v125 src0_sel:WORD_1
	v_cvt_pk_f32_fp8_e32 v[152:153], v126
	v_cvt_pk_f32_fp8_sdwa v[154:155], v126 src0_sel:WORD_1
	v_cvt_pk_f32_fp8_e32 v[156:157], v127
	v_cvt_pk_f32_fp8_sdwa v[158:159], v127 src0_sel:WORD_1
	v_fmac_f32_e32 v0, v59, v144
	v_fmac_f32_e32 v1, v59, v145
	v_fmac_f32_e32 v2, v59, v146
	v_fmac_f32_e32 v3, v59, v147
	v_fmac_f32_e32 v4, v59, v148
	v_fmac_f32_e32 v5, v59, v149
	v_fmac_f32_e32 v6, v59, v150
	v_fmac_f32_e32 v7, v59, v151
	v_fmac_f32_e32 v8, v59, v152
	v_fmac_f32_e32 v9, v59, v153
	v_fmac_f32_e32 v10, v59, v154
	v_fmac_f32_e32 v11, v59, v155
	v_fmac_f32_e32 v12, v59, v156
	v_fmac_f32_e32 v13, v59, v157
	v_fmac_f32_e32 v14, v59, v158
	v_fmac_f32_e32 v15, v59, v159
	v_lshl_add_u32 v161, v43, 7, v160
	global_load_dwordx4 v[124:127], v161, s[14:15]
	s_waitcnt vmcnt(15)
	v_cvt_pk_f32_fp8_e32 v[144:145], v128
	v_cvt_pk_f32_fp8_sdwa v[146:147], v128 src0_sel:WORD_1
	v_cvt_pk_f32_fp8_e32 v[148:149], v129
	v_cvt_pk_f32_fp8_sdwa v[150:151], v129 src0_sel:WORD_1
	v_cvt_pk_f32_fp8_e32 v[152:153], v130
	v_cvt_pk_f32_fp8_sdwa v[154:155], v130 src0_sel:WORD_1
	v_cvt_pk_f32_fp8_e32 v[156:157], v131
	v_cvt_pk_f32_fp8_sdwa v[158:159], v131 src0_sel:WORD_1
	v_fmac_f32_e32 v0, v60, v144
	v_fmac_f32_e32 v1, v60, v145
	v_fmac_f32_e32 v2, v60, v146
	v_fmac_f32_e32 v3, v60, v147
	v_fmac_f32_e32 v4, v60, v148
	v_fmac_f32_e32 v5, v60, v149
	v_fmac_f32_e32 v6, v60, v150
	v_fmac_f32_e32 v7, v60, v151
	v_fmac_f32_e32 v8, v60, v152
	v_fmac_f32_e32 v9, v60, v153
	v_fmac_f32_e32 v10, v60, v154
	v_fmac_f32_e32 v11, v60, v155
	v_fmac_f32_e32 v12, v60, v156
	v_fmac_f32_e32 v13, v60, v157
	v_fmac_f32_e32 v14, v60, v158
	v_fmac_f32_e32 v15, v60, v159
	v_lshl_add_u32 v161, v44, 7, v160
	global_load_dwordx4 v[128:131], v161, s[14:15]
	s_waitcnt vmcnt(15)
	v_cvt_pk_f32_fp8_e32 v[144:145], v132
	v_cvt_pk_f32_fp8_sdwa v[146:147], v132 src0_sel:WORD_1
	v_cvt_pk_f32_fp8_e32 v[148:149], v133
	v_cvt_pk_f32_fp8_sdwa v[150:151], v133 src0_sel:WORD_1
	v_cvt_pk_f32_fp8_e32 v[152:153], v134
	v_cvt_pk_f32_fp8_sdwa v[154:155], v134 src0_sel:WORD_1
	v_cvt_pk_f32_fp8_e32 v[156:157], v135
	v_cvt_pk_f32_fp8_sdwa v[158:159], v135 src0_sel:WORD_1
	v_fmac_f32_e32 v0, v61, v144
	v_fmac_f32_e32 v1, v61, v145
	v_fmac_f32_e32 v2, v61, v146
	v_fmac_f32_e32 v3, v61, v147
	v_fmac_f32_e32 v4, v61, v148
	v_fmac_f32_e32 v5, v61, v149
	v_fmac_f32_e32 v6, v61, v150
	v_fmac_f32_e32 v7, v61, v151
	v_fmac_f32_e32 v8, v61, v152
	v_fmac_f32_e32 v9, v61, v153
	v_fmac_f32_e32 v10, v61, v154
	v_fmac_f32_e32 v11, v61, v155
	v_fmac_f32_e32 v12, v61, v156
	v_fmac_f32_e32 v13, v61, v157
	v_fmac_f32_e32 v14, v61, v158
	v_fmac_f32_e32 v15, v61, v159
	v_lshl_add_u32 v161, v45, 7, v160
	global_load_dwordx4 v[132:135], v161, s[14:15]
	s_waitcnt vmcnt(15)
; DI void phase_peer_b(const Params& p, int layer, const float* gnext, bool last) {
;     ...
; #pragma unroll
;       for (int j = 0; j < 16; ++j) {
;         const int e = bt * 16 + j;
;         const float wj = __int_as_float(__builtin_amdgcn_readlane(__float_as_int(e < 64 ? w0 : w1), e & 63));
; #pragma unroll
;         for (int w = 0; w < 4; ++w) {
;           const f32x2 lo = __builtin_amdgcn_cvt_pk_f32_fp8((int)vr[j][w], false);
;           const f32x2 hi = __builtin_amdgcn_cvt_pk_f32_fp8((int)vr[j][w], true);
;           acc[4 * w] += wj * lo[0]; acc[4 * w + 1] += wj * lo[1]; acc[4 * w + 2] += wj * hi[0]; acc[4 * w + 3] += wj * hi[1];
;         }
;       }
	v_cvt_pk_f32_fp8_e32 v[144:145], v136
	v_cvt_pk_f32_fp8_sdwa v[146:147], v136 src0_sel:WORD_1
	v_cvt_pk_f32_fp8_e32 v[148:149], v137
	v_cvt_pk_f32_fp8_sdwa v[150:151], v137 src0_sel:WORD_1
	v_cvt_pk_f32_fp8_e32 v[152:153], v138
	v_cvt_pk_f32_fp8_sdwa v[154:155], v138 src0_sel:WORD_1
	v_cvt_pk_f32_fp8_e32 v[156:157], v139
	v_cvt_pk_f32_fp8_sdwa v[158:159], v139 src0_sel:WORD_1
	v_fmac_f32_e32 v0, v62, v144
	v_fmac_f32_e32 v1, v62, v145
	v_fmac_f32_e32 v2, v62, v146
	v_fmac_f32_e32 v3, v62, v147
	v_fmac_f32_e32 v4, v62, v148
	v_fmac_f32_e32 v5, v62, v149
	v_fmac_f32_e32 v6, v62, v150
	v_fmac_f32_e32 v7, v62, v151
	v_fmac_f32_e32 v8, v62, v152
	v_fmac_f32_e32 v9, v62, v153
	v_fmac_f32_e32 v10, v62, v154
	v_fmac_f32_e32 v11, v62, v155
	v_fmac_f32_e32 v12, v62, v156
	v_fmac_f32_e32 v13, v62, v157
	v_fmac_f32_e32 v14, v62, v158
	v_fmac_f32_e32 v15, v62, v159
	v_lshl_add_u32 v161, v46, 7, v160
	global_load_dwordx4 v[136:139], v161, s[14:15]
	s_waitcnt vmcnt(15)
	v_cvt_pk_f32_fp8_e32 v[144:145], v140
	v_cvt_pk_f32_fp8_sdwa v[146:147], v140 src0_sel:WORD_1
	v_cvt_pk_f32_fp8_e32 v[148:149], v141
	v_cvt_pk_f32_fp8_sdwa v[150:151], v141 src0_sel:WORD_1
	v_cvt_pk_f32_fp8_e32 v[152:153], v142
	v_cvt_pk_f32_fp8_sdwa v[154:155], v142 src0_sel:WORD_1
	v_cvt_pk_f32_fp8_e32 v[156:157], v143
	v_cvt_pk_f32_fp8_sdwa v[158:159], v143 src0_sel:WORD_1
	v_fmac_f32_e32 v0, v63, v144
	v_fmac_f32_e32 v1, v63, v145
	v_fmac_f32_e32 v2, v63, v146
	v_fmac_f32_e32 v3, v63, v147
	v_fmac_f32_e32 v4, v63, v148
	v_fmac_f32_e32 v5, v63, v149
	v_fmac_f32_e32 v6, v63, v150
	v_fmac_f32_e32 v7, v63, v151
	v_fmac_f32_e32 v8, v63, v152
	v_fmac_f32_e32 v9, v63, v153
	v_fmac_f32_e32 v10, v63, v154
	v_fmac_f32_e32 v11, v63, v155
	v_fmac_f32_e32 v12, v63, v156
	v_fmac_f32_e32 v13, v63, v157
	v_fmac_f32_e32 v14, v63, v158
	v_fmac_f32_e32 v15, v63, v159
	v_lshl_add_u32 v161, v47, 7, v160
	global_load_dwordx4 v[140:143], v161, s[14:15]
	s_waitcnt lgkmcnt(0)
	ds_read_b128 v[32:35], v163 offset:320
	ds_read_b128 v[36:39], v163 offset:336
	ds_read_b128 v[40:43], v163 offset:352
	ds_read_b128 v[44:47], v163 offset:368
	ds_read_b128 v[48:51], v163 offset:768
	ds_read_b128 v[52:55], v163 offset:784
	ds_read_b128 v[56:59], v163 offset:800
	ds_read_b128 v[60:63], v163 offset:816
	s_waitcnt vmcnt(15)
	v_cvt_pk_f32_fp8_e32 v[144:145], v80
	v_cvt_pk_f32_fp8_sdwa v[146:147], v80 src0_sel:WORD_1
	v_cvt_pk_f32_fp8_e32 v[148:149], v81
	v_cvt_pk_f32_fp8_sdwa v[150:151], v81 src0_sel:WORD_1
	v_cvt_pk_f32_fp8_e32 v[152:153], v82
	v_cvt_pk_f32_fp8_sdwa v[154:155], v82 src0_sel:WORD_1
	v_cvt_pk_f32_fp8_e32 v[156:157], v83
	v_cvt_pk_f32_fp8_sdwa v[158:159], v83 src0_sel:WORD_1
	v_fmac_f32_e32 v0, v64, v144
	v_fmac_f32_e32 v1, v64, v145
	v_fmac_f32_e32 v2, v64, v146
	v_fmac_f32_e32 v3, v64, v147
	v_fmac_f32_e32 v4, v64, v148
	v_fmac_f32_e32 v5, v64, v149
	v_fmac_f32_e32 v6, v64, v150
	v_fmac_f32_e32 v7, v64, v151
	v_fmac_f32_e32 v8, v64, v152
	v_fmac_f32_e32 v9, v64, v153
	v_fmac_f32_e32 v10, v64, v154
	v_fmac_f32_e32 v11, v64, v155
	v_fmac_f32_e32 v12, v64, v156
	v_fmac_f32_e32 v13, v64, v157
	v_fmac_f32_e32 v14, v64, v158
	v_fmac_f32_e32 v15, v64, v159
	v_lshl_add_u32 v161, v16, 7, v160
	global_load_dwordx4 v[80:83], v161, s[14:15]
	s_waitcnt vmcnt(15)
	v_cvt_pk_f32_fp8_e32 v[144:145], v84
	v_cvt_pk_f32_fp8_sdwa v[146:147], v84 src0_sel:WORD_1
	v_cvt_pk_f32_fp8_e32 v[148:149], v85
	v_cvt_pk_f32_fp8_sdwa v[150:151], v85 src0_sel:WORD_1
	v_cvt_pk_f32_fp8_e32 v[152:153], v86
	v_cvt_pk_f32_fp8_sdwa v[154:155], v86 src0_sel:WORD_1
	v_cvt_pk_f32_fp8_e32 v[156:157], v87
	v_cvt_pk_f32_fp8_sdwa v[158:159], v87 src0_sel:WORD_1
	v_fmac_f32_e32 v0, v65, v144
	v_fmac_f32_e32 v1, v65, v145
	v_fmac_f32_e32 v2, v65, v146
	v_fmac_f32_e32 v3, v65, v147
	v_fmac_f32_e32 v4, v65, v148
	v_fmac_f32_e32 v5, v65, v149
	v_fmac_f32_e32 v6, v65, v150
	v_fmac_f32_e32 v7, v65, v151
	v_fmac_f32_e32 v8, v65, v152
	v_fmac_f32_e32 v9, v65, v153
	v_fmac_f32_e32 v10, v65, v154
	v_fmac_f32_e32 v11, v65, v155
	v_fmac_f32_e32 v12, v65, v156
	v_fmac_f32_e32 v13, v65, v157
	v_fmac_f32_e32 v14, v65, v158
	v_fmac_f32_e32 v15, v65, v159
	v_lshl_add_u32 v161, v17, 7, v160
	global_load_dwordx4 v[84:87], v161, s[14:15]
	s_waitcnt vmcnt(15)
	v_cvt_pk_f32_fp8_e32 v[144:145], v88
	v_cvt_pk_f32_fp8_sdwa v[146:147], v88 src0_sel:WORD_1
	v_cvt_pk_f32_fp8_e32 v[148:149], v89
	v_cvt_pk_f32_fp8_sdwa v[150:151], v89 src0_sel:WORD_1
	v_cvt_pk_f32_fp8_e32 v[152:153], v90
	v_cvt_pk_f32_fp8_sdwa v[154:155], v90 src0_sel:WORD_1
	v_cvt_pk_f32_fp8_e32 v[156:157], v91
	v_cvt_pk_f32_fp8_sdwa v[158:159], v91 src0_sel:WORD_1
	v_fmac_f32_e32 v0, v66, v144
	v_fmac_f32_e32 v1, v66, v145
	v_fmac_f32_e32 v2, v66, v146
	v_fmac_f32_e32 v3, v66, v147
	v_fmac_f32_e32 v4, v66, v148
	v_fmac_f32_e32 v5, v66, v149
	v_fmac_f32_e32 v6, v66, v150
	v_fmac_f32_e32 v7, v66, v151
	v_fmac_f32_e32 v8, v66, v152
	v_fmac_f32_e32 v9, v66, v153
	v_fmac_f32_e32 v10, v66, v154
	v_fmac_f32_e32 v11, v66, v155
	v_fmac_f32_e32 v12, v66, v156
	v_fmac_f32_e32 v13, v66, v157
	v_fmac_f32_e32 v14, v66, v158
	v_fmac_f32_e32 v15, v66, v159
	v_lshl_add_u32 v161, v18, 7, v160
	global_load_dwordx4 v[88:91], v161, s[14:15]
	s_waitcnt vmcnt(15)
; DI void phase_peer_b(const Params& p, int layer, const float* gnext, bool last) {
;     ...
; #pragma unroll
;       for (int j = 0; j < 16; ++j) {
;         const int e = bt * 16 + j;
;         const float wj = __int_as_float(__builtin_amdgcn_readlane(__float_as_int(e < 64 ? w0 : w1), e & 63));
; #pragma unroll
;         for (int w = 0; w < 4; ++w) {
;           const f32x2 lo = __builtin_amdgcn_cvt_pk_f32_fp8((int)vr[j][w], false);
;           const f32x2 hi = __builtin_amdgcn_cvt_pk_f32_fp8((int)vr[j][w], true);
;           acc[4 * w] += wj * lo[0]; acc[4 * w + 1] += wj * lo[1]; acc[4 * w + 2] += wj * hi[0]; acc[4 * w + 3] += wj * hi[1];
;         }
;       }
	v_cvt_pk_f32_fp8_e32 v[144:145], v92
	v_cvt_pk_f32_fp8_sdwa v[146:147], v92 src0_sel:WORD_1
	v_cvt_pk_f32_fp8_e32 v[148:149], v93
	v_cvt_pk_f32_fp8_sdwa v[150:151], v93 src0_sel:WORD_1
	v_cvt_pk_f32_fp8_e32 v[152:153], v94
	v_cvt_pk_f32_fp8_sdwa v[154:155], v94 src0_sel:WORD_1
	v_cvt_pk_f32_fp8_e32 v[156:157], v95
	v_cvt_pk_f32_fp8_sdwa v[158:159], v95 src0_sel:WORD_1
	v_fmac_f32_e32 v0, v67, v144
	v_fmac_f32_e32 v1, v67, v145
	v_fmac_f32_e32 v2, v67, v146
	v_fmac_f32_e32 v3, v67, v147
	v_fmac_f32_e32 v4, v67, v148
	v_fmac_f32_e32 v5, v67, v149
	v_fmac_f32_e32 v6, v67, v150
	v_fmac_f32_e32 v7, v67, v151
	v_fmac_f32_e32 v8, v67, v152
	v_fmac_f32_e32 v9, v67, v153
	v_fmac_f32_e32 v10, v67, v154
	v_fmac_f32_e32 v11, v67, v155
	v_fmac_f32_e32 v12, v67, v156
	v_fmac_f32_e32 v13, v67, v157
	v_fmac_f32_e32 v14, v67, v158
	v_fmac_f32_e32 v15, v67, v159
	v_lshl_add_u32 v161, v19, 7, v160
	global_load_dwordx4 v[92:95], v161, s[14:15]
	s_waitcnt vmcnt(15)
	v_cvt_pk_f32_fp8_e32 v[144:145], v96
	v_cvt_pk_f32_fp8_sdwa v[146:147], v96 src0_sel:WORD_1
	v_cvt_pk_f32_fp8_e32 v[148:149], v97
	v_cvt_pk_f32_fp8_sdwa v[150:151], v97 src0_sel:WORD_1
	v_cvt_pk_f32_fp8_e32 v[152:153], v98
	v_cvt_pk_f32_fp8_sdwa v[154:155], v98 src0_sel:WORD_1
	v_cvt_pk_f32_fp8_e32 v[156:157], v99
	v_cvt_pk_f32_fp8_sdwa v[158:159], v99 src0_sel:WORD_1
	v_fmac_f32_e32 v0, v68, v144
	v_fmac_f32_e32 v1, v68, v145
	v_fmac_f32_e32 v2, v68, v146
	v_fmac_f32_e32 v3, v68, v147
	v_fmac_f32_e32 v4, v68, v148
	v_fmac_f32_e32 v5, v68, v149
	v_fmac_f32_e32 v6, v68, v150
	v_fmac_f32_e32 v7, v68, v151
	v_fmac_f32_e32 v8, v68, v152
	v_fmac_f32_e32 v9, v68, v153
	v_fmac_f32_e32 v10, v68, v154
	v_fmac_f32_e32 v11, v68, v155
	v_fmac_f32_e32 v12, v68, v156
	v_fmac_f32_e32 v13, v68, v157
	v_fmac_f32_e32 v14, v68, v158
	v_fmac_f32_e32 v15, v68, v159
	v_lshl_add_u32 v161, v20, 7, v160
	global_load_dwordx4 v[96:99], v161, s[14:15]
	s_waitcnt vmcnt(15)
	v_cvt_pk_f32_fp8_e32 v[144:145], v100
	v_cvt_pk_f32_fp8_sdwa v[146:147], v100 src0_sel:WORD_1
	v_cvt_pk_f32_fp8_e32 v[148:149], v101
	v_cvt_pk_f32_fp8_sdwa v[150:151], v101 src0_sel:WORD_1
	v_cvt_pk_f32_fp8_e32 v[152:153], v102
	v_cvt_pk_f32_fp8_sdwa v[154:155], v102 src0_sel:WORD_1
	v_cvt_pk_f32_fp8_e32 v[156:157], v103
	v_cvt_pk_f32_fp8_sdwa v[158:159], v103 src0_sel:WORD_1
	v_fmac_f32_e32 v0, v69, v144
	v_fmac_f32_e32 v1, v69, v145
	v_fmac_f32_e32 v2, v69, v146
	v_fmac_f32_e32 v3, v69, v147
	v_fmac_f32_e32 v4, v69, v148
	v_fmac_f32_e32 v5, v69, v149
	v_fmac_f32_e32 v6, v69, v150
	v_fmac_f32_e32 v7, v69, v151
	v_fmac_f32_e32 v8, v69, v152
	v_fmac_f32_e32 v9, v69, v153
	v_fmac_f32_e32 v10, v69, v154
	v_fmac_f32_e32 v11, v69, v155
	v_fmac_f32_e32 v12, v69, v156
	v_fmac_f32_e32 v13, v69, v157
	v_fmac_f32_e32 v14, v69, v158
	v_fmac_f32_e32 v15, v69, v159
	v_lshl_add_u32 v161, v21, 7, v160
	global_load_dwordx4 v[100:103], v161, s[14:15]
	s_waitcnt vmcnt(15)
	v_cvt_pk_f32_fp8_e32 v[144:145], v104
	v_cvt_pk_f32_fp8_sdwa v[146:147], v104 src0_sel:WORD_1
	v_cvt_pk_f32_fp8_e32 v[148:149], v105
	v_cvt_pk_f32_fp8_sdwa v[150:151], v105 src0_sel:WORD_1
	v_cvt_pk_f32_fp8_e32 v[152:153], v106
	v_cvt_pk_f32_fp8_sdwa v[154:155], v106 src0_sel:WORD_1
	v_cvt_pk_f32_fp8_e32 v[156:157], v107
	v_cvt_pk_f32_fp8_sdwa v[158:159], v107 src0_sel:WORD_1
	v_fmac_f32_e32 v0, v70, v144
	v_fmac_f32_e32 v1, v70, v145
	v_fmac_f32_e32 v2, v70, v146
	v_fmac_f32_e32 v3, v70, v147
	v_fmac_f32_e32 v4, v70, v148
	v_fmac_f32_e32 v5, v70, v149
	v_fmac_f32_e32 v6, v70, v150
	v_fmac_f32_e32 v7, v70, v151
	v_fmac_f32_e32 v8, v70, v152
	v_fmac_f32_e32 v9, v70, v153
	v_fmac_f32_e32 v10, v70, v154
	v_fmac_f32_e32 v11, v70, v155
	v_fmac_f32_e32 v12, v70, v156
	v_fmac_f32_e32 v13, v70, v157
	v_fmac_f32_e32 v14, v70, v158
	v_fmac_f32_e32 v15, v70, v159
	v_lshl_add_u32 v161, v22, 7, v160
	global_load_dwordx4 v[104:107], v161, s[14:15]
	s_waitcnt vmcnt(15)
	v_cvt_pk_f32_fp8_e32 v[144:145], v108
	v_cvt_pk_f32_fp8_sdwa v[146:147], v108 src0_sel:WORD_1
	v_cvt_pk_f32_fp8_e32 v[148:149], v109
	v_cvt_pk_f32_fp8_sdwa v[150:151], v109 src0_sel:WORD_1
	v_cvt_pk_f32_fp8_e32 v[152:153], v110
	v_cvt_pk_f32_fp8_sdwa v[154:155], v110 src0_sel:WORD_1
	v_cvt_pk_f32_fp8_e32 v[156:157], v111
	v_cvt_pk_f32_fp8_sdwa v[158:159], v111 src0_sel:WORD_1
	v_fmac_f32_e32 v0, v71, v144
	v_fmac_f32_e32 v1, v71, v145
	v_fmac_f32_e32 v2, v71, v146
	v_fmac_f32_e32 v3, v71, v147
	v_fmac_f32_e32 v4, v71, v148
	v_fmac_f32_e32 v5, v71, v149
	v_fmac_f32_e32 v6, v71, v150
	v_fmac_f32_e32 v7, v71, v151
	v_fmac_f32_e32 v8, v71, v152
	v_fmac_f32_e32 v9, v71, v153
	v_fmac_f32_e32 v10, v71, v154
	v_fmac_f32_e32 v11, v71, v155
	v_fmac_f32_e32 v12, v71, v156
	v_fmac_f32_e32 v13, v71, v157
	v_fmac_f32_e32 v14, v71, v158
	v_fmac_f32_e32 v15, v71, v159
	v_lshl_add_u32 v161, v23, 7, v160
	global_load_dwordx4 v[108:111], v161, s[14:15]
	s_waitcnt vmcnt(15)
	v_cvt_pk_f32_fp8_e32 v[144:145], v112
	v_cvt_pk_f32_fp8_sdwa v[146:147], v112 src0_sel:WORD_1
	v_cvt_pk_f32_fp8_e32 v[148:149], v113
	v_cvt_pk_f32_fp8_sdwa v[150:151], v113 src0_sel:WORD_1
	v_cvt_pk_f32_fp8_e32 v[152:153], v114
	v_cvt_pk_f32_fp8_sdwa v[154:155], v114 src0_sel:WORD_1
	v_cvt_pk_f32_fp8_e32 v[156:157], v115
	v_cvt_pk_f32_fp8_sdwa v[158:159], v115 src0_sel:WORD_1
	v_fmac_f32_e32 v0, v72, v144
	v_fmac_f32_e32 v1, v72, v145
	v_fmac_f32_e32 v2, v72, v146
	v_fmac_f32_e32 v3, v72, v147
	v_fmac_f32_e32 v4, v72, v148
	v_fmac_f32_e32 v5, v72, v149
	v_fmac_f32_e32 v6, v72, v150
	v_fmac_f32_e32 v7, v72, v151
	v_fmac_f32_e32 v8, v72, v152
	v_fmac_f32_e32 v9, v72, v153
	v_fmac_f32_e32 v10, v72, v154
	v_fmac_f32_e32 v11, v72, v155
	v_fmac_f32_e32 v12, v72, v156
	v_fmac_f32_e32 v13, v72, v157
	v_fmac_f32_e32 v14, v72, v158
	v_fmac_f32_e32 v15, v72, v159
	v_lshl_add_u32 v161, v24, 7, v160
	global_load_dwordx4 v[112:115], v161, s[14:15]
	s_waitcnt vmcnt(15)
; DI void phase_peer_b(const Params& p, int layer, const float* gnext, bool last) {
;     ...
; #pragma unroll
;       for (int j = 0; j < 16; ++j) {
;         const int e = bt * 16 + j;
;         const float wj = __int_as_float(__builtin_amdgcn_readlane(__float_as_int(e < 64 ? w0 : w1), e & 63));
; #pragma unroll
;         for (int w = 0; w < 4; ++w) {
;           const f32x2 lo = __builtin_amdgcn_cvt_pk_f32_fp8((int)vr[j][w], false);
;           const f32x2 hi = __builtin_amdgcn_cvt_pk_f32_fp8((int)vr[j][w], true);
;           acc[4 * w] += wj * lo[0]; acc[4 * w + 1] += wj * lo[1]; acc[4 * w + 2] += wj * hi[0]; acc[4 * w + 3] += wj * hi[1];
;         }
;       }
	v_cvt_pk_f32_fp8_e32 v[144:145], v116
	v_cvt_pk_f32_fp8_sdwa v[146:147], v116 src0_sel:WORD_1
	v_cvt_pk_f32_fp8_e32 v[148:149], v117
	v_cvt_pk_f32_fp8_sdwa v[150:151], v117 src0_sel:WORD_1
	v_cvt_pk_f32_fp8_e32 v[152:153], v118
	v_cvt_pk_f32_fp8_sdwa v[154:155], v118 src0_sel:WORD_1
	v_cvt_pk_f32_fp8_e32 v[156:157], v119
	v_cvt_pk_f32_fp8_sdwa v[158:159], v119 src0_sel:WORD_1
	v_fmac_f32_e32 v0, v73, v144
	v_fmac_f32_e32 v1, v73, v145
	v_fmac_f32_e32 v2, v73, v146
	v_fmac_f32_e32 v3, v73, v147
	v_fmac_f32_e32 v4, v73, v148
	v_fmac_f32_e32 v5, v73, v149
	v_fmac_f32_e32 v6, v73, v150
	v_fmac_f32_e32 v7, v73, v151
	v_fmac_f32_e32 v8, v73, v152
	v_fmac_f32_e32 v9, v73, v153
	v_fmac_f32_e32 v10, v73, v154
	v_fmac_f32_e32 v11, v73, v155
	v_fmac_f32_e32 v12, v73, v156
	v_fmac_f32_e32 v13, v73, v157
	v_fmac_f32_e32 v14, v73, v158
	v_fmac_f32_e32 v15, v73, v159
	v_lshl_add_u32 v161, v25, 7, v160
	global_load_dwordx4 v[116:119], v161, s[14:15]
	s_waitcnt vmcnt(15)
	v_cvt_pk_f32_fp8_e32 v[144:145], v120
	v_cvt_pk_f32_fp8_sdwa v[146:147], v120 src0_sel:WORD_1
	v_cvt_pk_f32_fp8_e32 v[148:149], v121
	v_cvt_pk_f32_fp8_sdwa v[150:151], v121 src0_sel:WORD_1
	v_cvt_pk_f32_fp8_e32 v[152:153], v122
	v_cvt_pk_f32_fp8_sdwa v[154:155], v122 src0_sel:WORD_1
	v_cvt_pk_f32_fp8_e32 v[156:157], v123
	v_cvt_pk_f32_fp8_sdwa v[158:159], v123 src0_sel:WORD_1
	v_fmac_f32_e32 v0, v74, v144
	v_fmac_f32_e32 v1, v74, v145
	v_fmac_f32_e32 v2, v74, v146
	v_fmac_f32_e32 v3, v74, v147
	v_fmac_f32_e32 v4, v74, v148
	v_fmac_f32_e32 v5, v74, v149
	v_fmac_f32_e32 v6, v74, v150
	v_fmac_f32_e32 v7, v74, v151
	v_fmac_f32_e32 v8, v74, v152
	v_fmac_f32_e32 v9, v74, v153
	v_fmac_f32_e32 v10, v74, v154
	v_fmac_f32_e32 v11, v74, v155
	v_fmac_f32_e32 v12, v74, v156
	v_fmac_f32_e32 v13, v74, v157
	v_fmac_f32_e32 v14, v74, v158
	v_fmac_f32_e32 v15, v74, v159
	v_lshl_add_u32 v161, v26, 7, v160
	global_load_dwordx4 v[120:123], v161, s[14:15]
	s_waitcnt vmcnt(15)
	v_cvt_pk_f32_fp8_e32 v[144:145], v124
	v_cvt_pk_f32_fp8_sdwa v[146:147], v124 src0_sel:WORD_1
	v_cvt_pk_f32_fp8_e32 v[148:149], v125
	v_cvt_pk_f32_fp8_sdwa v[150:151], v125 src0_sel:WORD_1
	v_cvt_pk_f32_fp8_e32 v[152:153], v126
	v_cvt_pk_f32_fp8_sdwa v[154:155], v126 src0_sel:WORD_1
	v_cvt_pk_f32_fp8_e32 v[156:157], v127
	v_cvt_pk_f32_fp8_sdwa v[158:159], v127 src0_sel:WORD_1
	v_fmac_f32_e32 v0, v75, v144
	v_fmac_f32_e32 v1, v75, v145
	v_fmac_f32_e32 v2, v75, v146
	v_fmac_f32_e32 v3, v75, v147
	v_fmac_f32_e32 v4, v75, v148
	v_fmac_f32_e32 v5, v75, v149
	v_fmac_f32_e32 v6, v75, v150
	v_fmac_f32_e32 v7, v75, v151
	v_fmac_f32_e32 v8, v75, v152
	v_fmac_f32_e32 v9, v75, v153
	v_fmac_f32_e32 v10, v75, v154
	v_fmac_f32_e32 v11, v75, v155
	v_fmac_f32_e32 v12, v75, v156
	v_fmac_f32_e32 v13, v75, v157
	v_fmac_f32_e32 v14, v75, v158
	v_fmac_f32_e32 v15, v75, v159
	v_lshl_add_u32 v161, v27, 7, v160
	global_load_dwordx4 v[124:127], v161, s[14:15]
	s_waitcnt vmcnt(15)
	v_cvt_pk_f32_fp8_e32 v[144:145], v128
	v_cvt_pk_f32_fp8_sdwa v[146:147], v128 src0_sel:WORD_1
	v_cvt_pk_f32_fp8_e32 v[148:149], v129
	v_cvt_pk_f32_fp8_sdwa v[150:151], v129 src0_sel:WORD_1
	v_cvt_pk_f32_fp8_e32 v[152:153], v130
	v_cvt_pk_f32_fp8_sdwa v[154:155], v130 src0_sel:WORD_1
	v_cvt_pk_f32_fp8_e32 v[156:157], v131
	v_cvt_pk_f32_fp8_sdwa v[158:159], v131 src0_sel:WORD_1
	v_fmac_f32_e32 v0, v76, v144
	v_fmac_f32_e32 v1, v76, v145
	v_fmac_f32_e32 v2, v76, v146
	v_fmac_f32_e32 v3, v76, v147
	v_fmac_f32_e32 v4, v76, v148
	v_fmac_f32_e32 v5, v76, v149
	v_fmac_f32_e32 v6, v76, v150
	v_fmac_f32_e32 v7, v76, v151
	v_fmac_f32_e32 v8, v76, v152
	v_fmac_f32_e32 v9, v76, v153
	v_fmac_f32_e32 v10, v76, v154
	v_fmac_f32_e32 v11, v76, v155
	v_fmac_f32_e32 v12, v76, v156
	v_fmac_f32_e32 v13, v76, v157
	v_fmac_f32_e32 v14, v76, v158
	v_fmac_f32_e32 v15, v76, v159
	v_lshl_add_u32 v161, v28, 7, v160
	global_load_dwordx4 v[128:131], v161, s[14:15]
	s_waitcnt vmcnt(15)
	v_cvt_pk_f32_fp8_e32 v[144:145], v132
	v_cvt_pk_f32_fp8_sdwa v[146:147], v132 src0_sel:WORD_1
	v_cvt_pk_f32_fp8_e32 v[148:149], v133
	v_cvt_pk_f32_fp8_sdwa v[150:151], v133 src0_sel:WORD_1
	v_cvt_pk_f32_fp8_e32 v[152:153], v134
	v_cvt_pk_f32_fp8_sdwa v[154:155], v134 src0_sel:WORD_1
	v_cvt_pk_f32_fp8_e32 v[156:157], v135
	v_cvt_pk_f32_fp8_sdwa v[158:159], v135 src0_sel:WORD_1
	v_fmac_f32_e32 v0, v77, v144
	v_fmac_f32_e32 v1, v77, v145
	v_fmac_f32_e32 v2, v77, v146
	v_fmac_f32_e32 v3, v77, v147
	v_fmac_f32_e32 v4, v77, v148
	v_fmac_f32_e32 v5, v77, v149
	v_fmac_f32_e32 v6, v77, v150
	v_fmac_f32_e32 v7, v77, v151
	v_fmac_f32_e32 v8, v77, v152
	v_fmac_f32_e32 v9, v77, v153
	v_fmac_f32_e32 v10, v77, v154
	v_fmac_f32_e32 v11, v77, v155
	v_fmac_f32_e32 v12, v77, v156
	v_fmac_f32_e32 v13, v77, v157
	v_fmac_f32_e32 v14, v77, v158
	v_fmac_f32_e32 v15, v77, v159
	v_lshl_add_u32 v161, v29, 7, v160
	global_load_dwordx4 v[132:135], v161, s[14:15]
	s_waitcnt vmcnt(15)
	v_cvt_pk_f32_fp8_e32 v[144:145], v136
	v_cvt_pk_f32_fp8_sdwa v[146:147], v136 src0_sel:WORD_1
	v_cvt_pk_f32_fp8_e32 v[148:149], v137
	v_cvt_pk_f32_fp8_sdwa v[150:151], v137 src0_sel:WORD_1
	v_cvt_pk_f32_fp8_e32 v[152:153], v138
	v_cvt_pk_f32_fp8_sdwa v[154:155], v138 src0_sel:WORD_1
	v_cvt_pk_f32_fp8_e32 v[156:157], v139
	v_cvt_pk_f32_fp8_sdwa v[158:159], v139 src0_sel:WORD_1
	v_fmac_f32_e32 v0, v78, v144
	v_fmac_f32_e32 v1, v78, v145
	v_fmac_f32_e32 v2, v78, v146
	v_fmac_f32_e32 v3, v78, v147
	v_fmac_f32_e32 v4, v78, v148
	v_fmac_f32_e32 v5, v78, v149
	v_fmac_f32_e32 v6, v78, v150
	v_fmac_f32_e32 v7, v78, v151
	v_fmac_f32_e32 v8, v78, v152
	v_fmac_f32_e32 v9, v78, v153
	v_fmac_f32_e32 v10, v78, v154
	v_fmac_f32_e32 v11, v78, v155
	v_fmac_f32_e32 v12, v78, v156
	v_fmac_f32_e32 v13, v78, v157
	v_fmac_f32_e32 v14, v78, v158
	v_fmac_f32_e32 v15, v78, v159
	v_lshl_add_u32 v161, v30, 7, v160
	global_load_dwordx4 v[136:139], v161, s[14:15]
	s_waitcnt vmcnt(15)
; DI void phase_peer_b(const Params& p, int layer, const float* gnext, bool last) {
;     ...
; #pragma unroll
;       for (int j = 0; j < 16; ++j) {
;         const int e = bt * 16 + j;
;         const float wj = __int_as_float(__builtin_amdgcn_readlane(__float_as_int(e < 64 ? w0 : w1), e & 63));
; #pragma unroll
;         for (int w = 0; w < 4; ++w) {
;           const f32x2 lo = __builtin_amdgcn_cvt_pk_f32_fp8((int)vr[j][w], false);
;           const f32x2 hi = __builtin_amdgcn_cvt_pk_f32_fp8((int)vr[j][w], true);
;           acc[4 * w] += wj * lo[0]; acc[4 * w + 1] += wj * lo[1]; acc[4 * w + 2] += wj * hi[0]; acc[4 * w + 3] += wj * hi[1];
;         }
;       }
	v_cvt_pk_f32_fp8_e32 v[144:145], v140
	v_cvt_pk_f32_fp8_sdwa v[146:147], v140 src0_sel:WORD_1
	v_cvt_pk_f32_fp8_e32 v[148:149], v141
	v_cvt_pk_f32_fp8_sdwa v[150:151], v141 src0_sel:WORD_1
	v_cvt_pk_f32_fp8_e32 v[152:153], v142
	v_cvt_pk_f32_fp8_sdwa v[154:155], v142 src0_sel:WORD_1
	v_cvt_pk_f32_fp8_e32 v[156:157], v143
	v_cvt_pk_f32_fp8_sdwa v[158:159], v143 src0_sel:WORD_1
	v_fmac_f32_e32 v0, v79, v144
	v_fmac_f32_e32 v1, v79, v145
	v_fmac_f32_e32 v2, v79, v146
	v_fmac_f32_e32 v3, v79, v147
	v_fmac_f32_e32 v4, v79, v148
	v_fmac_f32_e32 v5, v79, v149
	v_fmac_f32_e32 v6, v79, v150
	v_fmac_f32_e32 v7, v79, v151
	v_fmac_f32_e32 v8, v79, v152
	v_fmac_f32_e32 v9, v79, v153
	v_fmac_f32_e32 v10, v79, v154
	v_fmac_f32_e32 v11, v79, v155
	v_fmac_f32_e32 v12, v79, v156
	v_fmac_f32_e32 v13, v79, v157
	v_fmac_f32_e32 v14, v79, v158
	v_fmac_f32_e32 v15, v79, v159
	v_lshl_add_u32 v161, v31, 7, v160
	global_load_dwordx4 v[140:143], v161, s[14:15]
	s_waitcnt lgkmcnt(0)
	ds_read_b128 v[16:19], v163 offset:384
	ds_read_b128 v[20:23], v163 offset:400
	ds_read_b128 v[24:27], v163 offset:416
	ds_read_b128 v[28:31], v163 offset:432
	ds_read_b128 v[64:67], v163 offset:832
	ds_read_b128 v[68:71], v163 offset:848
	ds_read_b128 v[72:75], v163 offset:864
	ds_read_b128 v[76:79], v163 offset:880
	s_waitcnt vmcnt(15)
	v_cvt_pk_f32_fp8_e32 v[144:145], v80
	v_cvt_pk_f32_fp8_sdwa v[146:147], v80 src0_sel:WORD_1
	v_cvt_pk_f32_fp8_e32 v[148:149], v81
	v_cvt_pk_f32_fp8_sdwa v[150:151], v81 src0_sel:WORD_1
	v_cvt_pk_f32_fp8_e32 v[152:153], v82
	v_cvt_pk_f32_fp8_sdwa v[154:155], v82 src0_sel:WORD_1
	v_cvt_pk_f32_fp8_e32 v[156:157], v83
	v_cvt_pk_f32_fp8_sdwa v[158:159], v83 src0_sel:WORD_1
	v_fmac_f32_e32 v0, v48, v144
	v_fmac_f32_e32 v1, v48, v145
	v_fmac_f32_e32 v2, v48, v146
	v_fmac_f32_e32 v3, v48, v147
	v_fmac_f32_e32 v4, v48, v148
	v_fmac_f32_e32 v5, v48, v149
	v_fmac_f32_e32 v6, v48, v150
	v_fmac_f32_e32 v7, v48, v151
	v_fmac_f32_e32 v8, v48, v152
	v_fmac_f32_e32 v9, v48, v153
	v_fmac_f32_e32 v10, v48, v154
	v_fmac_f32_e32 v11, v48, v155
	v_fmac_f32_e32 v12, v48, v156
	v_fmac_f32_e32 v13, v48, v157
	v_fmac_f32_e32 v14, v48, v158
	v_fmac_f32_e32 v15, v48, v159
	v_lshl_add_u32 v161, v32, 7, v160
	global_load_dwordx4 v[80:83], v161, s[14:15]
	s_waitcnt vmcnt(15)
	v_cvt_pk_f32_fp8_e32 v[144:145], v84
	v_cvt_pk_f32_fp8_sdwa v[146:147], v84 src0_sel:WORD_1
	v_cvt_pk_f32_fp8_e32 v[148:149], v85
	v_cvt_pk_f32_fp8_sdwa v[150:151], v85 src0_sel:WORD_1
	v_cvt_pk_f32_fp8_e32 v[152:153], v86
	v_cvt_pk_f32_fp8_sdwa v[154:155], v86 src0_sel:WORD_1
	v_cvt_pk_f32_fp8_e32 v[156:157], v87
	v_cvt_pk_f32_fp8_sdwa v[158:159], v87 src0_sel:WORD_1
	v_fmac_f32_e32 v0, v49, v144
	v_fmac_f32_e32 v1, v49, v145
	v_fmac_f32_e32 v2, v49, v146
	v_fmac_f32_e32 v3, v49, v147
	v_fmac_f32_e32 v4, v49, v148
	v_fmac_f32_e32 v5, v49, v149
	v_fmac_f32_e32 v6, v49, v150
	v_fmac_f32_e32 v7, v49, v151
	v_fmac_f32_e32 v8, v49, v152
	v_fmac_f32_e32 v9, v49, v153
	v_fmac_f32_e32 v10, v49, v154
	v_fmac_f32_e32 v11, v49, v155
	v_fmac_f32_e32 v12, v49, v156
	v_fmac_f32_e32 v13, v49, v157
	v_fmac_f32_e32 v14, v49, v158
	v_fmac_f32_e32 v15, v49, v159
	v_lshl_add_u32 v161, v33, 7, v160
	global_load_dwordx4 v[84:87], v161, s[14:15]
	s_waitcnt vmcnt(15)
	v_cvt_pk_f32_fp8_e32 v[144:145], v88
	v_cvt_pk_f32_fp8_sdwa v[146:147], v88 src0_sel:WORD_1
	v_cvt_pk_f32_fp8_e32 v[148:149], v89
	v_cvt_pk_f32_fp8_sdwa v[150:151], v89 src0_sel:WORD_1
	v_cvt_pk_f32_fp8_e32 v[152:153], v90
	v_cvt_pk_f32_fp8_sdwa v[154:155], v90 src0_sel:WORD_1
	v_cvt_pk_f32_fp8_e32 v[156:157], v91
	v_cvt_pk_f32_fp8_sdwa v[158:159], v91 src0_sel:WORD_1
	v_fmac_f32_e32 v0, v50, v144
	v_fmac_f32_e32 v1, v50, v145
	v_fmac_f32_e32 v2, v50, v146
	v_fmac_f32_e32 v3, v50, v147
	v_fmac_f32_e32 v4, v50, v148
	v_fmac_f32_e32 v5, v50, v149
	v_fmac_f32_e32 v6, v50, v150
	v_fmac_f32_e32 v7, v50, v151
	v_fmac_f32_e32 v8, v50, v152
	v_fmac_f32_e32 v9, v50, v153
	v_fmac_f32_e32 v10, v50, v154
	v_fmac_f32_e32 v11, v50, v155
	v_fmac_f32_e32 v12, v50, v156
	v_fmac_f32_e32 v13, v50, v157
	v_fmac_f32_e32 v14, v50, v158
	v_fmac_f32_e32 v15, v50, v159
	v_lshl_add_u32 v161, v34, 7, v160
	global_load_dwordx4 v[88:91], v161, s[14:15]
	s_waitcnt vmcnt(15)
	v_cvt_pk_f32_fp8_e32 v[144:145], v92
	v_cvt_pk_f32_fp8_sdwa v[146:147], v92 src0_sel:WORD_1
	v_cvt_pk_f32_fp8_e32 v[148:149], v93
	v_cvt_pk_f32_fp8_sdwa v[150:151], v93 src0_sel:WORD_1
	v_cvt_pk_f32_fp8_e32 v[152:153], v94
	v_cvt_pk_f32_fp8_sdwa v[154:155], v94 src0_sel:WORD_1
	v_cvt_pk_f32_fp8_e32 v[156:157], v95
	v_cvt_pk_f32_fp8_sdwa v[158:159], v95 src0_sel:WORD_1
	v_fmac_f32_e32 v0, v51, v144
	v_fmac_f32_e32 v1, v51, v145
	v_fmac_f32_e32 v2, v51, v146
	v_fmac_f32_e32 v3, v51, v147
	v_fmac_f32_e32 v4, v51, v148
	v_fmac_f32_e32 v5, v51, v149
	v_fmac_f32_e32 v6, v51, v150
	v_fmac_f32_e32 v7, v51, v151
	v_fmac_f32_e32 v8, v51, v152
	v_fmac_f32_e32 v9, v51, v153
	v_fmac_f32_e32 v10, v51, v154
	v_fmac_f32_e32 v11, v51, v155
	v_fmac_f32_e32 v12, v51, v156
	v_fmac_f32_e32 v13, v51, v157
	v_fmac_f32_e32 v14, v51, v158
	v_fmac_f32_e32 v15, v51, v159
	v_lshl_add_u32 v161, v35, 7, v160
	global_load_dwordx4 v[92:95], v161, s[14:15]
	s_waitcnt vmcnt(15)
	v_cvt_pk_f32_fp8_e32 v[144:145], v96
	v_cvt_pk_f32_fp8_sdwa v[146:147], v96 src0_sel:WORD_1
	v_cvt_pk_f32_fp8_e32 v[148:149], v97
	v_cvt_pk_f32_fp8_sdwa v[150:151], v97 src0_sel:WORD_1
	v_cvt_pk_f32_fp8_e32 v[152:153], v98
	v_cvt_pk_f32_fp8_sdwa v[154:155], v98 src0_sel:WORD_1
	v_cvt_pk_f32_fp8_e32 v[156:157], v99
	v_cvt_pk_f32_fp8_sdwa v[158:159], v99 src0_sel:WORD_1
	v_fmac_f32_e32 v0, v52, v144
	v_fmac_f32_e32 v1, v52, v145
	v_fmac_f32_e32 v2, v52, v146
	v_fmac_f32_e32 v3, v52, v147
	v_fmac_f32_e32 v4, v52, v148
	v_fmac_f32_e32 v5, v52, v149
	v_fmac_f32_e32 v6, v52, v150
	v_fmac_f32_e32 v7, v52, v151
	v_fmac_f32_e32 v8, v52, v152
	v_fmac_f32_e32 v9, v52, v153
	v_fmac_f32_e32 v10, v52, v154
	v_fmac_f32_e32 v11, v52, v155
	v_fmac_f32_e32 v12, v52, v156
	v_fmac_f32_e32 v13, v52, v157
	v_fmac_f32_e32 v14, v52, v158
	v_fmac_f32_e32 v15, v52, v159
	v_lshl_add_u32 v161, v36, 7, v160
	global_load_dwordx4 v[96:99], v161, s[14:15]
	s_waitcnt vmcnt(15)
; DI void phase_peer_b(const Params& p, int layer, const float* gnext, bool last) {
;     ...
; #pragma unroll
;       for (int j = 0; j < 16; ++j) {
;         const int e = bt * 16 + j;
;         const float wj = __int_as_float(__builtin_amdgcn_readlane(__float_as_int(e < 64 ? w0 : w1), e & 63));
; #pragma unroll
;         for (int w = 0; w < 4; ++w) {
;           const f32x2 lo = __builtin_amdgcn_cvt_pk_f32_fp8((int)vr[j][w], false);
;           const f32x2 hi = __builtin_amdgcn_cvt_pk_f32_fp8((int)vr[j][w], true);
;           acc[4 * w] += wj * lo[0]; acc[4 * w + 1] += wj * lo[1]; acc[4 * w + 2] += wj * hi[0]; acc[4 * w + 3] += wj * hi[1];
;         }
;       }
	v_cvt_pk_f32_fp8_e32 v[144:145], v100
	v_cvt_pk_f32_fp8_sdwa v[146:147], v100 src0_sel:WORD_1
	v_cvt_pk_f32_fp8_e32 v[148:149], v101
	v_cvt_pk_f32_fp8_sdwa v[150:151], v101 src0_sel:WORD_1
	v_cvt_pk_f32_fp8_e32 v[152:153], v102
	v_cvt_pk_f32_fp8_sdwa v[154:155], v102 src0_sel:WORD_1
	v_cvt_pk_f32_fp8_e32 v[156:157], v103
	v_cvt_pk_f32_fp8_sdwa v[158:159], v103 src0_sel:WORD_1
	v_fmac_f32_e32 v0, v53, v144
	v_fmac_f32_e32 v1, v53, v145
	v_fmac_f32_e32 v2, v53, v146
	v_fmac_f32_e32 v3, v53, v147
	v_fmac_f32_e32 v4, v53, v148
	v_fmac_f32_e32 v5, v53, v149
	v_fmac_f32_e32 v6, v53, v150
	v_fmac_f32_e32 v7, v53, v151
	v_fmac_f32_e32 v8, v53, v152
	v_fmac_f32_e32 v9, v53, v153
	v_fmac_f32_e32 v10, v53, v154
	v_fmac_f32_e32 v11, v53, v155
	v_fmac_f32_e32 v12, v53, v156
	v_fmac_f32_e32 v13, v53, v157
	v_fmac_f32_e32 v14, v53, v158
	v_fmac_f32_e32 v15, v53, v159
	v_lshl_add_u32 v161, v37, 7, v160
	global_load_dwordx4 v[100:103], v161, s[14:15]
	s_waitcnt vmcnt(15)
	v_cvt_pk_f32_fp8_e32 v[144:145], v104
	v_cvt_pk_f32_fp8_sdwa v[146:147], v104 src0_sel:WORD_1
	v_cvt_pk_f32_fp8_e32 v[148:149], v105
	v_cvt_pk_f32_fp8_sdwa v[150:151], v105 src0_sel:WORD_1
	v_cvt_pk_f32_fp8_e32 v[152:153], v106
	v_cvt_pk_f32_fp8_sdwa v[154:155], v106 src0_sel:WORD_1
	v_cvt_pk_f32_fp8_e32 v[156:157], v107
	v_cvt_pk_f32_fp8_sdwa v[158:159], v107 src0_sel:WORD_1
	v_fmac_f32_e32 v0, v54, v144
	v_fmac_f32_e32 v1, v54, v145
	v_fmac_f32_e32 v2, v54, v146
	v_fmac_f32_e32 v3, v54, v147
	v_fmac_f32_e32 v4, v54, v148
	v_fmac_f32_e32 v5, v54, v149
	v_fmac_f32_e32 v6, v54, v150
	v_fmac_f32_e32 v7, v54, v151
	v_fmac_f32_e32 v8, v54, v152
	v_fmac_f32_e32 v9, v54, v153
	v_fmac_f32_e32 v10, v54, v154
	v_fmac_f32_e32 v11, v54, v155
	v_fmac_f32_e32 v12, v54, v156
	v_fmac_f32_e32 v13, v54, v157
	v_fmac_f32_e32 v14, v54, v158
	v_fmac_f32_e32 v15, v54, v159
	v_lshl_add_u32 v161, v38, 7, v160
	global_load_dwordx4 v[104:107], v161, s[14:15]
	s_waitcnt vmcnt(15)
	v_cvt_pk_f32_fp8_e32 v[144:145], v108
	v_cvt_pk_f32_fp8_sdwa v[146:147], v108 src0_sel:WORD_1
	v_cvt_pk_f32_fp8_e32 v[148:149], v109
	v_cvt_pk_f32_fp8_sdwa v[150:151], v109 src0_sel:WORD_1
	v_cvt_pk_f32_fp8_e32 v[152:153], v110
	v_cvt_pk_f32_fp8_sdwa v[154:155], v110 src0_sel:WORD_1
	v_cvt_pk_f32_fp8_e32 v[156:157], v111
	v_cvt_pk_f32_fp8_sdwa v[158:159], v111 src0_sel:WORD_1
	v_fmac_f32_e32 v0, v55, v144
	v_fmac_f32_e32 v1, v55, v145
	v_fmac_f32_e32 v2, v55, v146
	v_fmac_f32_e32 v3, v55, v147
	v_fmac_f32_e32 v4, v55, v148
	v_fmac_f32_e32 v5, v55, v149
	v_fmac_f32_e32 v6, v55, v150
	v_fmac_f32_e32 v7, v55, v151
	v_fmac_f32_e32 v8, v55, v152
	v_fmac_f32_e32 v9, v55, v153
	v_fmac_f32_e32 v10, v55, v154
	v_fmac_f32_e32 v11, v55, v155
	v_fmac_f32_e32 v12, v55, v156
	v_fmac_f32_e32 v13, v55, v157
	v_fmac_f32_e32 v14, v55, v158
	v_fmac_f32_e32 v15, v55, v159
	v_lshl_add_u32 v161, v39, 7, v160
	global_load_dwordx4 v[108:111], v161, s[14:15]
	s_waitcnt vmcnt(15)
	v_cvt_pk_f32_fp8_e32 v[144:145], v112
	v_cvt_pk_f32_fp8_sdwa v[146:147], v112 src0_sel:WORD_1
	v_cvt_pk_f32_fp8_e32 v[148:149], v113
	v_cvt_pk_f32_fp8_sdwa v[150:151], v113 src0_sel:WORD_1
	v_cvt_pk_f32_fp8_e32 v[152:153], v114
	v_cvt_pk_f32_fp8_sdwa v[154:155], v114 src0_sel:WORD_1
	v_cvt_pk_f32_fp8_e32 v[156:157], v115
	v_cvt_pk_f32_fp8_sdwa v[158:159], v115 src0_sel:WORD_1
	v_fmac_f32_e32 v0, v56, v144
	v_fmac_f32_e32 v1, v56, v145
	v_fmac_f32_e32 v2, v56, v146
	v_fmac_f32_e32 v3, v56, v147
	v_fmac_f32_e32 v4, v56, v148
	v_fmac_f32_e32 v5, v56, v149
	v_fmac_f32_e32 v6, v56, v150
	v_fmac_f32_e32 v7, v56, v151
	v_fmac_f32_e32 v8, v56, v152
	v_fmac_f32_e32 v9, v56, v153
	v_fmac_f32_e32 v10, v56, v154
	v_fmac_f32_e32 v11, v56, v155
	v_fmac_f32_e32 v12, v56, v156
	v_fmac_f32_e32 v13, v56, v157
	v_fmac_f32_e32 v14, v56, v158
	v_fmac_f32_e32 v15, v56, v159
	v_lshl_add_u32 v161, v40, 7, v160
	global_load_dwordx4 v[112:115], v161, s[14:15]
	s_waitcnt vmcnt(15)
	v_cvt_pk_f32_fp8_e32 v[144:145], v116
	v_cvt_pk_f32_fp8_sdwa v[146:147], v116 src0_sel:WORD_1
	v_cvt_pk_f32_fp8_e32 v[148:149], v117
	v_cvt_pk_f32_fp8_sdwa v[150:151], v117 src0_sel:WORD_1
	v_cvt_pk_f32_fp8_e32 v[152:153], v118
	v_cvt_pk_f32_fp8_sdwa v[154:155], v118 src0_sel:WORD_1
	v_cvt_pk_f32_fp8_e32 v[156:157], v119
	v_cvt_pk_f32_fp8_sdwa v[158:159], v119 src0_sel:WORD_1
	v_fmac_f32_e32 v0, v57, v144
	v_fmac_f32_e32 v1, v57, v145
	v_fmac_f32_e32 v2, v57, v146
	v_fmac_f32_e32 v3, v57, v147
	v_fmac_f32_e32 v4, v57, v148
	v_fmac_f32_e32 v5, v57, v149
	v_fmac_f32_e32 v6, v57, v150
	v_fmac_f32_e32 v7, v57, v151
	v_fmac_f32_e32 v8, v57, v152
	v_fmac_f32_e32 v9, v57, v153
	v_fmac_f32_e32 v10, v57, v154
	v_fmac_f32_e32 v11, v57, v155
	v_fmac_f32_e32 v12, v57, v156
	v_fmac_f32_e32 v13, v57, v157
	v_fmac_f32_e32 v14, v57, v158
	v_fmac_f32_e32 v15, v57, v159
	v_lshl_add_u32 v161, v41, 7, v160
	global_load_dwordx4 v[116:119], v161, s[14:15]
	s_waitcnt vmcnt(15)
	v_cvt_pk_f32_fp8_e32 v[144:145], v120
	v_cvt_pk_f32_fp8_sdwa v[146:147], v120 src0_sel:WORD_1
	v_cvt_pk_f32_fp8_e32 v[148:149], v121
	v_cvt_pk_f32_fp8_sdwa v[150:151], v121 src0_sel:WORD_1
	v_cvt_pk_f32_fp8_e32 v[152:153], v122
	v_cvt_pk_f32_fp8_sdwa v[154:155], v122 src0_sel:WORD_1
	v_cvt_pk_f32_fp8_e32 v[156:157], v123
	v_cvt_pk_f32_fp8_sdwa v[158:159], v123 src0_sel:WORD_1
	v_fmac_f32_e32 v0, v58, v144
	v_fmac_f32_e32 v1, v58, v145
	v_fmac_f32_e32 v2, v58, v146
	v_fmac_f32_e32 v3, v58, v147
	v_fmac_f32_e32 v4, v58, v148
	v_fmac_f32_e32 v5, v58, v149
	v_fmac_f32_e32 v6, v58, v150
	v_fmac_f32_e32 v7, v58, v151
	v_fmac_f32_e32 v8, v58, v152
	v_fmac_f32_e32 v9, v58, v153
	v_fmac_f32_e32 v10, v58, v154
	v_fmac_f32_e32 v11, v58, v155
	v_fmac_f32_e32 v12, v58, v156
	v_fmac_f32_e32 v13, v58, v157
	v_fmac_f32_e32 v14, v58, v158
	v_fmac_f32_e32 v15, v58, v159
	v_lshl_add_u32 v161, v42, 7, v160
	global_load_dwordx4 v[120:123], v161, s[14:15]
	s_waitcnt vmcnt(15)
; DI void phase_peer_b(const Params& p, int layer, const float* gnext, bool last) {
;     ...
; #pragma unroll
;       for (int j = 0; j < 16; ++j) {
;         const int e = bt * 16 + j;
;         const float wj = __int_as_float(__builtin_amdgcn_readlane(__float_as_int(e < 64 ? w0 : w1), e & 63));
; #pragma unroll
;         for (int w = 0; w < 4; ++w) {
;           const f32x2 lo = __builtin_amdgcn_cvt_pk_f32_fp8((int)vr[j][w], false);
;           const f32x2 hi = __builtin_amdgcn_cvt_pk_f32_fp8((int)vr[j][w], true);
;           acc[4 * w] += wj * lo[0]; acc[4 * w + 1] += wj * lo[1]; acc[4 * w + 2] += wj * hi[0]; acc[4 * w + 3] += wj * hi[1];
;         }
;       }
	v_cvt_pk_f32_fp8_e32 v[144:145], v124
	v_cvt_pk_f32_fp8_sdwa v[146:147], v124 src0_sel:WORD_1
	v_cvt_pk_f32_fp8_e32 v[148:149], v125
	v_cvt_pk_f32_fp8_sdwa v[150:151], v125 src0_sel:WORD_1
	v_cvt_pk_f32_fp8_e32 v[152:153], v126
	v_cvt_pk_f32_fp8_sdwa v[154:155], v126 src0_sel:WORD_1
	v_cvt_pk_f32_fp8_e32 v[156:157], v127
	v_cvt_pk_f32_fp8_sdwa v[158:159], v127 src0_sel:WORD_1
	v_fmac_f32_e32 v0, v59, v144
	v_fmac_f32_e32 v1, v59, v145
	v_fmac_f32_e32 v2, v59, v146
	v_fmac_f32_e32 v3, v59, v147
	v_fmac_f32_e32 v4, v59, v148
	v_fmac_f32_e32 v5, v59, v149
	v_fmac_f32_e32 v6, v59, v150
	v_fmac_f32_e32 v7, v59, v151
	v_fmac_f32_e32 v8, v59, v152
	v_fmac_f32_e32 v9, v59, v153
	v_fmac_f32_e32 v10, v59, v154
	v_fmac_f32_e32 v11, v59, v155
	v_fmac_f32_e32 v12, v59, v156
	v_fmac_f32_e32 v13, v59, v157
	v_fmac_f32_e32 v14, v59, v158
	v_fmac_f32_e32 v15, v59, v159
	v_lshl_add_u32 v161, v43, 7, v160
	global_load_dwordx4 v[124:127], v161, s[14:15]
	s_waitcnt vmcnt(15)
	v_cvt_pk_f32_fp8_e32 v[144:145], v128
	v_cvt_pk_f32_fp8_sdwa v[146:147], v128 src0_sel:WORD_1
	v_cvt_pk_f32_fp8_e32 v[148:149], v129
	v_cvt_pk_f32_fp8_sdwa v[150:151], v129 src0_sel:WORD_1
	v_cvt_pk_f32_fp8_e32 v[152:153], v130
	v_cvt_pk_f32_fp8_sdwa v[154:155], v130 src0_sel:WORD_1
	v_cvt_pk_f32_fp8_e32 v[156:157], v131
	v_cvt_pk_f32_fp8_sdwa v[158:159], v131 src0_sel:WORD_1
	v_fmac_f32_e32 v0, v60, v144
	v_fmac_f32_e32 v1, v60, v145
	v_fmac_f32_e32 v2, v60, v146
	v_fmac_f32_e32 v3, v60, v147
	v_fmac_f32_e32 v4, v60, v148
	v_fmac_f32_e32 v5, v60, v149
	v_fmac_f32_e32 v6, v60, v150
	v_fmac_f32_e32 v7, v60, v151
	v_fmac_f32_e32 v8, v60, v152
	v_fmac_f32_e32 v9, v60, v153
	v_fmac_f32_e32 v10, v60, v154
	v_fmac_f32_e32 v11, v60, v155
	v_fmac_f32_e32 v12, v60, v156
	v_fmac_f32_e32 v13, v60, v157
	v_fmac_f32_e32 v14, v60, v158
	v_fmac_f32_e32 v15, v60, v159
	v_lshl_add_u32 v161, v44, 7, v160
	global_load_dwordx4 v[128:131], v161, s[14:15]
	s_waitcnt vmcnt(15)
	v_cvt_pk_f32_fp8_e32 v[144:145], v132
	v_cvt_pk_f32_fp8_sdwa v[146:147], v132 src0_sel:WORD_1
	v_cvt_pk_f32_fp8_e32 v[148:149], v133
	v_cvt_pk_f32_fp8_sdwa v[150:151], v133 src0_sel:WORD_1
	v_cvt_pk_f32_fp8_e32 v[152:153], v134
	v_cvt_pk_f32_fp8_sdwa v[154:155], v134 src0_sel:WORD_1
	v_cvt_pk_f32_fp8_e32 v[156:157], v135
	v_cvt_pk_f32_fp8_sdwa v[158:159], v135 src0_sel:WORD_1
	v_fmac_f32_e32 v0, v61, v144
	v_fmac_f32_e32 v1, v61, v145
	v_fmac_f32_e32 v2, v61, v146
	v_fmac_f32_e32 v3, v61, v147
	v_fmac_f32_e32 v4, v61, v148
	v_fmac_f32_e32 v5, v61, v149
	v_fmac_f32_e32 v6, v61, v150
	v_fmac_f32_e32 v7, v61, v151
	v_fmac_f32_e32 v8, v61, v152
	v_fmac_f32_e32 v9, v61, v153
	v_fmac_f32_e32 v10, v61, v154
	v_fmac_f32_e32 v11, v61, v155
	v_fmac_f32_e32 v12, v61, v156
	v_fmac_f32_e32 v13, v61, v157
	v_fmac_f32_e32 v14, v61, v158
	v_fmac_f32_e32 v15, v61, v159
	v_lshl_add_u32 v161, v45, 7, v160
	global_load_dwordx4 v[132:135], v161, s[14:15]
	s_waitcnt vmcnt(15)
	v_cvt_pk_f32_fp8_e32 v[144:145], v136
	v_cvt_pk_f32_fp8_sdwa v[146:147], v136 src0_sel:WORD_1
	v_cvt_pk_f32_fp8_e32 v[148:149], v137
	v_cvt_pk_f32_fp8_sdwa v[150:151], v137 src0_sel:WORD_1
	v_cvt_pk_f32_fp8_e32 v[152:153], v138
	v_cvt_pk_f32_fp8_sdwa v[154:155], v138 src0_sel:WORD_1
	v_cvt_pk_f32_fp8_e32 v[156:157], v139
	v_cvt_pk_f32_fp8_sdwa v[158:159], v139 src0_sel:WORD_1
	v_fmac_f32_e32 v0, v62, v144
	v_fmac_f32_e32 v1, v62, v145
	v_fmac_f32_e32 v2, v62, v146
	v_fmac_f32_e32 v3, v62, v147
	v_fmac_f32_e32 v4, v62, v148
	v_fmac_f32_e32 v5, v62, v149
	v_fmac_f32_e32 v6, v62, v150
	v_fmac_f32_e32 v7, v62, v151
	v_fmac_f32_e32 v8, v62, v152
	v_fmac_f32_e32 v9, v62, v153
	v_fmac_f32_e32 v10, v62, v154
	v_fmac_f32_e32 v11, v62, v155
	v_fmac_f32_e32 v12, v62, v156
	v_fmac_f32_e32 v13, v62, v157
	v_fmac_f32_e32 v14, v62, v158
	v_fmac_f32_e32 v15, v62, v159
	v_lshl_add_u32 v161, v46, 7, v160
	global_load_dwordx4 v[136:139], v161, s[14:15]
	s_waitcnt vmcnt(15)
	v_cvt_pk_f32_fp8_e32 v[144:145], v140
	v_cvt_pk_f32_fp8_sdwa v[146:147], v140 src0_sel:WORD_1
	v_cvt_pk_f32_fp8_e32 v[148:149], v141
	v_cvt_pk_f32_fp8_sdwa v[150:151], v141 src0_sel:WORD_1
	v_cvt_pk_f32_fp8_e32 v[152:153], v142
	v_cvt_pk_f32_fp8_sdwa v[154:155], v142 src0_sel:WORD_1
	v_cvt_pk_f32_fp8_e32 v[156:157], v143
	v_cvt_pk_f32_fp8_sdwa v[158:159], v143 src0_sel:WORD_1
	v_fmac_f32_e32 v0, v63, v144
	v_fmac_f32_e32 v1, v63, v145
	v_fmac_f32_e32 v2, v63, v146
	v_fmac_f32_e32 v3, v63, v147
	v_fmac_f32_e32 v4, v63, v148
	v_fmac_f32_e32 v5, v63, v149
	v_fmac_f32_e32 v6, v63, v150
	v_fmac_f32_e32 v7, v63, v151
	v_fmac_f32_e32 v8, v63, v152
	v_fmac_f32_e32 v9, v63, v153
	v_fmac_f32_e32 v10, v63, v154
	v_fmac_f32_e32 v11, v63, v155
	v_fmac_f32_e32 v12, v63, v156
	v_fmac_f32_e32 v13, v63, v157
	v_fmac_f32_e32 v14, v63, v158
	v_fmac_f32_e32 v15, v63, v159
	v_lshl_add_u32 v161, v47, 7, v160
	global_load_dwordx4 v[140:143], v161, s[14:15]
	s_waitcnt lgkmcnt(0)
	ds_read_b128 v[32:35], v163 offset:448
	ds_read_b128 v[36:39], v163 offset:464
	ds_read_b128 v[40:43], v163 offset:480
	ds_read_b128 v[44:47], v163 offset:496
	ds_read_b128 v[48:51], v163 offset:896
	ds_read_b128 v[52:55], v163 offset:912
	ds_read_b128 v[56:59], v163 offset:928
	ds_read_b128 v[60:63], v163 offset:944
	s_waitcnt vmcnt(15)
; DI void phase_peer_b(const Params& p, int layer, const float* gnext, bool last) {
;     ...
; #pragma unroll
;       for (int j = 0; j < 16; ++j) {
;         const int e = bt * 16 + j;
;         const float wj = __int_as_float(__builtin_amdgcn_readlane(__float_as_int(e < 64 ? w0 : w1), e & 63));
; #pragma unroll
;         for (int w = 0; w < 4; ++w) {
;           const f32x2 lo = __builtin_amdgcn_cvt_pk_f32_fp8((int)vr[j][w], false);
;           const f32x2 hi = __builtin_amdgcn_cvt_pk_f32_fp8((int)vr[j][w], true);
;           acc[4 * w] += wj * lo[0]; acc[4 * w + 1] += wj * lo[1]; acc[4 * w + 2] += wj * hi[0]; acc[4 * w + 3] += wj * hi[1];
;         }
;       }
	v_cvt_pk_f32_fp8_e32 v[144:145], v80
	v_cvt_pk_f32_fp8_sdwa v[146:147], v80 src0_sel:WORD_1
	v_cvt_pk_f32_fp8_e32 v[148:149], v81
	v_cvt_pk_f32_fp8_sdwa v[150:151], v81 src0_sel:WORD_1
	v_cvt_pk_f32_fp8_e32 v[152:153], v82
	v_cvt_pk_f32_fp8_sdwa v[154:155], v82 src0_sel:WORD_1
	v_cvt_pk_f32_fp8_e32 v[156:157], v83
	v_cvt_pk_f32_fp8_sdwa v[158:159], v83 src0_sel:WORD_1
	v_fmac_f32_e32 v0, v64, v144
	v_fmac_f32_e32 v1, v64, v145
	v_fmac_f32_e32 v2, v64, v146
	v_fmac_f32_e32 v3, v64, v147
	v_fmac_f32_e32 v4, v64, v148
	v_fmac_f32_e32 v5, v64, v149
	v_fmac_f32_e32 v6, v64, v150
	v_fmac_f32_e32 v7, v64, v151
	v_fmac_f32_e32 v8, v64, v152
	v_fmac_f32_e32 v9, v64, v153
	v_fmac_f32_e32 v10, v64, v154
	v_fmac_f32_e32 v11, v64, v155
	v_fmac_f32_e32 v12, v64, v156
	v_fmac_f32_e32 v13, v64, v157
	v_fmac_f32_e32 v14, v64, v158
	v_fmac_f32_e32 v15, v64, v159
	v_lshl_add_u32 v161, v16, 7, v160
	global_load_dwordx4 v[80:83], v161, s[14:15]
	s_waitcnt vmcnt(15)
	v_cvt_pk_f32_fp8_e32 v[144:145], v84
	v_cvt_pk_f32_fp8_sdwa v[146:147], v84 src0_sel:WORD_1
	v_cvt_pk_f32_fp8_e32 v[148:149], v85
	v_cvt_pk_f32_fp8_sdwa v[150:151], v85 src0_sel:WORD_1
	v_cvt_pk_f32_fp8_e32 v[152:153], v86
	v_cvt_pk_f32_fp8_sdwa v[154:155], v86 src0_sel:WORD_1
	v_cvt_pk_f32_fp8_e32 v[156:157], v87
	v_cvt_pk_f32_fp8_sdwa v[158:159], v87 src0_sel:WORD_1
	v_fmac_f32_e32 v0, v65, v144
	v_fmac_f32_e32 v1, v65, v145
	v_fmac_f32_e32 v2, v65, v146
	v_fmac_f32_e32 v3, v65, v147
	v_fmac_f32_e32 v4, v65, v148
	v_fmac_f32_e32 v5, v65, v149
	v_fmac_f32_e32 v6, v65, v150
	v_fmac_f32_e32 v7, v65, v151
	v_fmac_f32_e32 v8, v65, v152
	v_fmac_f32_e32 v9, v65, v153
	v_fmac_f32_e32 v10, v65, v154
	v_fmac_f32_e32 v11, v65, v155
	v_fmac_f32_e32 v12, v65, v156
	v_fmac_f32_e32 v13, v65, v157
	v_fmac_f32_e32 v14, v65, v158
	v_fmac_f32_e32 v15, v65, v159
	v_lshl_add_u32 v161, v17, 7, v160
	global_load_dwordx4 v[84:87], v161, s[14:15]
	s_waitcnt vmcnt(15)
	v_cvt_pk_f32_fp8_e32 v[144:145], v88
	v_cvt_pk_f32_fp8_sdwa v[146:147], v88 src0_sel:WORD_1
	v_cvt_pk_f32_fp8_e32 v[148:149], v89
	v_cvt_pk_f32_fp8_sdwa v[150:151], v89 src0_sel:WORD_1
	v_cvt_pk_f32_fp8_e32 v[152:153], v90
	v_cvt_pk_f32_fp8_sdwa v[154:155], v90 src0_sel:WORD_1
	v_cvt_pk_f32_fp8_e32 v[156:157], v91
	v_cvt_pk_f32_fp8_sdwa v[158:159], v91 src0_sel:WORD_1
	v_fmac_f32_e32 v0, v66, v144
	v_fmac_f32_e32 v1, v66, v145
	v_fmac_f32_e32 v2, v66, v146
	v_fmac_f32_e32 v3, v66, v147
	v_fmac_f32_e32 v4, v66, v148
	v_fmac_f32_e32 v5, v66, v149
	v_fmac_f32_e32 v6, v66, v150
	v_fmac_f32_e32 v7, v66, v151
	v_fmac_f32_e32 v8, v66, v152
	v_fmac_f32_e32 v9, v66, v153
	v_fmac_f32_e32 v10, v66, v154
	v_fmac_f32_e32 v11, v66, v155
	v_fmac_f32_e32 v12, v66, v156
	v_fmac_f32_e32 v13, v66, v157
	v_fmac_f32_e32 v14, v66, v158
	v_fmac_f32_e32 v15, v66, v159
	v_lshl_add_u32 v161, v18, 7, v160
	global_load_dwordx4 v[88:91], v161, s[14:15]
	s_waitcnt vmcnt(15)
	v_cvt_pk_f32_fp8_e32 v[144:145], v92
	v_cvt_pk_f32_fp8_sdwa v[146:147], v92 src0_sel:WORD_1
	v_cvt_pk_f32_fp8_e32 v[148:149], v93
	v_cvt_pk_f32_fp8_sdwa v[150:151], v93 src0_sel:WORD_1
	v_cvt_pk_f32_fp8_e32 v[152:153], v94
	v_cvt_pk_f32_fp8_sdwa v[154:155], v94 src0_sel:WORD_1
	v_cvt_pk_f32_fp8_e32 v[156:157], v95
	v_cvt_pk_f32_fp8_sdwa v[158:159], v95 src0_sel:WORD_1
	v_fmac_f32_e32 v0, v67, v144
	v_fmac_f32_e32 v1, v67, v145
	v_fmac_f32_e32 v2, v67, v146
	v_fmac_f32_e32 v3, v67, v147
	v_fmac_f32_e32 v4, v67, v148
	v_fmac_f32_e32 v5, v67, v149
	v_fmac_f32_e32 v6, v67, v150
	v_fmac_f32_e32 v7, v67, v151
	v_fmac_f32_e32 v8, v67, v152
	v_fmac_f32_e32 v9, v67, v153
	v_fmac_f32_e32 v10, v67, v154
	v_fmac_f32_e32 v11, v67, v155
	v_fmac_f32_e32 v12, v67, v156
	v_fmac_f32_e32 v13, v67, v157
	v_fmac_f32_e32 v14, v67, v158
	v_fmac_f32_e32 v15, v67, v159
	v_lshl_add_u32 v161, v19, 7, v160
	global_load_dwordx4 v[92:95], v161, s[14:15]
	s_waitcnt vmcnt(15)
	v_cvt_pk_f32_fp8_e32 v[144:145], v96
	v_cvt_pk_f32_fp8_sdwa v[146:147], v96 src0_sel:WORD_1
	v_cvt_pk_f32_fp8_e32 v[148:149], v97
	v_cvt_pk_f32_fp8_sdwa v[150:151], v97 src0_sel:WORD_1
	v_cvt_pk_f32_fp8_e32 v[152:153], v98
	v_cvt_pk_f32_fp8_sdwa v[154:155], v98 src0_sel:WORD_1
	v_cvt_pk_f32_fp8_e32 v[156:157], v99
	v_cvt_pk_f32_fp8_sdwa v[158:159], v99 src0_sel:WORD_1
	v_fmac_f32_e32 v0, v68, v144
	v_fmac_f32_e32 v1, v68, v145
	v_fmac_f32_e32 v2, v68, v146
	v_fmac_f32_e32 v3, v68, v147
	v_fmac_f32_e32 v4, v68, v148
	v_fmac_f32_e32 v5, v68, v149
	v_fmac_f32_e32 v6, v68, v150
	v_fmac_f32_e32 v7, v68, v151
	v_fmac_f32_e32 v8, v68, v152
	v_fmac_f32_e32 v9, v68, v153
	v_fmac_f32_e32 v10, v68, v154
	v_fmac_f32_e32 v11, v68, v155
	v_fmac_f32_e32 v12, v68, v156
	v_fmac_f32_e32 v13, v68, v157
	v_fmac_f32_e32 v14, v68, v158
	v_fmac_f32_e32 v15, v68, v159
	v_lshl_add_u32 v161, v20, 7, v160
	global_load_dwordx4 v[96:99], v161, s[14:15]
	s_waitcnt vmcnt(15)
	v_cvt_pk_f32_fp8_e32 v[144:145], v100
	v_cvt_pk_f32_fp8_sdwa v[146:147], v100 src0_sel:WORD_1
	v_cvt_pk_f32_fp8_e32 v[148:149], v101
	v_cvt_pk_f32_fp8_sdwa v[150:151], v101 src0_sel:WORD_1
	v_cvt_pk_f32_fp8_e32 v[152:153], v102
	v_cvt_pk_f32_fp8_sdwa v[154:155], v102 src0_sel:WORD_1
	v_cvt_pk_f32_fp8_e32 v[156:157], v103
	v_cvt_pk_f32_fp8_sdwa v[158:159], v103 src0_sel:WORD_1
	v_fmac_f32_e32 v0, v69, v144
	v_fmac_f32_e32 v1, v69, v145
	v_fmac_f32_e32 v2, v69, v146
	v_fmac_f32_e32 v3, v69, v147
	v_fmac_f32_e32 v4, v69, v148
	v_fmac_f32_e32 v5, v69, v149
	v_fmac_f32_e32 v6, v69, v150
	v_fmac_f32_e32 v7, v69, v151
	v_fmac_f32_e32 v8, v69, v152
	v_fmac_f32_e32 v9, v69, v153
	v_fmac_f32_e32 v10, v69, v154
	v_fmac_f32_e32 v11, v69, v155
	v_fmac_f32_e32 v12, v69, v156
	v_fmac_f32_e32 v13, v69, v157
	v_fmac_f32_e32 v14, v69, v158
	v_fmac_f32_e32 v15, v69, v159
	v_lshl_add_u32 v161, v21, 7, v160
	global_load_dwordx4 v[100:103], v161, s[14:15]
	s_waitcnt vmcnt(15)
; DI void phase_peer_b(const Params& p, int layer, const float* gnext, bool last) {
;     ...
; #pragma unroll
;       for (int j = 0; j < 16; ++j) {
;         const int e = bt * 16 + j;
;         const float wj = __int_as_float(__builtin_amdgcn_readlane(__float_as_int(e < 64 ? w0 : w1), e & 63));
; #pragma unroll
;         for (int w = 0; w < 4; ++w) {
;           const f32x2 lo = __builtin_amdgcn_cvt_pk_f32_fp8((int)vr[j][w], false);
;           const f32x2 hi = __builtin_amdgcn_cvt_pk_f32_fp8((int)vr[j][w], true);
;           acc[4 * w] += wj * lo[0]; acc[4 * w + 1] += wj * lo[1]; acc[4 * w + 2] += wj * hi[0]; acc[4 * w + 3] += wj * hi[1];
;         }
;       }
	v_cvt_pk_f32_fp8_e32 v[144:145], v104
	v_cvt_pk_f32_fp8_sdwa v[146:147], v104 src0_sel:WORD_1
	v_cvt_pk_f32_fp8_e32 v[148:149], v105
	v_cvt_pk_f32_fp8_sdwa v[150:151], v105 src0_sel:WORD_1
	v_cvt_pk_f32_fp8_e32 v[152:153], v106
	v_cvt_pk_f32_fp8_sdwa v[154:155], v106 src0_sel:WORD_1
	v_cvt_pk_f32_fp8_e32 v[156:157], v107
	v_cvt_pk_f32_fp8_sdwa v[158:159], v107 src0_sel:WORD_1
	v_fmac_f32_e32 v0, v70, v144
	v_fmac_f32_e32 v1, v70, v145
	v_fmac_f32_e32 v2, v70, v146
	v_fmac_f32_e32 v3, v70, v147
	v_fmac_f32_e32 v4, v70, v148
	v_fmac_f32_e32 v5, v70, v149
	v_fmac_f32_e32 v6, v70, v150
	v_fmac_f32_e32 v7, v70, v151
	v_fmac_f32_e32 v8, v70, v152
	v_fmac_f32_e32 v9, v70, v153
	v_fmac_f32_e32 v10, v70, v154
	v_fmac_f32_e32 v11, v70, v155
	v_fmac_f32_e32 v12, v70, v156
	v_fmac_f32_e32 v13, v70, v157
	v_fmac_f32_e32 v14, v70, v158
	v_fmac_f32_e32 v15, v70, v159
	v_lshl_add_u32 v161, v22, 7, v160
	global_load_dwordx4 v[104:107], v161, s[14:15]
	s_waitcnt vmcnt(15)
	v_cvt_pk_f32_fp8_e32 v[144:145], v108
	v_cvt_pk_f32_fp8_sdwa v[146:147], v108 src0_sel:WORD_1
	v_cvt_pk_f32_fp8_e32 v[148:149], v109
	v_cvt_pk_f32_fp8_sdwa v[150:151], v109 src0_sel:WORD_1
	v_cvt_pk_f32_fp8_e32 v[152:153], v110
	v_cvt_pk_f32_fp8_sdwa v[154:155], v110 src0_sel:WORD_1
	v_cvt_pk_f32_fp8_e32 v[156:157], v111
	v_cvt_pk_f32_fp8_sdwa v[158:159], v111 src0_sel:WORD_1
	v_fmac_f32_e32 v0, v71, v144
	v_fmac_f32_e32 v1, v71, v145
	v_fmac_f32_e32 v2, v71, v146
	v_fmac_f32_e32 v3, v71, v147
	v_fmac_f32_e32 v4, v71, v148
	v_fmac_f32_e32 v5, v71, v149
	v_fmac_f32_e32 v6, v71, v150
	v_fmac_f32_e32 v7, v71, v151
	v_fmac_f32_e32 v8, v71, v152
	v_fmac_f32_e32 v9, v71, v153
	v_fmac_f32_e32 v10, v71, v154
	v_fmac_f32_e32 v11, v71, v155
	v_fmac_f32_e32 v12, v71, v156
	v_fmac_f32_e32 v13, v71, v157
	v_fmac_f32_e32 v14, v71, v158
	v_fmac_f32_e32 v15, v71, v159
	v_lshl_add_u32 v161, v23, 7, v160
	global_load_dwordx4 v[108:111], v161, s[14:15]
	s_waitcnt vmcnt(15)
	v_cvt_pk_f32_fp8_e32 v[144:145], v112
	v_cvt_pk_f32_fp8_sdwa v[146:147], v112 src0_sel:WORD_1
	v_cvt_pk_f32_fp8_e32 v[148:149], v113
	v_cvt_pk_f32_fp8_sdwa v[150:151], v113 src0_sel:WORD_1
	v_cvt_pk_f32_fp8_e32 v[152:153], v114
	v_cvt_pk_f32_fp8_sdwa v[154:155], v114 src0_sel:WORD_1
	v_cvt_pk_f32_fp8_e32 v[156:157], v115
	v_cvt_pk_f32_fp8_sdwa v[158:159], v115 src0_sel:WORD_1
	v_fmac_f32_e32 v0, v72, v144
	v_fmac_f32_e32 v1, v72, v145
	v_fmac_f32_e32 v2, v72, v146
	v_fmac_f32_e32 v3, v72, v147
	v_fmac_f32_e32 v4, v72, v148
	v_fmac_f32_e32 v5, v72, v149
	v_fmac_f32_e32 v6, v72, v150
	v_fmac_f32_e32 v7, v72, v151
	v_fmac_f32_e32 v8, v72, v152
	v_fmac_f32_e32 v9, v72, v153
	v_fmac_f32_e32 v10, v72, v154
	v_fmac_f32_e32 v11, v72, v155
	v_fmac_f32_e32 v12, v72, v156
	v_fmac_f32_e32 v13, v72, v157
	v_fmac_f32_e32 v14, v72, v158
	v_fmac_f32_e32 v15, v72, v159
	v_lshl_add_u32 v161, v24, 7, v160
	global_load_dwordx4 v[112:115], v161, s[14:15]
	s_waitcnt vmcnt(15)
	v_cvt_pk_f32_fp8_e32 v[144:145], v116
	v_cvt_pk_f32_fp8_sdwa v[146:147], v116 src0_sel:WORD_1
	v_cvt_pk_f32_fp8_e32 v[148:149], v117
	v_cvt_pk_f32_fp8_sdwa v[150:151], v117 src0_sel:WORD_1
	v_cvt_pk_f32_fp8_e32 v[152:153], v118
	v_cvt_pk_f32_fp8_sdwa v[154:155], v118 src0_sel:WORD_1
	v_cvt_pk_f32_fp8_e32 v[156:157], v119
	v_cvt_pk_f32_fp8_sdwa v[158:159], v119 src0_sel:WORD_1
	v_fmac_f32_e32 v0, v73, v144
	v_fmac_f32_e32 v1, v73, v145
	v_fmac_f32_e32 v2, v73, v146
	v_fmac_f32_e32 v3, v73, v147
	v_fmac_f32_e32 v4, v73, v148
	v_fmac_f32_e32 v5, v73, v149
	v_fmac_f32_e32 v6, v73, v150
	v_fmac_f32_e32 v7, v73, v151
	v_fmac_f32_e32 v8, v73, v152
	v_fmac_f32_e32 v9, v73, v153
	v_fmac_f32_e32 v10, v73, v154
	v_fmac_f32_e32 v11, v73, v155
	v_fmac_f32_e32 v12, v73, v156
	v_fmac_f32_e32 v13, v73, v157
	v_fmac_f32_e32 v14, v73, v158
	v_fmac_f32_e32 v15, v73, v159
	v_lshl_add_u32 v161, v25, 7, v160
	global_load_dwordx4 v[116:119], v161, s[14:15]
	s_waitcnt vmcnt(15)
	v_cvt_pk_f32_fp8_e32 v[144:145], v120
	v_cvt_pk_f32_fp8_sdwa v[146:147], v120 src0_sel:WORD_1
	v_cvt_pk_f32_fp8_e32 v[148:149], v121
	v_cvt_pk_f32_fp8_sdwa v[150:151], v121 src0_sel:WORD_1
	v_cvt_pk_f32_fp8_e32 v[152:153], v122
	v_cvt_pk_f32_fp8_sdwa v[154:155], v122 src0_sel:WORD_1
	v_cvt_pk_f32_fp8_e32 v[156:157], v123
	v_cvt_pk_f32_fp8_sdwa v[158:159], v123 src0_sel:WORD_1
	v_fmac_f32_e32 v0, v74, v144
	v_fmac_f32_e32 v1, v74, v145
	v_fmac_f32_e32 v2, v74, v146
	v_fmac_f32_e32 v3, v74, v147
	v_fmac_f32_e32 v4, v74, v148
	v_fmac_f32_e32 v5, v74, v149
	v_fmac_f32_e32 v6, v74, v150
	v_fmac_f32_e32 v7, v74, v151
	v_fmac_f32_e32 v8, v74, v152
	v_fmac_f32_e32 v9, v74, v153
	v_fmac_f32_e32 v10, v74, v154
	v_fmac_f32_e32 v11, v74, v155
	v_fmac_f32_e32 v12, v74, v156
	v_fmac_f32_e32 v13, v74, v157
	v_fmac_f32_e32 v14, v74, v158
	v_fmac_f32_e32 v15, v74, v159
	v_lshl_add_u32 v161, v26, 7, v160
	global_load_dwordx4 v[120:123], v161, s[14:15]
	s_waitcnt vmcnt(15)
	v_cvt_pk_f32_fp8_e32 v[144:145], v124
	v_cvt_pk_f32_fp8_sdwa v[146:147], v124 src0_sel:WORD_1
	v_cvt_pk_f32_fp8_e32 v[148:149], v125
	v_cvt_pk_f32_fp8_sdwa v[150:151], v125 src0_sel:WORD_1
	v_cvt_pk_f32_fp8_e32 v[152:153], v126
	v_cvt_pk_f32_fp8_sdwa v[154:155], v126 src0_sel:WORD_1
	v_cvt_pk_f32_fp8_e32 v[156:157], v127
	v_cvt_pk_f32_fp8_sdwa v[158:159], v127 src0_sel:WORD_1
	v_fmac_f32_e32 v0, v75, v144
	v_fmac_f32_e32 v1, v75, v145
	v_fmac_f32_e32 v2, v75, v146
	v_fmac_f32_e32 v3, v75, v147
	v_fmac_f32_e32 v4, v75, v148
	v_fmac_f32_e32 v5, v75, v149
	v_fmac_f32_e32 v6, v75, v150
	v_fmac_f32_e32 v7, v75, v151
	v_fmac_f32_e32 v8, v75, v152
	v_fmac_f32_e32 v9, v75, v153
	v_fmac_f32_e32 v10, v75, v154
	v_fmac_f32_e32 v11, v75, v155
	v_fmac_f32_e32 v12, v75, v156
	v_fmac_f32_e32 v13, v75, v157
	v_fmac_f32_e32 v14, v75, v158
	v_fmac_f32_e32 v15, v75, v159
	v_lshl_add_u32 v161, v27, 7, v160
	global_load_dwordx4 v[124:127], v161, s[14:15]
	s_waitcnt vmcnt(15)
; DI void phase_peer_b(const Params& p, int layer, const float* gnext, bool last) {
;     ...
; #pragma unroll
;       for (int j = 0; j < 16; ++j) {
;         const int e = bt * 16 + j;
;         const float wj = __int_as_float(__builtin_amdgcn_readlane(__float_as_int(e < 64 ? w0 : w1), e & 63));
; #pragma unroll
;         for (int w = 0; w < 4; ++w) {
;           const f32x2 lo = __builtin_amdgcn_cvt_pk_f32_fp8((int)vr[j][w], false);
;           const f32x2 hi = __builtin_amdgcn_cvt_pk_f32_fp8((int)vr[j][w], true);
;           acc[4 * w] += wj * lo[0]; acc[4 * w + 1] += wj * lo[1]; acc[4 * w + 2] += wj * hi[0]; acc[4 * w + 3] += wj * hi[1];
;         }
;       }
	v_cvt_pk_f32_fp8_e32 v[144:145], v128
	v_cvt_pk_f32_fp8_sdwa v[146:147], v128 src0_sel:WORD_1
	v_cvt_pk_f32_fp8_e32 v[148:149], v129
	v_cvt_pk_f32_fp8_sdwa v[150:151], v129 src0_sel:WORD_1
	v_cvt_pk_f32_fp8_e32 v[152:153], v130
	v_cvt_pk_f32_fp8_sdwa v[154:155], v130 src0_sel:WORD_1
	v_cvt_pk_f32_fp8_e32 v[156:157], v131
	v_cvt_pk_f32_fp8_sdwa v[158:159], v131 src0_sel:WORD_1
	v_fmac_f32_e32 v0, v76, v144
	v_fmac_f32_e32 v1, v76, v145
	v_fmac_f32_e32 v2, v76, v146
	v_fmac_f32_e32 v3, v76, v147
	v_fmac_f32_e32 v4, v76, v148
	v_fmac_f32_e32 v5, v76, v149
	v_fmac_f32_e32 v6, v76, v150
	v_fmac_f32_e32 v7, v76, v151
	v_fmac_f32_e32 v8, v76, v152
	v_fmac_f32_e32 v9, v76, v153
	v_fmac_f32_e32 v10, v76, v154
	v_fmac_f32_e32 v11, v76, v155
	v_fmac_f32_e32 v12, v76, v156
	v_fmac_f32_e32 v13, v76, v157
	v_fmac_f32_e32 v14, v76, v158
	v_fmac_f32_e32 v15, v76, v159
	v_lshl_add_u32 v161, v28, 7, v160
	global_load_dwordx4 v[128:131], v161, s[14:15]
	s_waitcnt vmcnt(15)
	v_cvt_pk_f32_fp8_e32 v[144:145], v132
	v_cvt_pk_f32_fp8_sdwa v[146:147], v132 src0_sel:WORD_1
	v_cvt_pk_f32_fp8_e32 v[148:149], v133
	v_cvt_pk_f32_fp8_sdwa v[150:151], v133 src0_sel:WORD_1
	v_cvt_pk_f32_fp8_e32 v[152:153], v134
	v_cvt_pk_f32_fp8_sdwa v[154:155], v134 src0_sel:WORD_1
	v_cvt_pk_f32_fp8_e32 v[156:157], v135
	v_cvt_pk_f32_fp8_sdwa v[158:159], v135 src0_sel:WORD_1
	v_fmac_f32_e32 v0, v77, v144
	v_fmac_f32_e32 v1, v77, v145
	v_fmac_f32_e32 v2, v77, v146
	v_fmac_f32_e32 v3, v77, v147
	v_fmac_f32_e32 v4, v77, v148
	v_fmac_f32_e32 v5, v77, v149
	v_fmac_f32_e32 v6, v77, v150
	v_fmac_f32_e32 v7, v77, v151
	v_fmac_f32_e32 v8, v77, v152
	v_fmac_f32_e32 v9, v77, v153
	v_fmac_f32_e32 v10, v77, v154
	v_fmac_f32_e32 v11, v77, v155
	v_fmac_f32_e32 v12, v77, v156
	v_fmac_f32_e32 v13, v77, v157
	v_fmac_f32_e32 v14, v77, v158
	v_fmac_f32_e32 v15, v77, v159
	v_lshl_add_u32 v161, v29, 7, v160
	global_load_dwordx4 v[132:135], v161, s[14:15]
	s_waitcnt vmcnt(15)
	v_cvt_pk_f32_fp8_e32 v[144:145], v136
	v_cvt_pk_f32_fp8_sdwa v[146:147], v136 src0_sel:WORD_1
	v_cvt_pk_f32_fp8_e32 v[148:149], v137
	v_cvt_pk_f32_fp8_sdwa v[150:151], v137 src0_sel:WORD_1
	v_cvt_pk_f32_fp8_e32 v[152:153], v138
	v_cvt_pk_f32_fp8_sdwa v[154:155], v138 src0_sel:WORD_1
	v_cvt_pk_f32_fp8_e32 v[156:157], v139
	v_cvt_pk_f32_fp8_sdwa v[158:159], v139 src0_sel:WORD_1
	v_fmac_f32_e32 v0, v78, v144
	v_fmac_f32_e32 v1, v78, v145
	v_fmac_f32_e32 v2, v78, v146
	v_fmac_f32_e32 v3, v78, v147
	v_fmac_f32_e32 v4, v78, v148
	v_fmac_f32_e32 v5, v78, v149
	v_fmac_f32_e32 v6, v78, v150
	v_fmac_f32_e32 v7, v78, v151
	v_fmac_f32_e32 v8, v78, v152
	v_fmac_f32_e32 v9, v78, v153
	v_fmac_f32_e32 v10, v78, v154
	v_fmac_f32_e32 v11, v78, v155
	v_fmac_f32_e32 v12, v78, v156
	v_fmac_f32_e32 v13, v78, v157
	v_fmac_f32_e32 v14, v78, v158
	v_fmac_f32_e32 v15, v78, v159
	v_lshl_add_u32 v161, v30, 7, v160
	global_load_dwordx4 v[136:139], v161, s[14:15]
	s_waitcnt vmcnt(15)
	v_cvt_pk_f32_fp8_e32 v[144:145], v140
	v_cvt_pk_f32_fp8_sdwa v[146:147], v140 src0_sel:WORD_1
	v_cvt_pk_f32_fp8_e32 v[148:149], v141
	v_cvt_pk_f32_fp8_sdwa v[150:151], v141 src0_sel:WORD_1
	v_cvt_pk_f32_fp8_e32 v[152:153], v142
	v_cvt_pk_f32_fp8_sdwa v[154:155], v142 src0_sel:WORD_1
	v_cvt_pk_f32_fp8_e32 v[156:157], v143
	v_cvt_pk_f32_fp8_sdwa v[158:159], v143 src0_sel:WORD_1
	v_fmac_f32_e32 v0, v79, v144
	v_fmac_f32_e32 v1, v79, v145
	v_fmac_f32_e32 v2, v79, v146
	v_fmac_f32_e32 v3, v79, v147
	v_fmac_f32_e32 v4, v79, v148
	v_fmac_f32_e32 v5, v79, v149
	v_fmac_f32_e32 v6, v79, v150
	v_fmac_f32_e32 v7, v79, v151
	v_fmac_f32_e32 v8, v79, v152
	v_fmac_f32_e32 v9, v79, v153
	v_fmac_f32_e32 v10, v79, v154
	v_fmac_f32_e32 v11, v79, v155
	v_fmac_f32_e32 v12, v79, v156
	v_fmac_f32_e32 v13, v79, v157
	v_fmac_f32_e32 v14, v79, v158
	v_fmac_f32_e32 v15, v79, v159
	v_lshl_add_u32 v161, v31, 7, v160
	global_load_dwordx4 v[140:143], v161, s[14:15]
	s_waitcnt lgkmcnt(0)
	ds_read_b128 v[64:67], v163 offset:960
	ds_read_b128 v[68:71], v163 offset:976
	ds_read_b128 v[72:75], v163 offset:992
	ds_read_b128 v[76:79], v163 offset:1008
	s_waitcnt vmcnt(15)
	v_cvt_pk_f32_fp8_e32 v[144:145], v80
	v_cvt_pk_f32_fp8_sdwa v[146:147], v80 src0_sel:WORD_1
	v_cvt_pk_f32_fp8_e32 v[148:149], v81
	v_cvt_pk_f32_fp8_sdwa v[150:151], v81 src0_sel:WORD_1
	v_cvt_pk_f32_fp8_e32 v[152:153], v82
	v_cvt_pk_f32_fp8_sdwa v[154:155], v82 src0_sel:WORD_1
	v_cvt_pk_f32_fp8_e32 v[156:157], v83
	v_cvt_pk_f32_fp8_sdwa v[158:159], v83 src0_sel:WORD_1
	v_fmac_f32_e32 v0, v48, v144
	v_fmac_f32_e32 v1, v48, v145
	v_fmac_f32_e32 v2, v48, v146
	v_fmac_f32_e32 v3, v48, v147
	v_fmac_f32_e32 v4, v48, v148
	v_fmac_f32_e32 v5, v48, v149
	v_fmac_f32_e32 v6, v48, v150
	v_fmac_f32_e32 v7, v48, v151
	v_fmac_f32_e32 v8, v48, v152
	v_fmac_f32_e32 v9, v48, v153
	v_fmac_f32_e32 v10, v48, v154
	v_fmac_f32_e32 v11, v48, v155
	v_fmac_f32_e32 v12, v48, v156
	v_fmac_f32_e32 v13, v48, v157
	v_fmac_f32_e32 v14, v48, v158
	v_fmac_f32_e32 v15, v48, v159
	v_lshl_add_u32 v161, v32, 7, v160
	global_load_dwordx4 v[80:83], v161, s[14:15]
	s_waitcnt vmcnt(15)
	v_cvt_pk_f32_fp8_e32 v[144:145], v84
	v_cvt_pk_f32_fp8_sdwa v[146:147], v84 src0_sel:WORD_1
	v_cvt_pk_f32_fp8_e32 v[148:149], v85
	v_cvt_pk_f32_fp8_sdwa v[150:151], v85 src0_sel:WORD_1
	v_cvt_pk_f32_fp8_e32 v[152:153], v86
	v_cvt_pk_f32_fp8_sdwa v[154:155], v86 src0_sel:WORD_1
	v_cvt_pk_f32_fp8_e32 v[156:157], v87
	v_cvt_pk_f32_fp8_sdwa v[158:159], v87 src0_sel:WORD_1
	v_fmac_f32_e32 v0, v49, v144
	v_fmac_f32_e32 v1, v49, v145
	v_fmac_f32_e32 v2, v49, v146
	v_fmac_f32_e32 v3, v49, v147
	v_fmac_f32_e32 v4, v49, v148
	v_fmac_f32_e32 v5, v49, v149
	v_fmac_f32_e32 v6, v49, v150
	v_fmac_f32_e32 v7, v49, v151
	v_fmac_f32_e32 v8, v49, v152
	v_fmac_f32_e32 v9, v49, v153
	v_fmac_f32_e32 v10, v49, v154
	v_fmac_f32_e32 v11, v49, v155
	v_fmac_f32_e32 v12, v49, v156
	v_fmac_f32_e32 v13, v49, v157
	v_fmac_f32_e32 v14, v49, v158
	v_fmac_f32_e32 v15, v49, v159
	v_lshl_add_u32 v161, v33, 7, v160
	global_load_dwordx4 v[84:87], v161, s[14:15]
	s_waitcnt vmcnt(15)
; DI void phase_peer_b(const Params& p, int layer, const float* gnext, bool last) {
;     ...
; #pragma unroll
;       for (int j = 0; j < 16; ++j) {
;         const int e = bt * 16 + j;
;         const float wj = __int_as_float(__builtin_amdgcn_readlane(__float_as_int(e < 64 ? w0 : w1), e & 63));
; #pragma unroll
;         for (int w = 0; w < 4; ++w) {
;           const f32x2 lo = __builtin_amdgcn_cvt_pk_f32_fp8((int)vr[j][w], false);
;           const f32x2 hi = __builtin_amdgcn_cvt_pk_f32_fp8((int)vr[j][w], true);
;           acc[4 * w] += wj * lo[0]; acc[4 * w + 1] += wj * lo[1]; acc[4 * w + 2] += wj * hi[0]; acc[4 * w + 3] += wj * hi[1];
;         }
;       }
	v_cvt_pk_f32_fp8_e32 v[144:145], v88
	v_cvt_pk_f32_fp8_sdwa v[146:147], v88 src0_sel:WORD_1
	v_cvt_pk_f32_fp8_e32 v[148:149], v89
	v_cvt_pk_f32_fp8_sdwa v[150:151], v89 src0_sel:WORD_1
	v_cvt_pk_f32_fp8_e32 v[152:153], v90
	v_cvt_pk_f32_fp8_sdwa v[154:155], v90 src0_sel:WORD_1
	v_cvt_pk_f32_fp8_e32 v[156:157], v91
	v_cvt_pk_f32_fp8_sdwa v[158:159], v91 src0_sel:WORD_1
	v_fmac_f32_e32 v0, v50, v144
	v_fmac_f32_e32 v1, v50, v145
	v_fmac_f32_e32 v2, v50, v146
	v_fmac_f32_e32 v3, v50, v147
	v_fmac_f32_e32 v4, v50, v148
	v_fmac_f32_e32 v5, v50, v149
	v_fmac_f32_e32 v6, v50, v150
	v_fmac_f32_e32 v7, v50, v151
	v_fmac_f32_e32 v8, v50, v152
	v_fmac_f32_e32 v9, v50, v153
	v_fmac_f32_e32 v10, v50, v154
	v_fmac_f32_e32 v11, v50, v155
	v_fmac_f32_e32 v12, v50, v156
	v_fmac_f32_e32 v13, v50, v157
	v_fmac_f32_e32 v14, v50, v158
	v_fmac_f32_e32 v15, v50, v159
	v_lshl_add_u32 v161, v34, 7, v160
	global_load_dwordx4 v[88:91], v161, s[14:15]
	s_waitcnt vmcnt(15)
	v_cvt_pk_f32_fp8_e32 v[144:145], v92
	v_cvt_pk_f32_fp8_sdwa v[146:147], v92 src0_sel:WORD_1
	v_cvt_pk_f32_fp8_e32 v[148:149], v93
	v_cvt_pk_f32_fp8_sdwa v[150:151], v93 src0_sel:WORD_1
	v_cvt_pk_f32_fp8_e32 v[152:153], v94
	v_cvt_pk_f32_fp8_sdwa v[154:155], v94 src0_sel:WORD_1
	v_cvt_pk_f32_fp8_e32 v[156:157], v95
	v_cvt_pk_f32_fp8_sdwa v[158:159], v95 src0_sel:WORD_1
	v_fmac_f32_e32 v0, v51, v144
	v_fmac_f32_e32 v1, v51, v145
	v_fmac_f32_e32 v2, v51, v146
	v_fmac_f32_e32 v3, v51, v147
	v_fmac_f32_e32 v4, v51, v148
	v_fmac_f32_e32 v5, v51, v149
	v_fmac_f32_e32 v6, v51, v150
	v_fmac_f32_e32 v7, v51, v151
	v_fmac_f32_e32 v8, v51, v152
	v_fmac_f32_e32 v9, v51, v153
	v_fmac_f32_e32 v10, v51, v154
	v_fmac_f32_e32 v11, v51, v155
	v_fmac_f32_e32 v12, v51, v156
	v_fmac_f32_e32 v13, v51, v157
	v_fmac_f32_e32 v14, v51, v158
	v_fmac_f32_e32 v15, v51, v159
	v_lshl_add_u32 v161, v35, 7, v160
	global_load_dwordx4 v[92:95], v161, s[14:15]
	s_waitcnt vmcnt(15)
	v_cvt_pk_f32_fp8_e32 v[144:145], v96
	v_cvt_pk_f32_fp8_sdwa v[146:147], v96 src0_sel:WORD_1
	v_cvt_pk_f32_fp8_e32 v[148:149], v97
	v_cvt_pk_f32_fp8_sdwa v[150:151], v97 src0_sel:WORD_1
	v_cvt_pk_f32_fp8_e32 v[152:153], v98
	v_cvt_pk_f32_fp8_sdwa v[154:155], v98 src0_sel:WORD_1
	v_cvt_pk_f32_fp8_e32 v[156:157], v99
	v_cvt_pk_f32_fp8_sdwa v[158:159], v99 src0_sel:WORD_1
	v_fmac_f32_e32 v0, v52, v144
	v_fmac_f32_e32 v1, v52, v145
	v_fmac_f32_e32 v2, v52, v146
	v_fmac_f32_e32 v3, v52, v147
	v_fmac_f32_e32 v4, v52, v148
	v_fmac_f32_e32 v5, v52, v149
	v_fmac_f32_e32 v6, v52, v150
	v_fmac_f32_e32 v7, v52, v151
	v_fmac_f32_e32 v8, v52, v152
	v_fmac_f32_e32 v9, v52, v153
	v_fmac_f32_e32 v10, v52, v154
	v_fmac_f32_e32 v11, v52, v155
	v_fmac_f32_e32 v12, v52, v156
	v_fmac_f32_e32 v13, v52, v157
	v_fmac_f32_e32 v14, v52, v158
	v_fmac_f32_e32 v15, v52, v159
	v_lshl_add_u32 v161, v36, 7, v160
	global_load_dwordx4 v[96:99], v161, s[14:15]
	s_waitcnt vmcnt(15)
	v_cvt_pk_f32_fp8_e32 v[144:145], v100
	v_cvt_pk_f32_fp8_sdwa v[146:147], v100 src0_sel:WORD_1
	v_cvt_pk_f32_fp8_e32 v[148:149], v101
	v_cvt_pk_f32_fp8_sdwa v[150:151], v101 src0_sel:WORD_1
	v_cvt_pk_f32_fp8_e32 v[152:153], v102
	v_cvt_pk_f32_fp8_sdwa v[154:155], v102 src0_sel:WORD_1
	v_cvt_pk_f32_fp8_e32 v[156:157], v103
	v_cvt_pk_f32_fp8_sdwa v[158:159], v103 src0_sel:WORD_1
	v_fmac_f32_e32 v0, v53, v144
	v_fmac_f32_e32 v1, v53, v145
	v_fmac_f32_e32 v2, v53, v146
	v_fmac_f32_e32 v3, v53, v147
	v_fmac_f32_e32 v4, v53, v148
	v_fmac_f32_e32 v5, v53, v149
	v_fmac_f32_e32 v6, v53, v150
	v_fmac_f32_e32 v7, v53, v151
	v_fmac_f32_e32 v8, v53, v152
	v_fmac_f32_e32 v9, v53, v153
	v_fmac_f32_e32 v10, v53, v154
	v_fmac_f32_e32 v11, v53, v155
	v_fmac_f32_e32 v12, v53, v156
	v_fmac_f32_e32 v13, v53, v157
	v_fmac_f32_e32 v14, v53, v158
	v_fmac_f32_e32 v15, v53, v159
	v_lshl_add_u32 v161, v37, 7, v160
	global_load_dwordx4 v[100:103], v161, s[14:15]
	s_waitcnt vmcnt(15)
	v_cvt_pk_f32_fp8_e32 v[144:145], v104
	v_cvt_pk_f32_fp8_sdwa v[146:147], v104 src0_sel:WORD_1
	v_cvt_pk_f32_fp8_e32 v[148:149], v105
	v_cvt_pk_f32_fp8_sdwa v[150:151], v105 src0_sel:WORD_1
	v_cvt_pk_f32_fp8_e32 v[152:153], v106
	v_cvt_pk_f32_fp8_sdwa v[154:155], v106 src0_sel:WORD_1
	v_cvt_pk_f32_fp8_e32 v[156:157], v107
	v_cvt_pk_f32_fp8_sdwa v[158:159], v107 src0_sel:WORD_1
	v_fmac_f32_e32 v0, v54, v144
	v_fmac_f32_e32 v1, v54, v145
	v_fmac_f32_e32 v2, v54, v146
	v_fmac_f32_e32 v3, v54, v147
	v_fmac_f32_e32 v4, v54, v148
	v_fmac_f32_e32 v5, v54, v149
	v_fmac_f32_e32 v6, v54, v150
	v_fmac_f32_e32 v7, v54, v151
	v_fmac_f32_e32 v8, v54, v152
	v_fmac_f32_e32 v9, v54, v153
	v_fmac_f32_e32 v10, v54, v154
	v_fmac_f32_e32 v11, v54, v155
	v_fmac_f32_e32 v12, v54, v156
	v_fmac_f32_e32 v13, v54, v157
	v_fmac_f32_e32 v14, v54, v158
	v_fmac_f32_e32 v15, v54, v159
	v_lshl_add_u32 v161, v38, 7, v160
	global_load_dwordx4 v[104:107], v161, s[14:15]
	s_waitcnt vmcnt(15)
	v_cvt_pk_f32_fp8_e32 v[144:145], v108
	v_cvt_pk_f32_fp8_sdwa v[146:147], v108 src0_sel:WORD_1
	v_cvt_pk_f32_fp8_e32 v[148:149], v109
	v_cvt_pk_f32_fp8_sdwa v[150:151], v109 src0_sel:WORD_1
	v_cvt_pk_f32_fp8_e32 v[152:153], v110
	v_cvt_pk_f32_fp8_sdwa v[154:155], v110 src0_sel:WORD_1
	v_cvt_pk_f32_fp8_e32 v[156:157], v111
	v_cvt_pk_f32_fp8_sdwa v[158:159], v111 src0_sel:WORD_1
	v_fmac_f32_e32 v0, v55, v144
	v_fmac_f32_e32 v1, v55, v145
	v_fmac_f32_e32 v2, v55, v146
	v_fmac_f32_e32 v3, v55, v147
	v_fmac_f32_e32 v4, v55, v148
	v_fmac_f32_e32 v5, v55, v149
	v_fmac_f32_e32 v6, v55, v150
	v_fmac_f32_e32 v7, v55, v151
	v_fmac_f32_e32 v8, v55, v152
	v_fmac_f32_e32 v9, v55, v153
	v_fmac_f32_e32 v10, v55, v154
	v_fmac_f32_e32 v11, v55, v155
	v_fmac_f32_e32 v12, v55, v156
	v_fmac_f32_e32 v13, v55, v157
	v_fmac_f32_e32 v14, v55, v158
	v_fmac_f32_e32 v15, v55, v159
	v_lshl_add_u32 v161, v39, 7, v160
	global_load_dwordx4 v[108:111], v161, s[14:15]
	s_waitcnt vmcnt(15)
; DI void phase_peer_b(const Params& p, int layer, const float* gnext, bool last) {
;     ...
; #pragma unroll
;       for (int j = 0; j < 16; ++j) {
;         const int e = bt * 16 + j;
;         const float wj = __int_as_float(__builtin_amdgcn_readlane(__float_as_int(e < 64 ? w0 : w1), e & 63));
; #pragma unroll
;         for (int w = 0; w < 4; ++w) {
;           const f32x2 lo = __builtin_amdgcn_cvt_pk_f32_fp8((int)vr[j][w], false);
;           const f32x2 hi = __builtin_amdgcn_cvt_pk_f32_fp8((int)vr[j][w], true);
;           acc[4 * w] += wj * lo[0]; acc[4 * w + 1] += wj * lo[1]; acc[4 * w + 2] += wj * hi[0]; acc[4 * w + 3] += wj * hi[1];
;         }
;       }
	v_cvt_pk_f32_fp8_e32 v[144:145], v112
	v_cvt_pk_f32_fp8_sdwa v[146:147], v112 src0_sel:WORD_1
	v_cvt_pk_f32_fp8_e32 v[148:149], v113
	v_cvt_pk_f32_fp8_sdwa v[150:151], v113 src0_sel:WORD_1
	v_cvt_pk_f32_fp8_e32 v[152:153], v114
	v_cvt_pk_f32_fp8_sdwa v[154:155], v114 src0_sel:WORD_1
	v_cvt_pk_f32_fp8_e32 v[156:157], v115
	v_cvt_pk_f32_fp8_sdwa v[158:159], v115 src0_sel:WORD_1
	v_fmac_f32_e32 v0, v56, v144
	v_fmac_f32_e32 v1, v56, v145
	v_fmac_f32_e32 v2, v56, v146
	v_fmac_f32_e32 v3, v56, v147
	v_fmac_f32_e32 v4, v56, v148
	v_fmac_f32_e32 v5, v56, v149
	v_fmac_f32_e32 v6, v56, v150
	v_fmac_f32_e32 v7, v56, v151
	v_fmac_f32_e32 v8, v56, v152
	v_fmac_f32_e32 v9, v56, v153
	v_fmac_f32_e32 v10, v56, v154
	v_fmac_f32_e32 v11, v56, v155
	v_fmac_f32_e32 v12, v56, v156
	v_fmac_f32_e32 v13, v56, v157
	v_fmac_f32_e32 v14, v56, v158
	v_fmac_f32_e32 v15, v56, v159
	v_lshl_add_u32 v161, v40, 7, v160
	global_load_dwordx4 v[112:115], v161, s[14:15]
	s_waitcnt vmcnt(15)
	v_cvt_pk_f32_fp8_e32 v[144:145], v116
	v_cvt_pk_f32_fp8_sdwa v[146:147], v116 src0_sel:WORD_1
	v_cvt_pk_f32_fp8_e32 v[148:149], v117
	v_cvt_pk_f32_fp8_sdwa v[150:151], v117 src0_sel:WORD_1
	v_cvt_pk_f32_fp8_e32 v[152:153], v118
	v_cvt_pk_f32_fp8_sdwa v[154:155], v118 src0_sel:WORD_1
	v_cvt_pk_f32_fp8_e32 v[156:157], v119
	v_cvt_pk_f32_fp8_sdwa v[158:159], v119 src0_sel:WORD_1
	v_fmac_f32_e32 v0, v57, v144
	v_fmac_f32_e32 v1, v57, v145
	v_fmac_f32_e32 v2, v57, v146
	v_fmac_f32_e32 v3, v57, v147
	v_fmac_f32_e32 v4, v57, v148
	v_fmac_f32_e32 v5, v57, v149
	v_fmac_f32_e32 v6, v57, v150
	v_fmac_f32_e32 v7, v57, v151
	v_fmac_f32_e32 v8, v57, v152
	v_fmac_f32_e32 v9, v57, v153
	v_fmac_f32_e32 v10, v57, v154
	v_fmac_f32_e32 v11, v57, v155
	v_fmac_f32_e32 v12, v57, v156
	v_fmac_f32_e32 v13, v57, v157
	v_fmac_f32_e32 v14, v57, v158
	v_fmac_f32_e32 v15, v57, v159
	v_lshl_add_u32 v161, v41, 7, v160
	global_load_dwordx4 v[116:119], v161, s[14:15]
	s_waitcnt vmcnt(15)
	v_cvt_pk_f32_fp8_e32 v[144:145], v120
	v_cvt_pk_f32_fp8_sdwa v[146:147], v120 src0_sel:WORD_1
	v_cvt_pk_f32_fp8_e32 v[148:149], v121
	v_cvt_pk_f32_fp8_sdwa v[150:151], v121 src0_sel:WORD_1
	v_cvt_pk_f32_fp8_e32 v[152:153], v122
	v_cvt_pk_f32_fp8_sdwa v[154:155], v122 src0_sel:WORD_1
	v_cvt_pk_f32_fp8_e32 v[156:157], v123
	v_cvt_pk_f32_fp8_sdwa v[158:159], v123 src0_sel:WORD_1
	v_fmac_f32_e32 v0, v58, v144
	v_fmac_f32_e32 v1, v58, v145
	v_fmac_f32_e32 v2, v58, v146
	v_fmac_f32_e32 v3, v58, v147
	v_fmac_f32_e32 v4, v58, v148
	v_fmac_f32_e32 v5, v58, v149
	v_fmac_f32_e32 v6, v58, v150
	v_fmac_f32_e32 v7, v58, v151
	v_fmac_f32_e32 v8, v58, v152
	v_fmac_f32_e32 v9, v58, v153
	v_fmac_f32_e32 v10, v58, v154
	v_fmac_f32_e32 v11, v58, v155
	v_fmac_f32_e32 v12, v58, v156
	v_fmac_f32_e32 v13, v58, v157
	v_fmac_f32_e32 v14, v58, v158
	v_fmac_f32_e32 v15, v58, v159
	v_lshl_add_u32 v161, v42, 7, v160
	global_load_dwordx4 v[120:123], v161, s[14:15]
	s_waitcnt vmcnt(15)
	v_cvt_pk_f32_fp8_e32 v[144:145], v124
	v_cvt_pk_f32_fp8_sdwa v[146:147], v124 src0_sel:WORD_1
	v_cvt_pk_f32_fp8_e32 v[148:149], v125
	v_cvt_pk_f32_fp8_sdwa v[150:151], v125 src0_sel:WORD_1
	v_cvt_pk_f32_fp8_e32 v[152:153], v126
	v_cvt_pk_f32_fp8_sdwa v[154:155], v126 src0_sel:WORD_1
	v_cvt_pk_f32_fp8_e32 v[156:157], v127
	v_cvt_pk_f32_fp8_sdwa v[158:159], v127 src0_sel:WORD_1
	v_fmac_f32_e32 v0, v59, v144
	v_fmac_f32_e32 v1, v59, v145
	v_fmac_f32_e32 v2, v59, v146
	v_fmac_f32_e32 v3, v59, v147
	v_fmac_f32_e32 v4, v59, v148
	v_fmac_f32_e32 v5, v59, v149
	v_fmac_f32_e32 v6, v59, v150
	v_fmac_f32_e32 v7, v59, v151
	v_fmac_f32_e32 v8, v59, v152
	v_fmac_f32_e32 v9, v59, v153
	v_fmac_f32_e32 v10, v59, v154
	v_fmac_f32_e32 v11, v59, v155
	v_fmac_f32_e32 v12, v59, v156
	v_fmac_f32_e32 v13, v59, v157
	v_fmac_f32_e32 v14, v59, v158
	v_fmac_f32_e32 v15, v59, v159
	v_lshl_add_u32 v161, v43, 7, v160
	global_load_dwordx4 v[124:127], v161, s[14:15]
	s_waitcnt vmcnt(15)
	v_cvt_pk_f32_fp8_e32 v[144:145], v128
	v_cvt_pk_f32_fp8_sdwa v[146:147], v128 src0_sel:WORD_1
	v_cvt_pk_f32_fp8_e32 v[148:149], v129
	v_cvt_pk_f32_fp8_sdwa v[150:151], v129 src0_sel:WORD_1
	v_cvt_pk_f32_fp8_e32 v[152:153], v130
	v_cvt_pk_f32_fp8_sdwa v[154:155], v130 src0_sel:WORD_1
	v_cvt_pk_f32_fp8_e32 v[156:157], v131
	v_cvt_pk_f32_fp8_sdwa v[158:159], v131 src0_sel:WORD_1
	v_fmac_f32_e32 v0, v60, v144
	v_fmac_f32_e32 v1, v60, v145
	v_fmac_f32_e32 v2, v60, v146
	v_fmac_f32_e32 v3, v60, v147
	v_fmac_f32_e32 v4, v60, v148
	v_fmac_f32_e32 v5, v60, v149
	v_fmac_f32_e32 v6, v60, v150
	v_fmac_f32_e32 v7, v60, v151
	v_fmac_f32_e32 v8, v60, v152
	v_fmac_f32_e32 v9, v60, v153
	v_fmac_f32_e32 v10, v60, v154
	v_fmac_f32_e32 v11, v60, v155
	v_fmac_f32_e32 v12, v60, v156
	v_fmac_f32_e32 v13, v60, v157
	v_fmac_f32_e32 v14, v60, v158
	v_fmac_f32_e32 v15, v60, v159
	v_lshl_add_u32 v161, v44, 7, v160
	global_load_dwordx4 v[128:131], v161, s[14:15]
	s_waitcnt vmcnt(15)
	v_cvt_pk_f32_fp8_e32 v[144:145], v132
	v_cvt_pk_f32_fp8_sdwa v[146:147], v132 src0_sel:WORD_1
	v_cvt_pk_f32_fp8_e32 v[148:149], v133
	v_cvt_pk_f32_fp8_sdwa v[150:151], v133 src0_sel:WORD_1
	v_cvt_pk_f32_fp8_e32 v[152:153], v134
	v_cvt_pk_f32_fp8_sdwa v[154:155], v134 src0_sel:WORD_1
	v_cvt_pk_f32_fp8_e32 v[156:157], v135
	v_cvt_pk_f32_fp8_sdwa v[158:159], v135 src0_sel:WORD_1
	v_fmac_f32_e32 v0, v61, v144
	v_fmac_f32_e32 v1, v61, v145
	v_fmac_f32_e32 v2, v61, v146
	v_fmac_f32_e32 v3, v61, v147
	v_fmac_f32_e32 v4, v61, v148
	v_fmac_f32_e32 v5, v61, v149
	v_fmac_f32_e32 v6, v61, v150
	v_fmac_f32_e32 v7, v61, v151
	v_fmac_f32_e32 v8, v61, v152
	v_fmac_f32_e32 v9, v61, v153
	v_fmac_f32_e32 v10, v61, v154
	v_fmac_f32_e32 v11, v61, v155
	v_fmac_f32_e32 v12, v61, v156
	v_fmac_f32_e32 v13, v61, v157
	v_fmac_f32_e32 v14, v61, v158
	v_fmac_f32_e32 v15, v61, v159
	v_lshl_add_u32 v161, v45, 7, v160
	global_load_dwordx4 v[132:135], v161, s[14:15]
	s_waitcnt vmcnt(15)
; DI void phase_peer_b(const Params& p, int layer, const float* gnext, bool last) {
;     ...
;     const int i0 = ibuf[row * 128 + lane], i1 = ibuf[row * 128 + 64 + lane];
;     const float w0 = wbuf[row * 128 + lane], w1 = wbuf[row * 128 + 64 + lane];
;     ...
; #pragma unroll
;       for (int j = 0; j < 16; ++j) {
;         const int e = bt * 16 + j;
;         const float wj = __int_as_float(__builtin_amdgcn_readlane(__float_as_int(e < 64 ? w0 : w1), e & 63));
; #pragma unroll
;         for (int w = 0; w < 4; ++w) {
;           const f32x2 lo = __builtin_amdgcn_cvt_pk_f32_fp8((int)vr[j][w], false);
;           const f32x2 hi = __builtin_amdgcn_cvt_pk_f32_fp8((int)vr[j][w], true);
;           acc[4 * w] += wj * lo[0]; acc[4 * w + 1] += wj * lo[1]; acc[4 * w + 2] += wj * hi[0]; acc[4 * w + 3] += wj * hi[1];
;         }
;       }
;     }
;       float* hp = hbuf + row * DM;
;       float hn[16];
; #pragma unroll
;       for (int q = 0; q < 2; ++q) {
;         const float4 a = *(const float4*)(hp + lane * 16 + q * 8);
;         const float4 bq = *(const float4*)(hp + lane * 16 + q * 8 + 4);
	v_cvt_pk_f32_fp8_e32 v[144:145], v136
	v_cvt_pk_f32_fp8_sdwa v[146:147], v136 src0_sel:WORD_1
	v_cvt_pk_f32_fp8_e32 v[148:149], v137
	v_cvt_pk_f32_fp8_sdwa v[150:151], v137 src0_sel:WORD_1
	v_cvt_pk_f32_fp8_e32 v[152:153], v138
	v_cvt_pk_f32_fp8_sdwa v[154:155], v138 src0_sel:WORD_1
	v_cvt_pk_f32_fp8_e32 v[156:157], v139
	v_cvt_pk_f32_fp8_sdwa v[158:159], v139 src0_sel:WORD_1
	v_fmac_f32_e32 v0, v62, v144
	v_fmac_f32_e32 v1, v62, v145
	v_fmac_f32_e32 v2, v62, v146
	v_fmac_f32_e32 v3, v62, v147
	v_fmac_f32_e32 v4, v62, v148
	v_fmac_f32_e32 v5, v62, v149
	v_fmac_f32_e32 v6, v62, v150
	v_fmac_f32_e32 v7, v62, v151
	v_fmac_f32_e32 v8, v62, v152
	v_fmac_f32_e32 v9, v62, v153
	v_fmac_f32_e32 v10, v62, v154
	v_fmac_f32_e32 v11, v62, v155
	v_fmac_f32_e32 v12, v62, v156
	v_fmac_f32_e32 v13, v62, v157
	v_fmac_f32_e32 v14, v62, v158
	v_fmac_f32_e32 v15, v62, v159
	v_lshl_add_u32 v161, v46, 7, v160
	global_load_dwordx4 v[136:139], v161, s[14:15]
	s_waitcnt vmcnt(15)
	v_cvt_pk_f32_fp8_e32 v[144:145], v140
	v_cvt_pk_f32_fp8_sdwa v[146:147], v140 src0_sel:WORD_1
	v_cvt_pk_f32_fp8_e32 v[148:149], v141
	v_cvt_pk_f32_fp8_sdwa v[150:151], v141 src0_sel:WORD_1
	v_cvt_pk_f32_fp8_e32 v[152:153], v142
	v_cvt_pk_f32_fp8_sdwa v[154:155], v142 src0_sel:WORD_1
	v_cvt_pk_f32_fp8_e32 v[156:157], v143
	v_cvt_pk_f32_fp8_sdwa v[158:159], v143 src0_sel:WORD_1
	v_fmac_f32_e32 v0, v63, v144
	v_fmac_f32_e32 v1, v63, v145
	v_fmac_f32_e32 v2, v63, v146
	v_fmac_f32_e32 v3, v63, v147
	v_fmac_f32_e32 v4, v63, v148
	v_fmac_f32_e32 v5, v63, v149
	v_fmac_f32_e32 v6, v63, v150
	v_fmac_f32_e32 v7, v63, v151
	v_fmac_f32_e32 v8, v63, v152
	v_fmac_f32_e32 v9, v63, v153
	v_fmac_f32_e32 v10, v63, v154
	v_fmac_f32_e32 v11, v63, v155
	v_fmac_f32_e32 v12, v63, v156
	v_fmac_f32_e32 v13, v63, v157
	v_fmac_f32_e32 v14, v63, v158
	v_fmac_f32_e32 v15, v63, v159
	v_lshl_add_u32 v161, v47, 7, v160
	global_load_dwordx4 v[140:143], v161, s[14:15]
	s_waitcnt lgkmcnt(0)
	global_load_dwordx4 v[48:51], v164, s[20:21] offset:0
	global_load_dwordx4 v[52:55], v164, s[20:21] offset:16
	global_load_dwordx4 v[56:59], v164, s[20:21] offset:32
	global_load_dwordx4 v[60:63], v164, s[20:21] offset:48
	s_add_u32 s24, s22, s23
	s_min_u32 s24, s24, 0x200f
	s_lshl_b32 s24, s24, 12
	s_mov_b32 s25, 0
	v_lshl_add_u64 v[170:171], v[168:169], 0, s[24:25]
	global_load_dwordx4 v[16:19], v[170:171], off offset:0
	global_load_dwordx4 v[20:23], v[170:171], off offset:512
	global_load_dwordx4 v[24:27], v[170:171], off offset:1024
	global_load_dwordx4 v[28:31], v[170:171], off offset:1536
	global_load_dwordx4 v[32:35], v[170:171], off offset:2048
	global_load_dwordx4 v[36:39], v[170:171], off offset:2560
	global_load_dwordx4 v[40:43], v[170:171], off offset:3072
	global_load_dwordx4 v[44:47], v[170:171], off offset:3584
	s_waitcnt vmcnt(27)
	v_cvt_pk_f32_fp8_e32 v[144:145], v80
	v_cvt_pk_f32_fp8_sdwa v[146:147], v80 src0_sel:WORD_1
	v_cvt_pk_f32_fp8_e32 v[148:149], v81
	v_cvt_pk_f32_fp8_sdwa v[150:151], v81 src0_sel:WORD_1
	v_cvt_pk_f32_fp8_e32 v[152:153], v82
	v_cvt_pk_f32_fp8_sdwa v[154:155], v82 src0_sel:WORD_1
	v_cvt_pk_f32_fp8_e32 v[156:157], v83
	v_cvt_pk_f32_fp8_sdwa v[158:159], v83 src0_sel:WORD_1
	v_fmac_f32_e32 v0, v64, v144
	v_fmac_f32_e32 v1, v64, v145
	v_fmac_f32_e32 v2, v64, v146
	v_fmac_f32_e32 v3, v64, v147
	v_fmac_f32_e32 v4, v64, v148
	v_fmac_f32_e32 v5, v64, v149
	v_fmac_f32_e32 v6, v64, v150
	v_fmac_f32_e32 v7, v64, v151
	v_fmac_f32_e32 v8, v64, v152
	v_fmac_f32_e32 v9, v64, v153
	v_fmac_f32_e32 v10, v64, v154
	v_fmac_f32_e32 v11, v64, v155
	v_fmac_f32_e32 v12, v64, v156
	v_fmac_f32_e32 v13, v64, v157
	v_fmac_f32_e32 v14, v64, v158
	v_fmac_f32_e32 v15, v64, v159
	s_waitcnt vmcnt(26)
	v_cvt_pk_f32_fp8_e32 v[144:145], v84
	v_cvt_pk_f32_fp8_sdwa v[146:147], v84 src0_sel:WORD_1
	v_cvt_pk_f32_fp8_e32 v[148:149], v85
	v_cvt_pk_f32_fp8_sdwa v[150:151], v85 src0_sel:WORD_1
	v_cvt_pk_f32_fp8_e32 v[152:153], v86
	v_cvt_pk_f32_fp8_sdwa v[154:155], v86 src0_sel:WORD_1
	v_cvt_pk_f32_fp8_e32 v[156:157], v87
	v_cvt_pk_f32_fp8_sdwa v[158:159], v87 src0_sel:WORD_1
	v_fmac_f32_e32 v0, v65, v144
	v_fmac_f32_e32 v1, v65, v145
	v_fmac_f32_e32 v2, v65, v146
	v_fmac_f32_e32 v3, v65, v147
	v_fmac_f32_e32 v4, v65, v148
	v_fmac_f32_e32 v5, v65, v149
	v_fmac_f32_e32 v6, v65, v150
	v_fmac_f32_e32 v7, v65, v151
	v_fmac_f32_e32 v8, v65, v152
	v_fmac_f32_e32 v9, v65, v153
	v_fmac_f32_e32 v10, v65, v154
	v_fmac_f32_e32 v11, v65, v155
	v_fmac_f32_e32 v12, v65, v156
	v_fmac_f32_e32 v13, v65, v157
	v_fmac_f32_e32 v14, v65, v158
	v_fmac_f32_e32 v15, v65, v159
	s_waitcnt vmcnt(25)
	v_cvt_pk_f32_fp8_e32 v[144:145], v88
	v_cvt_pk_f32_fp8_sdwa v[146:147], v88 src0_sel:WORD_1
	v_cvt_pk_f32_fp8_e32 v[148:149], v89
	v_cvt_pk_f32_fp8_sdwa v[150:151], v89 src0_sel:WORD_1
	v_cvt_pk_f32_fp8_e32 v[152:153], v90
	v_cvt_pk_f32_fp8_sdwa v[154:155], v90 src0_sel:WORD_1
	v_cvt_pk_f32_fp8_e32 v[156:157], v91
	v_cvt_pk_f32_fp8_sdwa v[158:159], v91 src0_sel:WORD_1
	v_fmac_f32_e32 v0, v66, v144
	v_fmac_f32_e32 v1, v66, v145
	v_fmac_f32_e32 v2, v66, v146
	v_fmac_f32_e32 v3, v66, v147
	v_fmac_f32_e32 v4, v66, v148
	v_fmac_f32_e32 v5, v66, v149
	v_fmac_f32_e32 v6, v66, v150
	v_fmac_f32_e32 v7, v66, v151
	v_fmac_f32_e32 v8, v66, v152
	v_fmac_f32_e32 v9, v66, v153
	v_fmac_f32_e32 v10, v66, v154
	v_fmac_f32_e32 v11, v66, v155
	v_fmac_f32_e32 v12, v66, v156
	v_fmac_f32_e32 v13, v66, v157
	v_fmac_f32_e32 v14, v66, v158
	v_fmac_f32_e32 v15, v66, v159
	s_waitcnt vmcnt(24)
; DI void phase_peer_b(const Params& p, int layer, const float* gnext, bool last) {
;     ...
; #pragma unroll
;       for (int j = 0; j < 16; ++j) {
;         const int e = bt * 16 + j;
;         const float wj = __int_as_float(__builtin_amdgcn_readlane(__float_as_int(e < 64 ? w0 : w1), e & 63));
; #pragma unroll
;         for (int w = 0; w < 4; ++w) {
;           const f32x2 lo = __builtin_amdgcn_cvt_pk_f32_fp8((int)vr[j][w], false);
;           const f32x2 hi = __builtin_amdgcn_cvt_pk_f32_fp8((int)vr[j][w], true);
;           acc[4 * w] += wj * lo[0]; acc[4 * w + 1] += wj * lo[1]; acc[4 * w + 2] += wj * hi[0]; acc[4 * w + 3] += wj * hi[1];
;         }
;       }
	v_cvt_pk_f32_fp8_e32 v[144:145], v92
	v_cvt_pk_f32_fp8_sdwa v[146:147], v92 src0_sel:WORD_1
	v_cvt_pk_f32_fp8_e32 v[148:149], v93
	v_cvt_pk_f32_fp8_sdwa v[150:151], v93 src0_sel:WORD_1
	v_cvt_pk_f32_fp8_e32 v[152:153], v94
	v_cvt_pk_f32_fp8_sdwa v[154:155], v94 src0_sel:WORD_1
	v_cvt_pk_f32_fp8_e32 v[156:157], v95
	v_cvt_pk_f32_fp8_sdwa v[158:159], v95 src0_sel:WORD_1
	v_fmac_f32_e32 v0, v67, v144
	v_fmac_f32_e32 v1, v67, v145
	v_fmac_f32_e32 v2, v67, v146
	v_fmac_f32_e32 v3, v67, v147
	v_fmac_f32_e32 v4, v67, v148
	v_fmac_f32_e32 v5, v67, v149
	v_fmac_f32_e32 v6, v67, v150
	v_fmac_f32_e32 v7, v67, v151
	v_fmac_f32_e32 v8, v67, v152
	v_fmac_f32_e32 v9, v67, v153
	v_fmac_f32_e32 v10, v67, v154
	v_fmac_f32_e32 v11, v67, v155
	v_fmac_f32_e32 v12, v67, v156
	v_fmac_f32_e32 v13, v67, v157
	v_fmac_f32_e32 v14, v67, v158
	v_fmac_f32_e32 v15, v67, v159
	s_waitcnt vmcnt(23)
	v_cvt_pk_f32_fp8_e32 v[144:145], v96
	v_cvt_pk_f32_fp8_sdwa v[146:147], v96 src0_sel:WORD_1
	v_cvt_pk_f32_fp8_e32 v[148:149], v97
	v_cvt_pk_f32_fp8_sdwa v[150:151], v97 src0_sel:WORD_1
	v_cvt_pk_f32_fp8_e32 v[152:153], v98
	v_cvt_pk_f32_fp8_sdwa v[154:155], v98 src0_sel:WORD_1
	v_cvt_pk_f32_fp8_e32 v[156:157], v99
	v_cvt_pk_f32_fp8_sdwa v[158:159], v99 src0_sel:WORD_1
	v_fmac_f32_e32 v0, v68, v144
	v_fmac_f32_e32 v1, v68, v145
	v_fmac_f32_e32 v2, v68, v146
	v_fmac_f32_e32 v3, v68, v147
	v_fmac_f32_e32 v4, v68, v148
	v_fmac_f32_e32 v5, v68, v149
	v_fmac_f32_e32 v6, v68, v150
	v_fmac_f32_e32 v7, v68, v151
	v_fmac_f32_e32 v8, v68, v152
	v_fmac_f32_e32 v9, v68, v153
	v_fmac_f32_e32 v10, v68, v154
	v_fmac_f32_e32 v11, v68, v155
	v_fmac_f32_e32 v12, v68, v156
	v_fmac_f32_e32 v13, v68, v157
	v_fmac_f32_e32 v14, v68, v158
	v_fmac_f32_e32 v15, v68, v159
	s_waitcnt vmcnt(22)
	v_cvt_pk_f32_fp8_e32 v[144:145], v100
	v_cvt_pk_f32_fp8_sdwa v[146:147], v100 src0_sel:WORD_1
	v_cvt_pk_f32_fp8_e32 v[148:149], v101
	v_cvt_pk_f32_fp8_sdwa v[150:151], v101 src0_sel:WORD_1
	v_cvt_pk_f32_fp8_e32 v[152:153], v102
	v_cvt_pk_f32_fp8_sdwa v[154:155], v102 src0_sel:WORD_1
	v_cvt_pk_f32_fp8_e32 v[156:157], v103
	v_cvt_pk_f32_fp8_sdwa v[158:159], v103 src0_sel:WORD_1
	v_fmac_f32_e32 v0, v69, v144
	v_fmac_f32_e32 v1, v69, v145
	v_fmac_f32_e32 v2, v69, v146
	v_fmac_f32_e32 v3, v69, v147
	v_fmac_f32_e32 v4, v69, v148
	v_fmac_f32_e32 v5, v69, v149
	v_fmac_f32_e32 v6, v69, v150
	v_fmac_f32_e32 v7, v69, v151
	v_fmac_f32_e32 v8, v69, v152
	v_fmac_f32_e32 v9, v69, v153
	v_fmac_f32_e32 v10, v69, v154
	v_fmac_f32_e32 v11, v69, v155
	v_fmac_f32_e32 v12, v69, v156
	v_fmac_f32_e32 v13, v69, v157
	v_fmac_f32_e32 v14, v69, v158
	v_fmac_f32_e32 v15, v69, v159
	s_waitcnt vmcnt(21)
	v_cvt_pk_f32_fp8_e32 v[144:145], v104
	v_cvt_pk_f32_fp8_sdwa v[146:147], v104 src0_sel:WORD_1
	v_cvt_pk_f32_fp8_e32 v[148:149], v105
	v_cvt_pk_f32_fp8_sdwa v[150:151], v105 src0_sel:WORD_1
	v_cvt_pk_f32_fp8_e32 v[152:153], v106
	v_cvt_pk_f32_fp8_sdwa v[154:155], v106 src0_sel:WORD_1
	v_cvt_pk_f32_fp8_e32 v[156:157], v107
	v_cvt_pk_f32_fp8_sdwa v[158:159], v107 src0_sel:WORD_1
	v_fmac_f32_e32 v0, v70, v144
	v_fmac_f32_e32 v1, v70, v145
	v_fmac_f32_e32 v2, v70, v146
	v_fmac_f32_e32 v3, v70, v147
	v_fmac_f32_e32 v4, v70, v148
	v_fmac_f32_e32 v5, v70, v149
	v_fmac_f32_e32 v6, v70, v150
	v_fmac_f32_e32 v7, v70, v151
	v_fmac_f32_e32 v8, v70, v152
	v_fmac_f32_e32 v9, v70, v153
	v_fmac_f32_e32 v10, v70, v154
	v_fmac_f32_e32 v11, v70, v155
	v_fmac_f32_e32 v12, v70, v156
	v_fmac_f32_e32 v13, v70, v157
	v_fmac_f32_e32 v14, v70, v158
	v_fmac_f32_e32 v15, v70, v159
	s_waitcnt vmcnt(20)
	v_cvt_pk_f32_fp8_e32 v[144:145], v108
	v_cvt_pk_f32_fp8_sdwa v[146:147], v108 src0_sel:WORD_1
	v_cvt_pk_f32_fp8_e32 v[148:149], v109
	v_cvt_pk_f32_fp8_sdwa v[150:151], v109 src0_sel:WORD_1
	v_cvt_pk_f32_fp8_e32 v[152:153], v110
	v_cvt_pk_f32_fp8_sdwa v[154:155], v110 src0_sel:WORD_1
	v_cvt_pk_f32_fp8_e32 v[156:157], v111
	v_cvt_pk_f32_fp8_sdwa v[158:159], v111 src0_sel:WORD_1
	v_fmac_f32_e32 v0, v71, v144
	v_fmac_f32_e32 v1, v71, v145
	v_fmac_f32_e32 v2, v71, v146
	v_fmac_f32_e32 v3, v71, v147
	v_fmac_f32_e32 v4, v71, v148
	v_fmac_f32_e32 v5, v71, v149
	v_fmac_f32_e32 v6, v71, v150
	v_fmac_f32_e32 v7, v71, v151
	v_fmac_f32_e32 v8, v71, v152
	v_fmac_f32_e32 v9, v71, v153
	v_fmac_f32_e32 v10, v71, v154
	v_fmac_f32_e32 v11, v71, v155
	v_fmac_f32_e32 v12, v71, v156
	v_fmac_f32_e32 v13, v71, v157
	v_fmac_f32_e32 v14, v71, v158
	v_fmac_f32_e32 v15, v71, v159
	s_waitcnt vmcnt(19)
	v_cvt_pk_f32_fp8_e32 v[144:145], v112
	v_cvt_pk_f32_fp8_sdwa v[146:147], v112 src0_sel:WORD_1
	v_cvt_pk_f32_fp8_e32 v[148:149], v113
	v_cvt_pk_f32_fp8_sdwa v[150:151], v113 src0_sel:WORD_1
	v_cvt_pk_f32_fp8_e32 v[152:153], v114
	v_cvt_pk_f32_fp8_sdwa v[154:155], v114 src0_sel:WORD_1
	v_cvt_pk_f32_fp8_e32 v[156:157], v115
	v_cvt_pk_f32_fp8_sdwa v[158:159], v115 src0_sel:WORD_1
	v_fmac_f32_e32 v0, v72, v144
	v_fmac_f32_e32 v1, v72, v145
	v_fmac_f32_e32 v2, v72, v146
	v_fmac_f32_e32 v3, v72, v147
	v_fmac_f32_e32 v4, v72, v148
	v_fmac_f32_e32 v5, v72, v149
	v_fmac_f32_e32 v6, v72, v150
	v_fmac_f32_e32 v7, v72, v151
	v_fmac_f32_e32 v8, v72, v152
	v_fmac_f32_e32 v9, v72, v153
	v_fmac_f32_e32 v10, v72, v154
	v_fmac_f32_e32 v11, v72, v155
	v_fmac_f32_e32 v12, v72, v156
	v_fmac_f32_e32 v13, v72, v157
	v_fmac_f32_e32 v14, v72, v158
	v_fmac_f32_e32 v15, v72, v159
	s_waitcnt vmcnt(18)
; DI void phase_peer_b(const Params& p, int layer, const float* gnext, bool last) {
;     ...
; #pragma unroll
;       for (int j = 0; j < 16; ++j) {
;         const int e = bt * 16 + j;
;         const float wj = __int_as_float(__builtin_amdgcn_readlane(__float_as_int(e < 64 ? w0 : w1), e & 63));
; #pragma unroll
;         for (int w = 0; w < 4; ++w) {
;           const f32x2 lo = __builtin_amdgcn_cvt_pk_f32_fp8((int)vr[j][w], false);
;           const f32x2 hi = __builtin_amdgcn_cvt_pk_f32_fp8((int)vr[j][w], true);
;           acc[4 * w] += wj * lo[0]; acc[4 * w + 1] += wj * lo[1]; acc[4 * w + 2] += wj * hi[0]; acc[4 * w + 3] += wj * hi[1];
;         }
;       }
;     }
;       float* hp = hbuf + row * DM;
;       float hn[16];
; #pragma unroll
;       for (int q = 0; q < 2; ++q) {
;         const float4 a = *(const float4*)(hp + lane * 16 + q * 8);
;         const float4 bq = *(const float4*)(hp + lane * 16 + q * 8 + 4);
;         hn[q * 8 + 0] = a.x + acc[q * 8 + 0]; hn[q * 8 + 1] = a.y + acc[q * 8 + 1]; hn[q * 8 + 2] = a.z + acc[q * 8 + 2]; hn[q * 8 + 3] = a.w + acc[q * 8 + 3];
;         hn[q * 8 + 4] = bq.x + acc[q * 8 + 4]; hn[q * 8 + 5] = bq.y + acc[q * 8 + 5]; hn[q * 8 + 6] = bq.z + acc[q * 8 + 6]; hn[q * 8 + 7] = bq.w + acc[q * 8 + 7];
;       }
	v_cvt_pk_f32_fp8_e32 v[144:145], v116
	v_cvt_pk_f32_fp8_sdwa v[146:147], v116 src0_sel:WORD_1
	v_cvt_pk_f32_fp8_e32 v[148:149], v117
	v_cvt_pk_f32_fp8_sdwa v[150:151], v117 src0_sel:WORD_1
	v_cvt_pk_f32_fp8_e32 v[152:153], v118
	v_cvt_pk_f32_fp8_sdwa v[154:155], v118 src0_sel:WORD_1
	v_cvt_pk_f32_fp8_e32 v[156:157], v119
	v_cvt_pk_f32_fp8_sdwa v[158:159], v119 src0_sel:WORD_1
	v_fmac_f32_e32 v0, v73, v144
	v_fmac_f32_e32 v1, v73, v145
	v_fmac_f32_e32 v2, v73, v146
	v_fmac_f32_e32 v3, v73, v147
	v_fmac_f32_e32 v4, v73, v148
	v_fmac_f32_e32 v5, v73, v149
	v_fmac_f32_e32 v6, v73, v150
	v_fmac_f32_e32 v7, v73, v151
	v_fmac_f32_e32 v8, v73, v152
	v_fmac_f32_e32 v9, v73, v153
	v_fmac_f32_e32 v10, v73, v154
	v_fmac_f32_e32 v11, v73, v155
	v_fmac_f32_e32 v12, v73, v156
	v_fmac_f32_e32 v13, v73, v157
	v_fmac_f32_e32 v14, v73, v158
	v_fmac_f32_e32 v15, v73, v159
	s_waitcnt vmcnt(17)
	v_cvt_pk_f32_fp8_e32 v[144:145], v120
	v_cvt_pk_f32_fp8_sdwa v[146:147], v120 src0_sel:WORD_1
	v_cvt_pk_f32_fp8_e32 v[148:149], v121
	v_cvt_pk_f32_fp8_sdwa v[150:151], v121 src0_sel:WORD_1
	v_cvt_pk_f32_fp8_e32 v[152:153], v122
	v_cvt_pk_f32_fp8_sdwa v[154:155], v122 src0_sel:WORD_1
	v_cvt_pk_f32_fp8_e32 v[156:157], v123
	v_cvt_pk_f32_fp8_sdwa v[158:159], v123 src0_sel:WORD_1
	v_fmac_f32_e32 v0, v74, v144
	v_fmac_f32_e32 v1, v74, v145
	v_fmac_f32_e32 v2, v74, v146
	v_fmac_f32_e32 v3, v74, v147
	v_fmac_f32_e32 v4, v74, v148
	v_fmac_f32_e32 v5, v74, v149
	v_fmac_f32_e32 v6, v74, v150
	v_fmac_f32_e32 v7, v74, v151
	v_fmac_f32_e32 v8, v74, v152
	v_fmac_f32_e32 v9, v74, v153
	v_fmac_f32_e32 v10, v74, v154
	v_fmac_f32_e32 v11, v74, v155
	v_fmac_f32_e32 v12, v74, v156
	v_fmac_f32_e32 v13, v74, v157
	v_fmac_f32_e32 v14, v74, v158
	v_fmac_f32_e32 v15, v74, v159
	s_waitcnt vmcnt(16)
	v_cvt_pk_f32_fp8_e32 v[144:145], v124
	v_cvt_pk_f32_fp8_sdwa v[146:147], v124 src0_sel:WORD_1
	v_cvt_pk_f32_fp8_e32 v[148:149], v125
	v_cvt_pk_f32_fp8_sdwa v[150:151], v125 src0_sel:WORD_1
	v_cvt_pk_f32_fp8_e32 v[152:153], v126
	v_cvt_pk_f32_fp8_sdwa v[154:155], v126 src0_sel:WORD_1
	v_cvt_pk_f32_fp8_e32 v[156:157], v127
	v_cvt_pk_f32_fp8_sdwa v[158:159], v127 src0_sel:WORD_1
	v_fmac_f32_e32 v0, v75, v144
	v_fmac_f32_e32 v1, v75, v145
	v_fmac_f32_e32 v2, v75, v146
	v_fmac_f32_e32 v3, v75, v147
	v_fmac_f32_e32 v4, v75, v148
	v_fmac_f32_e32 v5, v75, v149
	v_fmac_f32_e32 v6, v75, v150
	v_fmac_f32_e32 v7, v75, v151
	v_fmac_f32_e32 v8, v75, v152
	v_fmac_f32_e32 v9, v75, v153
	v_fmac_f32_e32 v10, v75, v154
	v_fmac_f32_e32 v11, v75, v155
	v_fmac_f32_e32 v12, v75, v156
	v_fmac_f32_e32 v13, v75, v157
	v_fmac_f32_e32 v14, v75, v158
	v_fmac_f32_e32 v15, v75, v159
	s_waitcnt vmcnt(15)
	v_cvt_pk_f32_fp8_e32 v[144:145], v128
	v_cvt_pk_f32_fp8_sdwa v[146:147], v128 src0_sel:WORD_1
	v_cvt_pk_f32_fp8_e32 v[148:149], v129
	v_cvt_pk_f32_fp8_sdwa v[150:151], v129 src0_sel:WORD_1
	v_cvt_pk_f32_fp8_e32 v[152:153], v130
	v_cvt_pk_f32_fp8_sdwa v[154:155], v130 src0_sel:WORD_1
	v_cvt_pk_f32_fp8_e32 v[156:157], v131
	v_cvt_pk_f32_fp8_sdwa v[158:159], v131 src0_sel:WORD_1
	v_fmac_f32_e32 v0, v76, v144
	v_fmac_f32_e32 v1, v76, v145
	v_fmac_f32_e32 v2, v76, v146
	v_fmac_f32_e32 v3, v76, v147
	v_fmac_f32_e32 v4, v76, v148
	v_fmac_f32_e32 v5, v76, v149
	v_fmac_f32_e32 v6, v76, v150
	v_fmac_f32_e32 v7, v76, v151
	v_fmac_f32_e32 v8, v76, v152
	v_fmac_f32_e32 v9, v76, v153
	v_fmac_f32_e32 v10, v76, v154
	v_fmac_f32_e32 v11, v76, v155
	v_fmac_f32_e32 v12, v76, v156
	v_fmac_f32_e32 v13, v76, v157
	v_fmac_f32_e32 v14, v76, v158
	v_fmac_f32_e32 v15, v76, v159
	s_waitcnt vmcnt(14)
	v_cvt_pk_f32_fp8_e32 v[144:145], v132
	v_cvt_pk_f32_fp8_sdwa v[146:147], v132 src0_sel:WORD_1
	v_cvt_pk_f32_fp8_e32 v[148:149], v133
	v_cvt_pk_f32_fp8_sdwa v[150:151], v133 src0_sel:WORD_1
	v_cvt_pk_f32_fp8_e32 v[152:153], v134
	v_cvt_pk_f32_fp8_sdwa v[154:155], v134 src0_sel:WORD_1
	v_cvt_pk_f32_fp8_e32 v[156:157], v135
	v_cvt_pk_f32_fp8_sdwa v[158:159], v135 src0_sel:WORD_1
	v_fmac_f32_e32 v0, v77, v144
	v_fmac_f32_e32 v1, v77, v145
	v_fmac_f32_e32 v2, v77, v146
	v_fmac_f32_e32 v3, v77, v147
	v_fmac_f32_e32 v4, v77, v148
	v_fmac_f32_e32 v5, v77, v149
	v_fmac_f32_e32 v6, v77, v150
	v_fmac_f32_e32 v7, v77, v151
	v_fmac_f32_e32 v8, v77, v152
	v_fmac_f32_e32 v9, v77, v153
	v_fmac_f32_e32 v10, v77, v154
	v_fmac_f32_e32 v11, v77, v155
	v_fmac_f32_e32 v12, v77, v156
	v_fmac_f32_e32 v13, v77, v157
	v_fmac_f32_e32 v14, v77, v158
	v_fmac_f32_e32 v15, v77, v159
	s_waitcnt vmcnt(13)
	v_cvt_pk_f32_fp8_e32 v[144:145], v136
	v_cvt_pk_f32_fp8_sdwa v[146:147], v136 src0_sel:WORD_1
	v_cvt_pk_f32_fp8_e32 v[148:149], v137
	v_cvt_pk_f32_fp8_sdwa v[150:151], v137 src0_sel:WORD_1
	v_cvt_pk_f32_fp8_e32 v[152:153], v138
	v_cvt_pk_f32_fp8_sdwa v[154:155], v138 src0_sel:WORD_1
	v_cvt_pk_f32_fp8_e32 v[156:157], v139
	v_cvt_pk_f32_fp8_sdwa v[158:159], v139 src0_sel:WORD_1
	v_fmac_f32_e32 v0, v78, v144
	v_fmac_f32_e32 v1, v78, v145
	v_fmac_f32_e32 v2, v78, v146
	v_fmac_f32_e32 v3, v78, v147
	v_fmac_f32_e32 v4, v78, v148
	v_fmac_f32_e32 v5, v78, v149
	v_fmac_f32_e32 v6, v78, v150
	v_fmac_f32_e32 v7, v78, v151
	v_fmac_f32_e32 v8, v78, v152
	v_fmac_f32_e32 v9, v78, v153
	v_fmac_f32_e32 v10, v78, v154
	v_fmac_f32_e32 v11, v78, v155
	v_fmac_f32_e32 v12, v78, v156
	v_fmac_f32_e32 v13, v78, v157
	v_fmac_f32_e32 v14, v78, v158
	v_fmac_f32_e32 v15, v78, v159
	s_waitcnt vmcnt(12)
	v_cvt_pk_f32_fp8_e32 v[144:145], v140
	v_cvt_pk_f32_fp8_sdwa v[146:147], v140 src0_sel:WORD_1
	v_cvt_pk_f32_fp8_e32 v[148:149], v141
	v_cvt_pk_f32_fp8_sdwa v[150:151], v141 src0_sel:WORD_1
	v_cvt_pk_f32_fp8_e32 v[152:153], v142
	v_cvt_pk_f32_fp8_sdwa v[154:155], v142 src0_sel:WORD_1
	v_cvt_pk_f32_fp8_e32 v[156:157], v143
	v_cvt_pk_f32_fp8_sdwa v[158:159], v143 src0_sel:WORD_1
	v_fmac_f32_e32 v0, v79, v144
	v_fmac_f32_e32 v1, v79, v145
	v_fmac_f32_e32 v2, v79, v146
	v_fmac_f32_e32 v3, v79, v147
	v_fmac_f32_e32 v4, v79, v148
	v_fmac_f32_e32 v5, v79, v149
	v_fmac_f32_e32 v6, v79, v150
	v_fmac_f32_e32 v7, v79, v151
	v_fmac_f32_e32 v8, v79, v152
	v_fmac_f32_e32 v9, v79, v153
	v_fmac_f32_e32 v10, v79, v154
	v_fmac_f32_e32 v11, v79, v155
	v_fmac_f32_e32 v12, v79, v156
	v_fmac_f32_e32 v13, v79, v157
	v_fmac_f32_e32 v14, v79, v158
	v_fmac_f32_e32 v15, v79, v159
	s_waitcnt vmcnt(8)
	v_add_f32_e32 v48, v48, v0
	v_add_f32_e32 v49, v49, v1
	v_add_f32_e32 v50, v50, v2
	v_add_f32_e32 v51, v51, v3
	v_add_f32_e32 v52, v52, v4
	v_add_f32_e32 v53, v53, v5
	v_add_f32_e32 v54, v54, v6
	v_add_f32_e32 v55, v55, v7
	v_add_f32_e32 v56, v56, v8
	v_add_f32_e32 v57, v57, v9
	v_add_f32_e32 v58, v58, v10
	v_add_f32_e32 v59, v59, v11
	v_add_f32_e32 v60, v60, v12
	v_add_f32_e32 v61, v61, v13
	v_add_f32_e32 v62, v62, v14
	v_add_f32_e32 v63, v63, v15
	global_store_dwordx4 v164, v[48:51], s[20:21] offset:0
	global_store_dwordx4 v164, v[52:55], s[20:21] offset:16
	global_store_dwordx4 v164, v[56:59], s[20:21] offset:32
	global_store_dwordx4 v164, v[60:63], s[20:21] offset:48
	s_add_u32 s22, s22, s23
	s_cmpk_lt_u32 s22, 0x2010
	s_cbranch_scc1 .Lpv0_item

; DI void phase_peer_b(const Params& p, int layer, const float* gnext, bool last) {
;   const int tid = threadIdx.x, lane = tid & 63, wave = tid >> 6;
;   const float* wbuf = (const float*)(p.ws + OFF_R + R_WBUF);
;   const int* ibuf = (const int*)(p.ws + OFF_R + R_IBUF);
;   u16* xnw = (u16*)(p.ws + OFF_XN);
;   float* hbuf = (float*)(p.ws + OFF_H);
;   const unsigned char* EV = (const unsigned char*)(p.ws + OFF_EXP) + (size_t)(layer * 2 + 1) * NEXP * DM;
; #pragma unroll 1
;   for (size_t row = (size_t)blockIdx.x * 4 + wave; row < (size_t)T; row += (size_t)gridDim.x * 4) {
;     const int i0 = ibuf[row * 128 + lane], i1 = ibuf[row * 128 + 64 + lane];
;     const float w0 = wbuf[row * 128 + lane], w1 = wbuf[row * 128 + 64 + lane];
.LBB0_722:
	s_or_b64 exec, exec, s[2:3]
	s_barrier
	s_mov_b64 exec, -1
	v_mbcnt_lo_u32_b32 v165, -1, 0
	v_mbcnt_hi_u32_b32 v165, -1, v165
	v_and_b32_e32 v160, 7, v165
	v_lshlrev_b32_e32 v167, 6, v160
	v_lshlrev_b32_e32 v160, 4, v160
	v_lshrrev_b32_e32 v166, 3, v165
	s_and_b32 s24, s95, 7
	s_lshr_b32 s22, s95, 3
	s_lshr_b32 s23, s70, 3
	s_cmp_ge_u32 s22, s23
	s_cbranch_scc1 .Lpv1_end
	s_lshl_b32 s22, s22, 2
	s_add_u32 s22, s22, s94
	s_lshl_b32 s23, s23, 2
	s_lshl_b32 s25, s24, 21
	s_add_u32 s25, s25, 0x1b0c0000
	s_add_u32 s14, s68, s25
	s_addc_u32 s15, s69, 0
	s_add_u32 s16, s68, 0x2b4b0800
	s_addc_u32 s17, s69, 0
	s_add_u32 s18, s68, 0x294a0800
	s_addc_u32 s19, s69, 0
	s_lshl_b32 s25, s24, 9
	s_add_u32 s20, s68, s25
	s_addc_u32 s21, s69, 0
	s_mul_i32 s25, s94, 8320
	v_lshlrev_b32_e32 v162, 4, v165
	v_add_u32_e32 v162, s25, v162
	v_mul_u32_u24_e32 v163, 1040, v166
	v_add_u32_e32 v163, s25, v163
	v_and_b32_e32 v161, 31, v165
	v_lshlrev_b32_e32 v161, 4, v161
	v_mov_b32_e32 v168, s16
	v_mov_b32_e32 v169, s17
	v_mov_b32_e32 v170, s18
	v_mov_b32_e32 v171, s19
	v_cmp_gt_u32_e32 vcc, 32, v165
	s_nop 1
	v_cndmask_b32_e32 v168, v170, v168, vcc
	v_cndmask_b32_e32 v169, v171, v169, vcc
	v_add_co_u32_e32 v168, vcc, v168, v161
	s_nop 1
	v_addc_co_u32_e32 v169, vcc, 0, v169, vcc
	s_cmpk_ge_u32 s22, 0x2010
	s_cbranch_scc1 .Lpv1_end
	s_lshl_b32 s24, s22, 12
	s_mov_b32 s25, 0
	v_lshl_add_u64 v[170:171], v[168:169], 0, s[24:25]
	global_load_dwordx4 v[16:19], v[170:171], off offset:0
	global_load_dwordx4 v[20:23], v[170:171], off offset:512
	global_load_dwordx4 v[24:27], v[170:171], off offset:1024
	global_load_dwordx4 v[28:31], v[170:171], off offset:1536
	global_load_dwordx4 v[32:35], v[170:171], off offset:2048
	global_load_dwordx4 v[36:39], v[170:171], off offset:2560
	global_load_dwordx4 v[40:43], v[170:171], off offset:3072
	global_load_dwordx4 v[44:47], v[170:171], off offset:3584
	s_waitcnt vmcnt(0)
